# w_in epilogue: straight-line paths per tile class (gate / U / XA tiles) derived from the original code, 16-byte gate stores; EpiGlu and EpiFfn 16-byte accesses
# speedup vs baseline: 1.1072x; 1.0181x over previous
; __device__ __forceinline__ float sigm(float x) { return __builtin_amdgcn_rcpf(1.f + __expf(-x)); }
; __device__ __forceinline__ void st_bf4(bf16_t* p, const f32x4 v) { u32x2 w; w.x = cvt_pk_bf16(v[0], v[1]); w.y = cvt_pk_bf16(v[2], v[3]); *(u32x2*)p = w; }
;     __device__ __forceinline__ void operator()(const f32x4 (&acc)[2][2][4][2], const Unit& u, int wr, int wc, int fr, int fq) const {
; #pragma unroll
;         for (int ai = 0; ai < 2; ++ai)
; #pragma unroll
;             for (int m = 0; m < 4; ++m) { const int row = u.pm * 256 + ai * 128 + wr * 64 + m * 16 + fr;
; #pragma unroll
;                 for (int n = 0; n < 2; ++n) { const int col = u.pn * 128 + wc * 32 + 8 * fq + 4 * n; const f32x4 a = acc[ai][0][m][n], b = acc[ai][1][m][n]; f32x4 o;
; #pragma unroll
;                     for (int i = 0; i < 4; ++i) o[i] = a[i] * sigm(a[i]) * b[i];
;                     st_bf4(ACT + (size_t)row * cfg::DFF + col, o); } }
;     }
.LBB0_216:
	v_mul_f32_e32 v147, 0xbfb8aa3b, v126
	v_exp_f32_e32 v147, v147
	v_lshl_or_b32 v146, s19, 7, v143
	v_lshl_add_u32 v145, s18, 8, v96
	s_andn2_b64 vcc, exec, s[6:7]
	v_add_f32_e32 v147, 1.0, v147
	v_rcp_f32_e32 v147, v147
	s_mov_b32 s72, 0xa00000
	s_mov_b32 s73, 0xc00000
	s_mov_b32 s71, 0x1400000
	v_mul_f32_e32 v126, v126, v147
	v_mul_f32_e32 v148, v126, v122
	v_mul_f32_e32 v122, 0xbfb8aa3b, v127
	v_exp_f32_e32 v122, v122
	v_ashrrev_i32_e32 v147, 31, v146
	v_add_f32_e32 v122, 1.0, v122
	v_rcp_f32_e32 v122, v122
	s_nop 0
	v_mul_f32_e32 v122, v127, v122
	v_mul_f32_e32 v149, v122, v123
	v_mul_f32_e32 v122, 0xbfb8aa3b, v128
	v_exp_f32_e32 v122, v122
	s_nop 0
	v_add_f32_e32 v122, 1.0, v122
	v_rcp_f32_e32 v122, v122
	s_nop 0
	v_mul_f32_e32 v122, v128, v122
	v_mul_f32_e32 v150, v122, v124
	v_mul_f32_e32 v122, 0xbfb8aa3b, v129
	v_exp_f32_e32 v122, v122
	v_cvt_pk_bf16_f32 v222, v148, v149
	s_nop 0
	v_add_f32_e32 v122, 1.0, v122
	v_rcp_f32_e32 v122, v122
	s_nop 0
	v_mul_f32_e32 v122, v129, v122
	v_mul_f32_e32 v129, v122, v125
	v_mov_b64_e32 v[122:123], s[4:5]
	v_mad_i64_i32 v[126:127], s[18:19], v145, s64, v[122:123]
	v_lshlrev_b64 v[124:125], 1, v[146:147]
	v_lshl_add_u64 v[126:127], v[126:127], 0, v[124:125]
	v_cvt_pk_bf16_f32 v223, v150, v129
	v_mul_f32_e32 v128, 0xbfb8aa3b, v118
	v_exp_f32_e32 v128, v128
	s_nop 0
	v_add_f32_e32 v128, 1.0, v128
	v_rcp_f32_e32 v128, v128
	s_nop 0
	v_mul_f32_e32 v118, v118, v128
	v_mul_f32_e32 v114, v118, v114
	v_mul_f32_e32 v118, 0xbfb8aa3b, v119
	v_exp_f32_e32 v118, v118
	s_nop 0
	v_add_f32_e32 v118, 1.0, v118
	v_rcp_f32_e32 v118, v118
	s_nop 0
	v_mul_f32_e32 v118, v119, v118
	v_mul_f32_e32 v115, v118, v115
	v_mul_f32_e32 v118, 0xbfb8aa3b, v120
	v_exp_f32_e32 v118, v118
	v_cvt_pk_bf16_f32 v224, v114, v115
	s_nop 0
	v_add_f32_e32 v118, 1.0, v118
	v_rcp_f32_e32 v118, v118
	s_nop 0
	v_mul_f32_e32 v118, v120, v118
	v_mul_f32_e32 v116, v118, v116
	v_mul_f32_e32 v118, 0xbfb8aa3b, v121
	v_exp_f32_e32 v118, v118
	s_nop 0
	v_add_f32_e32 v118, 1.0, v118
	v_rcp_f32_e32 v118, v118
	s_nop 0
	v_mul_f32_e32 v118, v121, v118
	v_mul_f32_e32 v117, v118, v117
	v_cvt_pk_bf16_f32 v225, v116, v117
	global_store_dwordx4 v[126:127], v[222:225], off
	v_mul_f32_e32 v115, 0xbfb8aa3b, v110
	v_exp_f32_e32 v115, v115
	v_or_b32_e32 v114, 16, v145
	v_add_f32_e32 v115, 1.0, v115
	v_rcp_f32_e32 v115, v115
	s_nop 0
	v_mul_f32_e32 v110, v110, v115
	v_mul_f32_e32 v110, v110, v106
	v_mul_f32_e32 v106, 0xbfb8aa3b, v111
	v_exp_f32_e32 v106, v106
	s_nop 0
	v_add_f32_e32 v106, 1.0, v106
	v_rcp_f32_e32 v106, v106
	s_nop 0
	v_mul_f32_e32 v106, v111, v106
	v_mul_f32_e32 v111, v106, v107
	v_mul_f32_e32 v106, 0xbfb8aa3b, v112
	v_exp_f32_e32 v106, v106
	s_nop 0
	v_add_f32_e32 v106, 1.0, v106
	v_rcp_f32_e32 v106, v106
	s_nop 0
	v_mul_f32_e32 v106, v112, v106
	v_mul_f32_e32 v112, v106, v108
	v_mul_f32_e32 v106, 0xbfb8aa3b, v113
	v_exp_f32_e32 v106, v106
	v_cvt_pk_bf16_f32 v226, v110, v111
	s_nop 0
	v_add_f32_e32 v106, 1.0, v106
	v_rcp_f32_e32 v106, v106
	s_nop 0
	v_mul_f32_e32 v106, v113, v106
	v_mul_f32_e32 v109, v106, v109
	v_mad_i64_i32 v[106:107], s[18:19], v114, s64, v[122:123]
	v_lshl_add_u64 v[106:107], v[106:107], 0, v[124:125]
	v_cvt_pk_bf16_f32 v227, v112, v109
	v_mul_f32_e32 v108, 0xbfb8aa3b, v102
	v_exp_f32_e32 v108, v108
	s_nop 0
	v_add_f32_e32 v108, 1.0, v108
	v_rcp_f32_e32 v108, v108
	s_nop 0
	v_mul_f32_e32 v102, v102, v108
	v_mul_f32_e32 v98, v102, v98
	v_mul_f32_e32 v102, 0xbfb8aa3b, v103
	v_exp_f32_e32 v102, v102
	s_nop 0
	v_add_f32_e32 v102, 1.0, v102
	v_rcp_f32_e32 v102, v102
	s_nop 0
	v_mul_f32_e32 v102, v103, v102
	v_mul_f32_e32 v99, v102, v99
	v_mul_f32_e32 v102, 0xbfb8aa3b, v104
	v_exp_f32_e32 v102, v102
	v_cvt_pk_bf16_f32 v228, v98, v99
	s_nop 0
	v_add_f32_e32 v102, 1.0, v102
	v_rcp_f32_e32 v102, v102
	s_nop 0
	v_mul_f32_e32 v102, v104, v102
	v_mul_f32_e32 v100, v102, v100
	v_mul_f32_e32 v102, 0xbfb8aa3b, v105
	v_exp_f32_e32 v102, v102
	s_nop 0
	v_add_f32_e32 v102, 1.0, v102
	v_rcp_f32_e32 v102, v102
	s_nop 0
	v_mul_f32_e32 v102, v105, v102
	v_mul_f32_e32 v101, v102, v101
	v_cvt_pk_bf16_f32 v229, v100, v101
	global_store_dwordx4 v[106:107], v[226:229], off
	v_mul_f32_e32 v99, 0xbfb8aa3b, v92
	v_exp_f32_e32 v99, v99
	v_or_b32_e32 v98, 32, v145
	v_add_f32_e32 v99, 1.0, v99
	v_rcp_f32_e32 v99, v99
	s_nop 0
	v_mul_f32_e32 v92, v92, v99
	v_mul_f32_e32 v92, v92, v88
	v_mul_f32_e32 v88, 0xbfb8aa3b, v93
	v_exp_f32_e32 v88, v88
	s_nop 0
	v_add_f32_e32 v88, 1.0, v88
	v_rcp_f32_e32 v88, v88
	s_nop 0
	v_mul_f32_e32 v88, v93, v88
	v_mul_f32_e32 v93, v88, v89
	v_mul_f32_e32 v88, 0xbfb8aa3b, v94
	v_exp_f32_e32 v88, v88
	s_nop 0
	v_add_f32_e32 v88, 1.0, v88
	v_rcp_f32_e32 v88, v88
	s_nop 0
	v_mul_f32_e32 v88, v94, v88
	v_mul_f32_e32 v94, v88, v90
	v_mul_f32_e32 v88, 0xbfb8aa3b, v95
	v_exp_f32_e32 v88, v88
	v_cvt_pk_bf16_f32 v230, v92, v93
	s_nop 0
	v_add_f32_e32 v88, 1.0, v88
	v_rcp_f32_e32 v88, v88
	s_nop 0
	v_mul_f32_e32 v88, v95, v88
	v_mul_f32_e32 v91, v88, v91
	v_mad_i64_i32 v[88:89], s[18:19], v98, s64, v[122:123]
	v_lshl_add_u64 v[88:89], v[88:89], 0, v[124:125]
	v_cvt_pk_bf16_f32 v231, v94, v91
	v_mul_f32_e32 v90, 0xbfb8aa3b, v84
	v_exp_f32_e32 v90, v90
	s_nop 0
	v_add_f32_e32 v90, 1.0, v90
	v_rcp_f32_e32 v90, v90
	s_nop 0
	v_mul_f32_e32 v84, v84, v90
	v_mul_f32_e32 v80, v84, v80
	v_mul_f32_e32 v84, 0xbfb8aa3b, v85
	v_exp_f32_e32 v84, v84
	s_nop 0
	v_add_f32_e32 v84, 1.0, v84
	v_rcp_f32_e32 v84, v84
	s_nop 0
	v_mul_f32_e32 v84, v85, v84
	v_mul_f32_e32 v81, v84, v81
	v_mul_f32_e32 v84, 0xbfb8aa3b, v86
	v_exp_f32_e32 v84, v84
	v_cvt_pk_bf16_f32 v232, v80, v81
	s_nop 0
	v_add_f32_e32 v84, 1.0, v84
	v_rcp_f32_e32 v84, v84
	s_nop 0
; __device__ __forceinline__ float sigm(float x) { return __builtin_amdgcn_rcpf(1.f + __expf(-x)); }
; __device__ __forceinline__ void st_bf4(bf16_t* p, const f32x4 v) { u32x2 w; w.x = cvt_pk_bf16(v[0], v[1]); w.y = cvt_pk_bf16(v[2], v[3]); *(u32x2*)p = w; }
;     __device__ __forceinline__ void operator()(const f32x4 (&acc)[2][2][4][2], const Unit& u, int wr, int wc, int fr, int fq) const {
; #pragma unroll
;         for (int ai = 0; ai < 2; ++ai)
; #pragma unroll
;             for (int m = 0; m < 4; ++m) { const int row = u.pm * 256 + ai * 128 + wr * 64 + m * 16 + fr;
; #pragma unroll
;                 for (int n = 0; n < 2; ++n) { const int col = u.pn * 128 + wc * 32 + 8 * fq + 4 * n; const f32x4 a = acc[ai][0][m][n], b = acc[ai][1][m][n]; f32x4 o;
; #pragma unroll
;                     for (int i = 0; i < 4; ++i) o[i] = a[i] * sigm(a[i]) * b[i];
;                     st_bf4(ACT + (size_t)row * cfg::DFF + col, o); } }
;     }
	v_mul_f32_e32 v84, v86, v84
	v_mul_f32_e32 v82, v84, v82
	v_mul_f32_e32 v84, 0xbfb8aa3b, v87
	v_exp_f32_e32 v84, v84
	s_nop 0
	v_add_f32_e32 v84, 1.0, v84
	v_rcp_f32_e32 v84, v84
	s_nop 0
	v_mul_f32_e32 v84, v87, v84
	v_mul_f32_e32 v83, v84, v83
	v_cvt_pk_bf16_f32 v233, v82, v83
	global_store_dwordx4 v[88:89], v[230:233], off
	v_mul_f32_e32 v81, 0xbfb8aa3b, v76
	v_exp_f32_e32 v81, v81
	v_or_b32_e32 v80, 48, v145
	v_add_f32_e32 v81, 1.0, v81
	v_rcp_f32_e32 v81, v81
	s_nop 0
	v_mul_f32_e32 v76, v76, v81
	v_mul_f32_e32 v76, v76, v72
	v_mul_f32_e32 v72, 0xbfb8aa3b, v77
	v_exp_f32_e32 v72, v72
	s_nop 0
	v_add_f32_e32 v72, 1.0, v72
	v_rcp_f32_e32 v72, v72
	s_nop 0
	v_mul_f32_e32 v72, v77, v72
	v_mul_f32_e32 v77, v72, v73
	v_mul_f32_e32 v72, 0xbfb8aa3b, v78
	v_exp_f32_e32 v72, v72
	s_nop 0
	v_add_f32_e32 v72, 1.0, v72
	v_rcp_f32_e32 v72, v72
	s_nop 0
	v_mul_f32_e32 v72, v78, v72
	v_mul_f32_e32 v78, v72, v74
	v_mul_f32_e32 v72, 0xbfb8aa3b, v79
	v_exp_f32_e32 v72, v72
	v_cvt_pk_bf16_f32 v234, v76, v77
	s_nop 0
	v_add_f32_e32 v72, 1.0, v72
	v_rcp_f32_e32 v72, v72
	s_nop 0
	v_mul_f32_e32 v72, v79, v72
	v_mul_f32_e32 v75, v72, v75
	v_mad_i64_i32 v[72:73], s[18:19], v80, s64, v[122:123]
	v_lshl_add_u64 v[72:73], v[72:73], 0, v[124:125]
	v_cvt_pk_bf16_f32 v235, v78, v75
	v_mul_f32_e32 v74, 0xbfb8aa3b, v68
	v_exp_f32_e32 v74, v74
	s_nop 0
	v_add_f32_e32 v74, 1.0, v74
	v_rcp_f32_e32 v74, v74
	s_nop 0
	v_mul_f32_e32 v68, v68, v74
	v_mul_f32_e32 v64, v68, v64
	v_mul_f32_e32 v68, 0xbfb8aa3b, v69
	v_exp_f32_e32 v68, v68
	s_nop 0
	v_add_f32_e32 v68, 1.0, v68
	v_rcp_f32_e32 v68, v68
	s_nop 0
	v_mul_f32_e32 v68, v69, v68
	v_mul_f32_e32 v65, v68, v65
	v_mul_f32_e32 v68, 0xbfb8aa3b, v70
	v_exp_f32_e32 v68, v68
	v_cvt_pk_bf16_f32 v236, v64, v65
	s_nop 0
	v_add_f32_e32 v68, 1.0, v68
	v_rcp_f32_e32 v68, v68
	s_nop 0
	v_mul_f32_e32 v68, v70, v68
	v_mul_f32_e32 v66, v68, v66
	v_mul_f32_e32 v68, 0xbfb8aa3b, v71
	v_exp_f32_e32 v68, v68
	s_nop 0
	v_add_f32_e32 v68, 1.0, v68
	v_rcp_f32_e32 v68, v68
	s_nop 0
	v_mul_f32_e32 v68, v71, v68
	v_mul_f32_e32 v67, v68, v67
	v_cvt_pk_bf16_f32 v237, v66, v67
	global_store_dwordx4 v[72:73], v[234:237], off
	v_mul_f32_e32 v65, 0xbfb8aa3b, v60
	v_exp_f32_e32 v65, v65
	v_add_u32_e32 v64, 0x80, v145
	v_add_f32_e32 v65, 1.0, v65
	v_rcp_f32_e32 v65, v65
	s_nop 0
	v_mul_f32_e32 v60, v60, v65
	v_mul_f32_e32 v60, v60, v56
	v_mul_f32_e32 v56, 0xbfb8aa3b, v61
	v_exp_f32_e32 v56, v56
	s_nop 0
	v_add_f32_e32 v56, 1.0, v56
	v_rcp_f32_e32 v56, v56
	s_nop 0
	v_mul_f32_e32 v56, v61, v56
	v_mul_f32_e32 v61, v56, v57
	v_mul_f32_e32 v56, 0xbfb8aa3b, v62
	v_exp_f32_e32 v56, v56
	s_nop 0
	v_add_f32_e32 v56, 1.0, v56
	v_rcp_f32_e32 v56, v56
	s_nop 0
	v_mul_f32_e32 v56, v62, v56
	v_mul_f32_e32 v62, v56, v58
	v_mul_f32_e32 v56, 0xbfb8aa3b, v63
	v_exp_f32_e32 v56, v56
	v_cvt_pk_bf16_f32 v238, v60, v61
	s_nop 0
	v_add_f32_e32 v56, 1.0, v56
	v_rcp_f32_e32 v56, v56
	s_nop 0
	v_mul_f32_e32 v56, v63, v56
	v_mul_f32_e32 v59, v56, v59
	v_mad_i64_i32 v[56:57], s[18:19], v64, s64, v[122:123]
	v_lshl_add_u64 v[56:57], v[56:57], 0, v[124:125]
	v_cvt_pk_bf16_f32 v239, v62, v59
	v_mul_f32_e32 v58, 0xbfb8aa3b, v52
	v_exp_f32_e32 v58, v58
	s_nop 0
	v_add_f32_e32 v58, 1.0, v58
	v_rcp_f32_e32 v58, v58
	s_nop 0
	v_mul_f32_e32 v52, v52, v58
	v_mul_f32_e32 v48, v52, v48
	v_mul_f32_e32 v52, 0xbfb8aa3b, v53
	v_exp_f32_e32 v52, v52
	s_nop 0
	v_add_f32_e32 v52, 1.0, v52
	v_rcp_f32_e32 v52, v52
	s_nop 0
	v_mul_f32_e32 v52, v53, v52
	v_mul_f32_e32 v49, v52, v49
	v_mul_f32_e32 v52, 0xbfb8aa3b, v54
	v_exp_f32_e32 v52, v52
	v_cvt_pk_bf16_f32 v240, v48, v49
	s_nop 0
	v_add_f32_e32 v52, 1.0, v52
	v_rcp_f32_e32 v52, v52
	s_nop 0
	v_mul_f32_e32 v52, v54, v52
	v_mul_f32_e32 v50, v52, v50
	v_mul_f32_e32 v52, 0xbfb8aa3b, v55
	v_exp_f32_e32 v52, v52
	s_nop 0
	v_add_f32_e32 v52, 1.0, v52
	v_rcp_f32_e32 v52, v52
	s_nop 0
	v_mul_f32_e32 v52, v55, v52
	v_mul_f32_e32 v51, v52, v51
	v_cvt_pk_bf16_f32 v241, v50, v51
	global_store_dwordx4 v[56:57], v[238:241], off
	v_mul_f32_e32 v49, 0xbfb8aa3b, v44
	v_exp_f32_e32 v49, v49
	v_add_u32_e32 v48, 0x90, v145
	v_add_f32_e32 v49, 1.0, v49
	v_rcp_f32_e32 v49, v49
	s_nop 0
	v_mul_f32_e32 v44, v44, v49
	v_mul_f32_e32 v44, v44, v40
	v_mul_f32_e32 v40, 0xbfb8aa3b, v45
	v_exp_f32_e32 v40, v40
	s_nop 0
	v_add_f32_e32 v40, 1.0, v40
	v_rcp_f32_e32 v40, v40
	s_nop 0
	v_mul_f32_e32 v40, v45, v40
	v_mul_f32_e32 v45, v40, v41
	v_mul_f32_e32 v40, 0xbfb8aa3b, v46
	v_exp_f32_e32 v40, v40
	s_nop 0
	v_add_f32_e32 v40, 1.0, v40
	v_rcp_f32_e32 v40, v40
	s_nop 0
	v_mul_f32_e32 v40, v46, v40
	v_mul_f32_e32 v46, v40, v42
	v_mul_f32_e32 v40, 0xbfb8aa3b, v47
	v_exp_f32_e32 v40, v40
	v_cvt_pk_bf16_f32 v242, v44, v45
	s_nop 0
	v_add_f32_e32 v40, 1.0, v40
	v_rcp_f32_e32 v40, v40
	s_nop 0
; __device__ __forceinline__ float sigm(float x) { return __builtin_amdgcn_rcpf(1.f + __expf(-x)); }
; __device__ __forceinline__ void st_bf4(bf16_t* p, const f32x4 v) { u32x2 w; w.x = cvt_pk_bf16(v[0], v[1]); w.y = cvt_pk_bf16(v[2], v[3]); *(u32x2*)p = w; }
;     __device__ __forceinline__ void operator()(const f32x4 (&acc)[2][2][4][2], const Unit& u, int wr, int wc, int fr, int fq) const {
; #pragma unroll
;         for (int ai = 0; ai < 2; ++ai)
; #pragma unroll
;             for (int m = 0; m < 4; ++m) { const int row = u.pm * 256 + ai * 128 + wr * 64 + m * 16 + fr;
; #pragma unroll
;                 for (int n = 0; n < 2; ++n) { const int col = u.pn * 128 + wc * 32 + 8 * fq + 4 * n; const f32x4 a = acc[ai][0][m][n], b = acc[ai][1][m][n]; f32x4 o;
; #pragma unroll
;                     for (int i = 0; i < 4; ++i) o[i] = a[i] * sigm(a[i]) * b[i];
;                     st_bf4(ACT + (size_t)row * cfg::DFF + col, o); } }
;     }
	v_mul_f32_e32 v40, v47, v40
	v_mul_f32_e32 v43, v40, v43
	v_mad_i64_i32 v[40:41], s[18:19], v48, s64, v[122:123]
	v_lshl_add_u64 v[40:41], v[40:41], 0, v[124:125]
	v_cvt_pk_bf16_f32 v243, v46, v43
	v_mul_f32_e32 v42, 0xbfb8aa3b, v36
	v_exp_f32_e32 v42, v42
	s_nop 0
	v_add_f32_e32 v42, 1.0, v42
	v_rcp_f32_e32 v42, v42
	s_nop 0
	v_mul_f32_e32 v36, v36, v42
	v_mul_f32_e32 v32, v36, v32
	v_mul_f32_e32 v36, 0xbfb8aa3b, v37
	v_exp_f32_e32 v36, v36
	s_nop 0
	v_add_f32_e32 v36, 1.0, v36
	v_rcp_f32_e32 v36, v36
	s_nop 0
	v_mul_f32_e32 v36, v37, v36
	v_mul_f32_e32 v33, v36, v33
	v_mul_f32_e32 v36, 0xbfb8aa3b, v38
	v_exp_f32_e32 v36, v36
	v_cvt_pk_bf16_f32 v244, v32, v33
	s_nop 0
	v_add_f32_e32 v36, 1.0, v36
	v_rcp_f32_e32 v36, v36
	s_nop 0
	v_mul_f32_e32 v36, v38, v36
	v_mul_f32_e32 v34, v36, v34
	v_mul_f32_e32 v36, 0xbfb8aa3b, v39
	v_exp_f32_e32 v36, v36
	s_nop 0
	v_add_f32_e32 v36, 1.0, v36
	v_rcp_f32_e32 v36, v36
	s_nop 0
	v_mul_f32_e32 v36, v39, v36
	v_mul_f32_e32 v35, v36, v35
	v_cvt_pk_bf16_f32 v245, v34, v35
	global_store_dwordx4 v[40:41], v[242:245], off
	v_mul_f32_e32 v33, 0xbfb8aa3b, v28
	v_exp_f32_e32 v33, v33
	v_add_u32_e32 v32, 0xa0, v145
	v_add_f32_e32 v33, 1.0, v33
	v_rcp_f32_e32 v33, v33
	s_nop 0
	v_mul_f32_e32 v28, v28, v33
	v_mul_f32_e32 v28, v28, v24
	v_mul_f32_e32 v24, 0xbfb8aa3b, v29
	v_exp_f32_e32 v24, v24
	s_nop 0
	v_add_f32_e32 v24, 1.0, v24
	v_rcp_f32_e32 v24, v24
	s_nop 0
	v_mul_f32_e32 v24, v29, v24
	v_mul_f32_e32 v29, v24, v25
	v_mul_f32_e32 v24, 0xbfb8aa3b, v30
	v_exp_f32_e32 v24, v24
	s_nop 0
	v_add_f32_e32 v24, 1.0, v24
	v_rcp_f32_e32 v24, v24
	s_nop 0
	v_mul_f32_e32 v24, v30, v24
	v_mul_f32_e32 v30, v24, v26
	v_mul_f32_e32 v24, 0xbfb8aa3b, v31
	v_exp_f32_e32 v24, v24
	v_cvt_pk_bf16_f32 v246, v28, v29
	s_nop 0
	v_add_f32_e32 v24, 1.0, v24
	v_rcp_f32_e32 v24, v24
	s_nop 0
	v_mul_f32_e32 v24, v31, v24
	v_mul_f32_e32 v27, v24, v27
	v_mad_i64_i32 v[24:25], s[18:19], v32, s64, v[122:123]
	v_lshl_add_u64 v[24:25], v[24:25], 0, v[124:125]
	v_cvt_pk_bf16_f32 v247, v30, v27
	v_mul_f32_e32 v26, 0xbfb8aa3b, v20
	v_exp_f32_e32 v26, v26
	s_nop 0
	v_add_f32_e32 v26, 1.0, v26
	v_rcp_f32_e32 v26, v26
	s_nop 0
	v_mul_f32_e32 v20, v20, v26
	v_mul_f32_e32 v16, v20, v16
	v_mul_f32_e32 v20, 0xbfb8aa3b, v21
	v_exp_f32_e32 v20, v20
	s_nop 0
	v_add_f32_e32 v20, 1.0, v20
	v_rcp_f32_e32 v20, v20
	s_nop 0
	v_mul_f32_e32 v20, v21, v20
	v_mul_f32_e32 v17, v20, v17
	v_mul_f32_e32 v20, 0xbfb8aa3b, v22
	v_exp_f32_e32 v20, v20
	v_cvt_pk_bf16_f32 v248, v16, v17
	s_nop 0
	v_add_f32_e32 v20, 1.0, v20
	v_rcp_f32_e32 v20, v20
	s_nop 0
	v_mul_f32_e32 v20, v22, v20
	v_mul_f32_e32 v18, v20, v18
	v_mul_f32_e32 v20, 0xbfb8aa3b, v23
	v_exp_f32_e32 v20, v20
	s_nop 0
	v_add_f32_e32 v20, 1.0, v20
	v_rcp_f32_e32 v20, v20
	s_nop 0
	v_mul_f32_e32 v20, v23, v20
	v_mul_f32_e32 v19, v20, v19
	v_cvt_pk_bf16_f32 v249, v18, v19
	global_store_dwordx4 v[24:25], v[246:249], off
	v_mul_f32_e32 v17, 0xbfb8aa3b, v12
	v_exp_f32_e32 v17, v17
	v_add_u32_e32 v16, 0xb0, v145
	v_add_f32_e32 v17, 1.0, v17
	v_rcp_f32_e32 v17, v17
	s_nop 0
	v_mul_f32_e32 v12, v12, v17
	v_mul_f32_e32 v12, v12, v8
	v_mul_f32_e32 v8, 0xbfb8aa3b, v13
	v_exp_f32_e32 v8, v8
	s_nop 0
	v_add_f32_e32 v8, 1.0, v8
	v_rcp_f32_e32 v8, v8
	s_nop 0
	v_mul_f32_e32 v8, v13, v8
	v_mul_f32_e32 v13, v8, v9
	v_mul_f32_e32 v8, 0xbfb8aa3b, v14
	v_exp_f32_e32 v8, v8
	s_nop 0
	v_add_f32_e32 v8, 1.0, v8
	v_rcp_f32_e32 v8, v8
	s_nop 0
	v_mul_f32_e32 v8, v14, v8
	v_mul_f32_e32 v14, v8, v10
	v_mul_f32_e32 v8, 0xbfb8aa3b, v15
	v_exp_f32_e32 v8, v8
	v_cvt_pk_bf16_f32 v250, v12, v13
	s_nop 0
	v_add_f32_e32 v8, 1.0, v8
	v_rcp_f32_e32 v8, v8
	s_nop 0
	v_mul_f32_e32 v8, v15, v8
	v_mul_f32_e32 v11, v8, v11
	v_mad_i64_i32 v[8:9], s[18:19], v16, s64, v[122:123]
	v_lshl_add_u64 v[8:9], v[8:9], 0, v[124:125]
	v_cvt_pk_bf16_f32 v251, v14, v11
	v_mul_f32_e32 v10, 0xbfb8aa3b, v4
	v_exp_f32_e32 v10, v10
	s_mov_b64 s[18:19], -1
	v_add_f32_e32 v10, 1.0, v10
	v_rcp_f32_e32 v10, v10
	s_nop 0
	v_mul_f32_e32 v4, v4, v10
	v_mul_f32_e32 v0, v4, v0
	v_mul_f32_e32 v4, 0xbfb8aa3b, v5
	v_exp_f32_e32 v4, v4
	s_nop 0
	v_add_f32_e32 v4, 1.0, v4
	v_rcp_f32_e32 v4, v4
	s_nop 0
	v_mul_f32_e32 v4, v5, v4
	v_mul_f32_e32 v1, v4, v1
	v_mul_f32_e32 v4, 0xbfb8aa3b, v6
	v_exp_f32_e32 v4, v4
	v_cvt_pk_bf16_f32 v252, v0, v1
	s_nop 0
	v_add_f32_e32 v4, 1.0, v4
	v_rcp_f32_e32 v4, v4
	s_nop 0
	v_mul_f32_e32 v4, v6, v4
	v_mul_f32_e32 v2, v4, v2
	v_mul_f32_e32 v4, 0xbfb8aa3b, v7
	v_exp_f32_e32 v4, v4
	s_nop 0
	v_add_f32_e32 v4, 1.0, v4
	v_rcp_f32_e32 v4, v4
	s_nop 0
	v_mul_f32_e32 v4, v7, v4
	v_mul_f32_e32 v3, v4, v3
	v_cvt_pk_bf16_f32 v253, v2, v3
	global_store_dwordx4 v[8:9], v[250:253], off
	s_cbranch_vccnz .LBB0_205
	s_andn2_b64 vcc, exec, s[2:3]
	s_cbranch_vccnz .LBB0_204
	s_barrier
	s_branch .LBB0_204

; __device__ __forceinline__ float sigm(float x) { return __builtin_amdgcn_rcpf(1.f + __expf(-x)); }
; __device__ __forceinline__ f32x4 ld_bf4(const bf16_t* p) { const u32x2 w = *(const u32x2*)p; f32x4 r; r[0] = __uint_as_float(w.x << 16); r[1] = __uint_as_float(w.x & 0xffff0000u); r[2] = __uint_as_float(w.y << 16); r[3] = __uint_as_float(w.y & 0xffff0000u); return r; }
; __device__ __forceinline__ void st_bf4(bf16_t* p, const f32x4 v) { u32x2 w; w.x = cvt_pk_bf16(v[0], v[1]); w.y = cvt_pk_bf16(v[2], v[3]); *(u32x2*)p = w; }
;     __device__ __forceinline__ void operator()(const f32x4 (&acc)[2][2][4][2], const Unit& u, int wr, int wc, int fr, int fq) const {
; #pragma unroll
;         for (int ai = 0; ai < 2; ++ai)
; #pragma unroll
;             for (int m = 0; m < 4; ++m) { const int row = u.pm * 256 + ai * 128 + wr * 64 + m * 16 + fr;
; #pragma unroll
;                 for (int bj = 0; bj < 2; ++bj)
; #pragma unroll
;                     for (int n = 0; n < 2; ++n) { const int col = u.pn * 256 + bj * 128 + wc * 32 + 8 * fq + 4 * n; const f32x4 v = acc[ai][bj][m][n];
;                         const f32x4 y0 = ld_bf4(YC0 + (size_t)row * 512 + col); f32x4 o;
; #pragma unroll
;                         for (int i = 0; i < 4; ++i) o[i] = y0[i] * sigm(v[i]);
;                         st_bf4(YC + (size_t)row * 512 + col, o); } }
.LBB0_471:
	s_andn2_b64 vcc, exec, s[6:7]
	s_mov_b64 s[6:7], -1
	s_mov_b32 s72, 0xa00000
	s_mov_b32 s73, 0xc00000
	s_mov_b32 s71, 0x1400000
	v_lshl_add_u32 v144, s18, 8, v96
	v_lshl_or_b32 v142, s53, 8, v151
	v_lshlrev_b32_e32 v170, 10, v144
	v_lshl_add_u32 v170, v142, 1, v170
	v_add_u32_e32 v171, 0x4000, v170
	v_add_u32_e32 v172, 0x8000, v170
	v_add_u32_e32 v173, 0xc000, v170
	v_add_u32_e32 v174, 0x20000, v170
	v_add_u32_e32 v175, 0x24000, v170
	v_add_u32_e32 v176, 0x28000, v170
	v_add_u32_e32 v177, 0x2c000, v170
	global_load_dwordx4 v[198:201], v170, s[0:1]
	global_load_dwordx4 v[202:205], v170, s[0:1] offset:256
	global_load_dwordx4 v[206:209], v171, s[0:1]
	global_load_dwordx4 v[210:213], v171, s[0:1] offset:256
	global_load_dwordx4 v[214:217], v172, s[0:1]
	global_load_dwordx4 v[218:221], v172, s[0:1] offset:256
	global_load_dwordx4 v[222:225], v173, s[0:1]
	global_load_dwordx4 v[226:229], v173, s[0:1] offset:256
	global_load_dwordx4 v[230:233], v174, s[0:1]
	global_load_dwordx4 v[234:237], v174, s[0:1] offset:256
	global_load_dwordx4 v[238:241], v175, s[0:1]
	global_load_dwordx4 v[242:245], v175, s[0:1] offset:256
	global_load_dwordx4 v[246:249], v176, s[0:1]
	global_load_dwordx4 v[250:253], v176, s[0:1] offset:256
	global_load_dwordx4 v[182:185], v177, s[0:1]
	global_load_dwordx4 v[186:189], v177, s[0:1] offset:256
	s_waitcnt vmcnt(14)
	v_mul_f32_e32 v126, 0xbfb8aa3b, v126
	v_mul_f32_e32 v127, 0xbfb8aa3b, v127
	v_mul_f32_e32 v128, 0xbfb8aa3b, v128
	v_mul_f32_e32 v129, 0xbfb8aa3b, v129
	v_exp_f32_e32 v126, v126
	v_exp_f32_e32 v127, v127
	v_exp_f32_e32 v128, v128
	v_exp_f32_e32 v129, v129
	s_nop 0
	v_add_f32_e32 v126, 1.0, v126
	v_add_f32_e32 v127, 1.0, v127
	v_add_f32_e32 v128, 1.0, v128
	v_add_f32_e32 v129, 1.0, v129
	v_rcp_f32_e32 v126, v126
	v_rcp_f32_e32 v127, v127
	v_rcp_f32_e32 v128, v128
	v_rcp_f32_e32 v129, v129
	v_lshlrev_b32_e32 v154, 16, v198
	v_and_b32_e32 v155, 0xffff0000, v198
	v_lshlrev_b32_e32 v156, 16, v199
	v_and_b32_e32 v157, 0xffff0000, v199
	v_mul_f32_e32 v126, v126, v154
	v_mul_f32_e32 v127, v127, v155
	v_mul_f32_e32 v128, v128, v156
	v_mul_f32_e32 v129, v129, v157
	v_cvt_pk_bf16_f32 v198, v126, v127
	v_cvt_pk_bf16_f32 v199, v128, v129
	v_mul_f32_e32 v122, 0xbfb8aa3b, v122
	v_mul_f32_e32 v123, 0xbfb8aa3b, v123
	v_mul_f32_e32 v124, 0xbfb8aa3b, v124
	v_mul_f32_e32 v125, 0xbfb8aa3b, v125
	v_exp_f32_e32 v122, v122
	v_exp_f32_e32 v123, v123
	v_exp_f32_e32 v124, v124
	v_exp_f32_e32 v125, v125
	s_nop 0
	v_add_f32_e32 v122, 1.0, v122
	v_add_f32_e32 v123, 1.0, v123
	v_add_f32_e32 v124, 1.0, v124
	v_add_f32_e32 v125, 1.0, v125
	v_rcp_f32_e32 v122, v122
	v_rcp_f32_e32 v123, v123
	v_rcp_f32_e32 v124, v124
	v_rcp_f32_e32 v125, v125
	v_lshlrev_b32_e32 v154, 16, v200
	v_and_b32_e32 v155, 0xffff0000, v200
	v_lshlrev_b32_e32 v156, 16, v201
	v_and_b32_e32 v157, 0xffff0000, v201
	v_mul_f32_e32 v122, v122, v154
	v_mul_f32_e32 v123, v123, v155
	v_mul_f32_e32 v124, v124, v156
	v_mul_f32_e32 v125, v125, v157
	v_cvt_pk_bf16_f32 v200, v122, v123
	v_cvt_pk_bf16_f32 v201, v124, v125
	v_mul_f32_e32 v118, 0xbfb8aa3b, v118
	v_mul_f32_e32 v119, 0xbfb8aa3b, v119
	v_mul_f32_e32 v120, 0xbfb8aa3b, v120
	v_mul_f32_e32 v121, 0xbfb8aa3b, v121
	v_exp_f32_e32 v118, v118
	v_exp_f32_e32 v119, v119
	v_exp_f32_e32 v120, v120
	v_exp_f32_e32 v121, v121
	s_nop 0
	v_add_f32_e32 v118, 1.0, v118
	v_add_f32_e32 v119, 1.0, v119
	v_add_f32_e32 v120, 1.0, v120
	v_add_f32_e32 v121, 1.0, v121
	v_rcp_f32_e32 v118, v118
	v_rcp_f32_e32 v119, v119
	v_rcp_f32_e32 v120, v120
	v_rcp_f32_e32 v121, v121
	v_lshlrev_b32_e32 v154, 16, v202
	v_and_b32_e32 v155, 0xffff0000, v202
	v_lshlrev_b32_e32 v156, 16, v203
	v_and_b32_e32 v157, 0xffff0000, v203
	v_mul_f32_e32 v118, v118, v154
	v_mul_f32_e32 v119, v119, v155
	v_mul_f32_e32 v120, v120, v156
	v_mul_f32_e32 v121, v121, v157
	v_cvt_pk_bf16_f32 v202, v118, v119
	v_cvt_pk_bf16_f32 v203, v120, v121
	v_mul_f32_e32 v114, 0xbfb8aa3b, v114
	v_mul_f32_e32 v115, 0xbfb8aa3b, v115
	v_mul_f32_e32 v116, 0xbfb8aa3b, v116
	v_mul_f32_e32 v117, 0xbfb8aa3b, v117
	v_exp_f32_e32 v114, v114
	v_exp_f32_e32 v115, v115
	v_exp_f32_e32 v116, v116
	v_exp_f32_e32 v117, v117
	s_nop 0
	v_add_f32_e32 v114, 1.0, v114
	v_add_f32_e32 v115, 1.0, v115
	v_add_f32_e32 v116, 1.0, v116
	v_add_f32_e32 v117, 1.0, v117
	v_rcp_f32_e32 v114, v114
	v_rcp_f32_e32 v115, v115
	v_rcp_f32_e32 v116, v116
	v_rcp_f32_e32 v117, v117
	v_lshlrev_b32_e32 v154, 16, v204
	v_and_b32_e32 v155, 0xffff0000, v204
	v_lshlrev_b32_e32 v156, 16, v205
	v_and_b32_e32 v157, 0xffff0000, v205
	v_mul_f32_e32 v114, v114, v154
	v_mul_f32_e32 v115, v115, v155
	v_mul_f32_e32 v116, v116, v156
	v_mul_f32_e32 v117, v117, v157
	v_cvt_pk_bf16_f32 v204, v114, v115
	v_cvt_pk_bf16_f32 v205, v116, v117
	global_store_dwordx4 v170, v[198:201], s[4:5]
	global_store_dwordx4 v170, v[202:205], s[4:5] offset:256
	s_waitcnt vmcnt(14)
; __device__ __forceinline__ float sigm(float x) { return __builtin_amdgcn_rcpf(1.f + __expf(-x)); }
; __device__ __forceinline__ f32x4 ld_bf4(const bf16_t* p) { const u32x2 w = *(const u32x2*)p; f32x4 r; r[0] = __uint_as_float(w.x << 16); r[1] = __uint_as_float(w.x & 0xffff0000u); r[2] = __uint_as_float(w.y << 16); r[3] = __uint_as_float(w.y & 0xffff0000u); return r; }
; __device__ __forceinline__ void st_bf4(bf16_t* p, const f32x4 v) { u32x2 w; w.x = cvt_pk_bf16(v[0], v[1]); w.y = cvt_pk_bf16(v[2], v[3]); *(u32x2*)p = w; }
;     __device__ __forceinline__ void operator()(const f32x4 (&acc)[2][2][4][2], const Unit& u, int wr, int wc, int fr, int fq) const {
; #pragma unroll
;         for (int ai = 0; ai < 2; ++ai)
; #pragma unroll
;             for (int m = 0; m < 4; ++m) { const int row = u.pm * 256 + ai * 128 + wr * 64 + m * 16 + fr;
; #pragma unroll
;                 for (int bj = 0; bj < 2; ++bj)
; #pragma unroll
;                     for (int n = 0; n < 2; ++n) { const int col = u.pn * 256 + bj * 128 + wc * 32 + 8 * fq + 4 * n; const f32x4 v = acc[ai][bj][m][n];
;                         const f32x4 y0 = ld_bf4(YC0 + (size_t)row * 512 + col); f32x4 o;
; #pragma unroll
;                         for (int i = 0; i < 4; ++i) o[i] = y0[i] * sigm(v[i]);
;                         st_bf4(YC + (size_t)row * 512 + col, o); } }
	v_mul_f32_e32 v110, 0xbfb8aa3b, v110
	v_mul_f32_e32 v111, 0xbfb8aa3b, v111
	v_mul_f32_e32 v112, 0xbfb8aa3b, v112
	v_mul_f32_e32 v113, 0xbfb8aa3b, v113
	v_exp_f32_e32 v110, v110
	v_exp_f32_e32 v111, v111
	v_exp_f32_e32 v112, v112
	v_exp_f32_e32 v113, v113
	s_nop 0
	v_add_f32_e32 v110, 1.0, v110
	v_add_f32_e32 v111, 1.0, v111
	v_add_f32_e32 v112, 1.0, v112
	v_add_f32_e32 v113, 1.0, v113
	v_rcp_f32_e32 v110, v110
	v_rcp_f32_e32 v111, v111
	v_rcp_f32_e32 v112, v112
	v_rcp_f32_e32 v113, v113
	v_lshlrev_b32_e32 v154, 16, v206
	v_and_b32_e32 v155, 0xffff0000, v206
	v_lshlrev_b32_e32 v156, 16, v207
	v_and_b32_e32 v157, 0xffff0000, v207
	v_mul_f32_e32 v110, v110, v154
	v_mul_f32_e32 v111, v111, v155
	v_mul_f32_e32 v112, v112, v156
	v_mul_f32_e32 v113, v113, v157
	v_cvt_pk_bf16_f32 v206, v110, v111
	v_cvt_pk_bf16_f32 v207, v112, v113
	v_mul_f32_e32 v106, 0xbfb8aa3b, v106
	v_mul_f32_e32 v107, 0xbfb8aa3b, v107
	v_mul_f32_e32 v108, 0xbfb8aa3b, v108
	v_mul_f32_e32 v109, 0xbfb8aa3b, v109
	v_exp_f32_e32 v106, v106
	v_exp_f32_e32 v107, v107
	v_exp_f32_e32 v108, v108
	v_exp_f32_e32 v109, v109
	s_nop 0
	v_add_f32_e32 v106, 1.0, v106
	v_add_f32_e32 v107, 1.0, v107
	v_add_f32_e32 v108, 1.0, v108
	v_add_f32_e32 v109, 1.0, v109
	v_rcp_f32_e32 v106, v106
	v_rcp_f32_e32 v107, v107
	v_rcp_f32_e32 v108, v108
	v_rcp_f32_e32 v109, v109
	v_lshlrev_b32_e32 v154, 16, v208
	v_and_b32_e32 v155, 0xffff0000, v208
	v_lshlrev_b32_e32 v156, 16, v209
	v_and_b32_e32 v157, 0xffff0000, v209
	v_mul_f32_e32 v106, v106, v154
	v_mul_f32_e32 v107, v107, v155
	v_mul_f32_e32 v108, v108, v156
	v_mul_f32_e32 v109, v109, v157
	v_cvt_pk_bf16_f32 v208, v106, v107
	v_cvt_pk_bf16_f32 v209, v108, v109
	v_mul_f32_e32 v102, 0xbfb8aa3b, v102
	v_mul_f32_e32 v103, 0xbfb8aa3b, v103
	v_mul_f32_e32 v104, 0xbfb8aa3b, v104
	v_mul_f32_e32 v105, 0xbfb8aa3b, v105
	v_exp_f32_e32 v102, v102
	v_exp_f32_e32 v103, v103
	v_exp_f32_e32 v104, v104
	v_exp_f32_e32 v105, v105
	s_nop 0
	v_add_f32_e32 v102, 1.0, v102
	v_add_f32_e32 v103, 1.0, v103
	v_add_f32_e32 v104, 1.0, v104
	v_add_f32_e32 v105, 1.0, v105
	v_rcp_f32_e32 v102, v102
	v_rcp_f32_e32 v103, v103
	v_rcp_f32_e32 v104, v104
	v_rcp_f32_e32 v105, v105
	v_lshlrev_b32_e32 v154, 16, v210
	v_and_b32_e32 v155, 0xffff0000, v210
	v_lshlrev_b32_e32 v156, 16, v211
	v_and_b32_e32 v157, 0xffff0000, v211
	v_mul_f32_e32 v102, v102, v154
	v_mul_f32_e32 v103, v103, v155
	v_mul_f32_e32 v104, v104, v156
	v_mul_f32_e32 v105, v105, v157
	v_cvt_pk_bf16_f32 v210, v102, v103
	v_cvt_pk_bf16_f32 v211, v104, v105
	v_mul_f32_e32 v98, 0xbfb8aa3b, v98
	v_mul_f32_e32 v99, 0xbfb8aa3b, v99
	v_mul_f32_e32 v100, 0xbfb8aa3b, v100
	v_mul_f32_e32 v101, 0xbfb8aa3b, v101
	v_exp_f32_e32 v98, v98
	v_exp_f32_e32 v99, v99
	v_exp_f32_e32 v100, v100
	v_exp_f32_e32 v101, v101
	s_nop 0
	v_add_f32_e32 v98, 1.0, v98
	v_add_f32_e32 v99, 1.0, v99
	v_add_f32_e32 v100, 1.0, v100
	v_add_f32_e32 v101, 1.0, v101
	v_rcp_f32_e32 v98, v98
	v_rcp_f32_e32 v99, v99
	v_rcp_f32_e32 v100, v100
	v_rcp_f32_e32 v101, v101
	v_lshlrev_b32_e32 v154, 16, v212
	v_and_b32_e32 v155, 0xffff0000, v212
	v_lshlrev_b32_e32 v156, 16, v213
	v_and_b32_e32 v157, 0xffff0000, v213
	v_mul_f32_e32 v98, v98, v154
	v_mul_f32_e32 v99, v99, v155
	v_mul_f32_e32 v100, v100, v156
	v_mul_f32_e32 v101, v101, v157
	v_cvt_pk_bf16_f32 v212, v98, v99
	v_cvt_pk_bf16_f32 v213, v100, v101
	global_store_dwordx4 v171, v[206:209], s[4:5]
	global_store_dwordx4 v171, v[210:213], s[4:5] offset:256
	s_waitcnt vmcnt(14)
	v_mul_f32_e32 v92, 0xbfb8aa3b, v92
	v_mul_f32_e32 v93, 0xbfb8aa3b, v93
	v_mul_f32_e32 v94, 0xbfb8aa3b, v94
	v_mul_f32_e32 v95, 0xbfb8aa3b, v95
	v_exp_f32_e32 v92, v92
	v_exp_f32_e32 v93, v93
	v_exp_f32_e32 v94, v94
	v_exp_f32_e32 v95, v95
	s_nop 0
	v_add_f32_e32 v92, 1.0, v92
	v_add_f32_e32 v93, 1.0, v93
	v_add_f32_e32 v94, 1.0, v94
	v_add_f32_e32 v95, 1.0, v95
	v_rcp_f32_e32 v92, v92
	v_rcp_f32_e32 v93, v93
	v_rcp_f32_e32 v94, v94
	v_rcp_f32_e32 v95, v95
	v_lshlrev_b32_e32 v154, 16, v214
	v_and_b32_e32 v155, 0xffff0000, v214
	v_lshlrev_b32_e32 v156, 16, v215
	v_and_b32_e32 v157, 0xffff0000, v215
	v_mul_f32_e32 v92, v92, v154
	v_mul_f32_e32 v93, v93, v155
	v_mul_f32_e32 v94, v94, v156
	v_mul_f32_e32 v95, v95, v157
	v_cvt_pk_bf16_f32 v214, v92, v93
	v_cvt_pk_bf16_f32 v215, v94, v95
	v_mul_f32_e32 v88, 0xbfb8aa3b, v88
	v_mul_f32_e32 v89, 0xbfb8aa3b, v89
	v_mul_f32_e32 v90, 0xbfb8aa3b, v90
	v_mul_f32_e32 v91, 0xbfb8aa3b, v91
	v_exp_f32_e32 v88, v88
	v_exp_f32_e32 v89, v89
	v_exp_f32_e32 v90, v90
	v_exp_f32_e32 v91, v91
	s_nop 0
	v_add_f32_e32 v88, 1.0, v88
	v_add_f32_e32 v89, 1.0, v89
	v_add_f32_e32 v90, 1.0, v90
	v_add_f32_e32 v91, 1.0, v91
	v_rcp_f32_e32 v88, v88
	v_rcp_f32_e32 v89, v89
	v_rcp_f32_e32 v90, v90
	v_rcp_f32_e32 v91, v91
	v_lshlrev_b32_e32 v154, 16, v216
	v_and_b32_e32 v155, 0xffff0000, v216
	v_lshlrev_b32_e32 v156, 16, v217
	v_and_b32_e32 v157, 0xffff0000, v217
	v_mul_f32_e32 v88, v88, v154
	v_mul_f32_e32 v89, v89, v155
	v_mul_f32_e32 v90, v90, v156
	v_mul_f32_e32 v91, v91, v157
	v_cvt_pk_bf16_f32 v216, v88, v89
	v_cvt_pk_bf16_f32 v217, v90, v91
	v_mul_f32_e32 v84, 0xbfb8aa3b, v84
	v_mul_f32_e32 v85, 0xbfb8aa3b, v85
	v_mul_f32_e32 v86, 0xbfb8aa3b, v86
	v_mul_f32_e32 v87, 0xbfb8aa3b, v87
	v_exp_f32_e32 v84, v84
	v_exp_f32_e32 v85, v85
	v_exp_f32_e32 v86, v86
	v_exp_f32_e32 v87, v87
	s_nop 0
	v_add_f32_e32 v84, 1.0, v84
	v_add_f32_e32 v85, 1.0, v85
	v_add_f32_e32 v86, 1.0, v86
	v_add_f32_e32 v87, 1.0, v87
	v_rcp_f32_e32 v84, v84
	v_rcp_f32_e32 v85, v85
	v_rcp_f32_e32 v86, v86
	v_rcp_f32_e32 v87, v87
	v_lshlrev_b32_e32 v154, 16, v218
	v_and_b32_e32 v155, 0xffff0000, v218
	v_lshlrev_b32_e32 v156, 16, v219
	v_and_b32_e32 v157, 0xffff0000, v219
	v_mul_f32_e32 v84, v84, v154
	v_mul_f32_e32 v85, v85, v155
	v_mul_f32_e32 v86, v86, v156
	v_mul_f32_e32 v87, v87, v157
	v_cvt_pk_bf16_f32 v218, v84, v85
	v_cvt_pk_bf16_f32 v219, v86, v87
	v_mul_f32_e32 v80, 0xbfb8aa3b, v80
	v_mul_f32_e32 v81, 0xbfb8aa3b, v81
	v_mul_f32_e32 v82, 0xbfb8aa3b, v82
	v_mul_f32_e32 v83, 0xbfb8aa3b, v83
	v_exp_f32_e32 v80, v80
	v_exp_f32_e32 v81, v81
	v_exp_f32_e32 v82, v82
	v_exp_f32_e32 v83, v83
	s_nop 0
	v_add_f32_e32 v80, 1.0, v80
	v_add_f32_e32 v81, 1.0, v81
	v_add_f32_e32 v82, 1.0, v82
	v_add_f32_e32 v83, 1.0, v83
	v_rcp_f32_e32 v80, v80
	v_rcp_f32_e32 v81, v81
	v_rcp_f32_e32 v82, v82
	v_rcp_f32_e32 v83, v83
	v_lshlrev_b32_e32 v154, 16, v220
	v_and_b32_e32 v155, 0xffff0000, v220
	v_lshlrev_b32_e32 v156, 16, v221
	v_and_b32_e32 v157, 0xffff0000, v221
	v_mul_f32_e32 v80, v80, v154
	v_mul_f32_e32 v81, v81, v155
	v_mul_f32_e32 v82, v82, v156
	v_mul_f32_e32 v83, v83, v157
	v_cvt_pk_bf16_f32 v220, v80, v81
	v_cvt_pk_bf16_f32 v221, v82, v83
	global_store_dwordx4 v172, v[214:217], s[4:5]
	global_store_dwordx4 v172, v[218:221], s[4:5] offset:256
	s_waitcnt vmcnt(14)
; __device__ __forceinline__ float sigm(float x) { return __builtin_amdgcn_rcpf(1.f + __expf(-x)); }
; __device__ __forceinline__ f32x4 ld_bf4(const bf16_t* p) { const u32x2 w = *(const u32x2*)p; f32x4 r; r[0] = __uint_as_float(w.x << 16); r[1] = __uint_as_float(w.x & 0xffff0000u); r[2] = __uint_as_float(w.y << 16); r[3] = __uint_as_float(w.y & 0xffff0000u); return r; }
; __device__ __forceinline__ void st_bf4(bf16_t* p, const f32x4 v) { u32x2 w; w.x = cvt_pk_bf16(v[0], v[1]); w.y = cvt_pk_bf16(v[2], v[3]); *(u32x2*)p = w; }
;     __device__ __forceinline__ void operator()(const f32x4 (&acc)[2][2][4][2], const Unit& u, int wr, int wc, int fr, int fq) const {
; #pragma unroll
;         for (int ai = 0; ai < 2; ++ai)
; #pragma unroll
;             for (int m = 0; m < 4; ++m) { const int row = u.pm * 256 + ai * 128 + wr * 64 + m * 16 + fr;
; #pragma unroll
;                 for (int bj = 0; bj < 2; ++bj)
; #pragma unroll
;                     for (int n = 0; n < 2; ++n) { const int col = u.pn * 256 + bj * 128 + wc * 32 + 8 * fq + 4 * n; const f32x4 v = acc[ai][bj][m][n];
;                         const f32x4 y0 = ld_bf4(YC0 + (size_t)row * 512 + col); f32x4 o;
; #pragma unroll
;                         for (int i = 0; i < 4; ++i) o[i] = y0[i] * sigm(v[i]);
;                         st_bf4(YC + (size_t)row * 512 + col, o); } }
	v_mul_f32_e32 v76, 0xbfb8aa3b, v76
	v_mul_f32_e32 v77, 0xbfb8aa3b, v77
	v_mul_f32_e32 v78, 0xbfb8aa3b, v78
	v_mul_f32_e32 v79, 0xbfb8aa3b, v79
	v_exp_f32_e32 v76, v76
	v_exp_f32_e32 v77, v77
	v_exp_f32_e32 v78, v78
	v_exp_f32_e32 v79, v79
	s_nop 0
	v_add_f32_e32 v76, 1.0, v76
	v_add_f32_e32 v77, 1.0, v77
	v_add_f32_e32 v78, 1.0, v78
	v_add_f32_e32 v79, 1.0, v79
	v_rcp_f32_e32 v76, v76
	v_rcp_f32_e32 v77, v77
	v_rcp_f32_e32 v78, v78
	v_rcp_f32_e32 v79, v79
	v_lshlrev_b32_e32 v154, 16, v222
	v_and_b32_e32 v155, 0xffff0000, v222
	v_lshlrev_b32_e32 v156, 16, v223
	v_and_b32_e32 v157, 0xffff0000, v223
	v_mul_f32_e32 v76, v76, v154
	v_mul_f32_e32 v77, v77, v155
	v_mul_f32_e32 v78, v78, v156
	v_mul_f32_e32 v79, v79, v157
	v_cvt_pk_bf16_f32 v222, v76, v77
	v_cvt_pk_bf16_f32 v223, v78, v79
	v_mul_f32_e32 v72, 0xbfb8aa3b, v72
	v_mul_f32_e32 v73, 0xbfb8aa3b, v73
	v_mul_f32_e32 v74, 0xbfb8aa3b, v74
	v_mul_f32_e32 v75, 0xbfb8aa3b, v75
	v_exp_f32_e32 v72, v72
	v_exp_f32_e32 v73, v73
	v_exp_f32_e32 v74, v74
	v_exp_f32_e32 v75, v75
	s_nop 0
	v_add_f32_e32 v72, 1.0, v72
	v_add_f32_e32 v73, 1.0, v73
	v_add_f32_e32 v74, 1.0, v74
	v_add_f32_e32 v75, 1.0, v75
	v_rcp_f32_e32 v72, v72
	v_rcp_f32_e32 v73, v73
	v_rcp_f32_e32 v74, v74
	v_rcp_f32_e32 v75, v75
	v_lshlrev_b32_e32 v154, 16, v224
	v_and_b32_e32 v155, 0xffff0000, v224
	v_lshlrev_b32_e32 v156, 16, v225
	v_and_b32_e32 v157, 0xffff0000, v225
	v_mul_f32_e32 v72, v72, v154
	v_mul_f32_e32 v73, v73, v155
	v_mul_f32_e32 v74, v74, v156
	v_mul_f32_e32 v75, v75, v157
	v_cvt_pk_bf16_f32 v224, v72, v73
	v_cvt_pk_bf16_f32 v225, v74, v75
	v_mul_f32_e32 v68, 0xbfb8aa3b, v68
	v_mul_f32_e32 v69, 0xbfb8aa3b, v69
	v_mul_f32_e32 v70, 0xbfb8aa3b, v70
	v_mul_f32_e32 v71, 0xbfb8aa3b, v71
	v_exp_f32_e32 v68, v68
	v_exp_f32_e32 v69, v69
	v_exp_f32_e32 v70, v70
	v_exp_f32_e32 v71, v71
	s_nop 0
	v_add_f32_e32 v68, 1.0, v68
	v_add_f32_e32 v69, 1.0, v69
	v_add_f32_e32 v70, 1.0, v70
	v_add_f32_e32 v71, 1.0, v71
	v_rcp_f32_e32 v68, v68
	v_rcp_f32_e32 v69, v69
	v_rcp_f32_e32 v70, v70
	v_rcp_f32_e32 v71, v71
	v_lshlrev_b32_e32 v154, 16, v226
	v_and_b32_e32 v155, 0xffff0000, v226
	v_lshlrev_b32_e32 v156, 16, v227
	v_and_b32_e32 v157, 0xffff0000, v227
	v_mul_f32_e32 v68, v68, v154
	v_mul_f32_e32 v69, v69, v155
	v_mul_f32_e32 v70, v70, v156
	v_mul_f32_e32 v71, v71, v157
	v_cvt_pk_bf16_f32 v226, v68, v69
	v_cvt_pk_bf16_f32 v227, v70, v71
	v_mul_f32_e32 v64, 0xbfb8aa3b, v64
	v_mul_f32_e32 v65, 0xbfb8aa3b, v65
	v_mul_f32_e32 v66, 0xbfb8aa3b, v66
	v_mul_f32_e32 v67, 0xbfb8aa3b, v67
	v_exp_f32_e32 v64, v64
	v_exp_f32_e32 v65, v65
	v_exp_f32_e32 v66, v66
	v_exp_f32_e32 v67, v67
	s_nop 0
	v_add_f32_e32 v64, 1.0, v64
	v_add_f32_e32 v65, 1.0, v65
	v_add_f32_e32 v66, 1.0, v66
	v_add_f32_e32 v67, 1.0, v67
	v_rcp_f32_e32 v64, v64
	v_rcp_f32_e32 v65, v65
	v_rcp_f32_e32 v66, v66
	v_rcp_f32_e32 v67, v67
	v_lshlrev_b32_e32 v154, 16, v228
	v_and_b32_e32 v155, 0xffff0000, v228
	v_lshlrev_b32_e32 v156, 16, v229
	v_and_b32_e32 v157, 0xffff0000, v229
	v_mul_f32_e32 v64, v64, v154
	v_mul_f32_e32 v65, v65, v155
	v_mul_f32_e32 v66, v66, v156
	v_mul_f32_e32 v67, v67, v157
	v_cvt_pk_bf16_f32 v228, v64, v65
	v_cvt_pk_bf16_f32 v229, v66, v67
	global_store_dwordx4 v173, v[222:225], s[4:5]
	global_store_dwordx4 v173, v[226:229], s[4:5] offset:256
	s_waitcnt vmcnt(14)
	v_mul_f32_e32 v60, 0xbfb8aa3b, v60
	v_mul_f32_e32 v61, 0xbfb8aa3b, v61
	v_mul_f32_e32 v62, 0xbfb8aa3b, v62
	v_mul_f32_e32 v63, 0xbfb8aa3b, v63
	v_exp_f32_e32 v60, v60
	v_exp_f32_e32 v61, v61
	v_exp_f32_e32 v62, v62
	v_exp_f32_e32 v63, v63
	s_nop 0
	v_add_f32_e32 v60, 1.0, v60
	v_add_f32_e32 v61, 1.0, v61
	v_add_f32_e32 v62, 1.0, v62
	v_add_f32_e32 v63, 1.0, v63
	v_rcp_f32_e32 v60, v60
	v_rcp_f32_e32 v61, v61
	v_rcp_f32_e32 v62, v62
	v_rcp_f32_e32 v63, v63
	v_lshlrev_b32_e32 v154, 16, v230
	v_and_b32_e32 v155, 0xffff0000, v230
	v_lshlrev_b32_e32 v156, 16, v231
	v_and_b32_e32 v157, 0xffff0000, v231
	v_mul_f32_e32 v60, v60, v154
	v_mul_f32_e32 v61, v61, v155
	v_mul_f32_e32 v62, v62, v156
	v_mul_f32_e32 v63, v63, v157
	v_cvt_pk_bf16_f32 v230, v60, v61
	v_cvt_pk_bf16_f32 v231, v62, v63
	v_mul_f32_e32 v56, 0xbfb8aa3b, v56
	v_mul_f32_e32 v57, 0xbfb8aa3b, v57
	v_mul_f32_e32 v58, 0xbfb8aa3b, v58
	v_mul_f32_e32 v59, 0xbfb8aa3b, v59
	v_exp_f32_e32 v56, v56
	v_exp_f32_e32 v57, v57
	v_exp_f32_e32 v58, v58
	v_exp_f32_e32 v59, v59
	s_nop 0
	v_add_f32_e32 v56, 1.0, v56
	v_add_f32_e32 v57, 1.0, v57
	v_add_f32_e32 v58, 1.0, v58
	v_add_f32_e32 v59, 1.0, v59
	v_rcp_f32_e32 v56, v56
	v_rcp_f32_e32 v57, v57
	v_rcp_f32_e32 v58, v58
	v_rcp_f32_e32 v59, v59
	v_lshlrev_b32_e32 v154, 16, v232
	v_and_b32_e32 v155, 0xffff0000, v232
	v_lshlrev_b32_e32 v156, 16, v233
	v_and_b32_e32 v157, 0xffff0000, v233
	v_mul_f32_e32 v56, v56, v154
	v_mul_f32_e32 v57, v57, v155
	v_mul_f32_e32 v58, v58, v156
	v_mul_f32_e32 v59, v59, v157
	v_cvt_pk_bf16_f32 v232, v56, v57
	v_cvt_pk_bf16_f32 v233, v58, v59
	v_mul_f32_e32 v52, 0xbfb8aa3b, v52
	v_mul_f32_e32 v53, 0xbfb8aa3b, v53
	v_mul_f32_e32 v54, 0xbfb8aa3b, v54
	v_mul_f32_e32 v55, 0xbfb8aa3b, v55
	v_exp_f32_e32 v52, v52
	v_exp_f32_e32 v53, v53
	v_exp_f32_e32 v54, v54
	v_exp_f32_e32 v55, v55
	s_nop 0
	v_add_f32_e32 v52, 1.0, v52
	v_add_f32_e32 v53, 1.0, v53
	v_add_f32_e32 v54, 1.0, v54
	v_add_f32_e32 v55, 1.0, v55
	v_rcp_f32_e32 v52, v52
	v_rcp_f32_e32 v53, v53
	v_rcp_f32_e32 v54, v54
	v_rcp_f32_e32 v55, v55
	v_lshlrev_b32_e32 v154, 16, v234
	v_and_b32_e32 v155, 0xffff0000, v234
	v_lshlrev_b32_e32 v156, 16, v235
	v_and_b32_e32 v157, 0xffff0000, v235
	v_mul_f32_e32 v52, v52, v154
	v_mul_f32_e32 v53, v53, v155
	v_mul_f32_e32 v54, v54, v156
	v_mul_f32_e32 v55, v55, v157
	v_cvt_pk_bf16_f32 v234, v52, v53
	v_cvt_pk_bf16_f32 v235, v54, v55
	v_mul_f32_e32 v48, 0xbfb8aa3b, v48
	v_mul_f32_e32 v49, 0xbfb8aa3b, v49
	v_mul_f32_e32 v50, 0xbfb8aa3b, v50
	v_mul_f32_e32 v51, 0xbfb8aa3b, v51
	v_exp_f32_e32 v48, v48
	v_exp_f32_e32 v49, v49
	v_exp_f32_e32 v50, v50
	v_exp_f32_e32 v51, v51
	s_nop 0
	v_add_f32_e32 v48, 1.0, v48
	v_add_f32_e32 v49, 1.0, v49
	v_add_f32_e32 v50, 1.0, v50
	v_add_f32_e32 v51, 1.0, v51
	v_rcp_f32_e32 v48, v48
	v_rcp_f32_e32 v49, v49
	v_rcp_f32_e32 v50, v50
	v_rcp_f32_e32 v51, v51
	v_lshlrev_b32_e32 v154, 16, v236
	v_and_b32_e32 v155, 0xffff0000, v236
	v_lshlrev_b32_e32 v156, 16, v237
	v_and_b32_e32 v157, 0xffff0000, v237
	v_mul_f32_e32 v48, v48, v154
	v_mul_f32_e32 v49, v49, v155
	v_mul_f32_e32 v50, v50, v156
	v_mul_f32_e32 v51, v51, v157
	v_cvt_pk_bf16_f32 v236, v48, v49
	v_cvt_pk_bf16_f32 v237, v50, v51
	global_store_dwordx4 v174, v[230:233], s[4:5]
	global_store_dwordx4 v174, v[234:237], s[4:5] offset:256
	s_waitcnt vmcnt(14)
; __device__ __forceinline__ float sigm(float x) { return __builtin_amdgcn_rcpf(1.f + __expf(-x)); }
; __device__ __forceinline__ f32x4 ld_bf4(const bf16_t* p) { const u32x2 w = *(const u32x2*)p; f32x4 r; r[0] = __uint_as_float(w.x << 16); r[1] = __uint_as_float(w.x & 0xffff0000u); r[2] = __uint_as_float(w.y << 16); r[3] = __uint_as_float(w.y & 0xffff0000u); return r; }
; __device__ __forceinline__ void st_bf4(bf16_t* p, const f32x4 v) { u32x2 w; w.x = cvt_pk_bf16(v[0], v[1]); w.y = cvt_pk_bf16(v[2], v[3]); *(u32x2*)p = w; }
;     __device__ __forceinline__ void operator()(const f32x4 (&acc)[2][2][4][2], const Unit& u, int wr, int wc, int fr, int fq) const {
; #pragma unroll
;         for (int ai = 0; ai < 2; ++ai)
; #pragma unroll
;             for (int m = 0; m < 4; ++m) { const int row = u.pm * 256 + ai * 128 + wr * 64 + m * 16 + fr;
; #pragma unroll
;                 for (int bj = 0; bj < 2; ++bj)
; #pragma unroll
;                     for (int n = 0; n < 2; ++n) { const int col = u.pn * 256 + bj * 128 + wc * 32 + 8 * fq + 4 * n; const f32x4 v = acc[ai][bj][m][n];
;                         const f32x4 y0 = ld_bf4(YC0 + (size_t)row * 512 + col); f32x4 o;
; #pragma unroll
;                         for (int i = 0; i < 4; ++i) o[i] = y0[i] * sigm(v[i]);
;                         st_bf4(YC + (size_t)row * 512 + col, o); } }
	v_mul_f32_e32 v44, 0xbfb8aa3b, v44
	v_mul_f32_e32 v45, 0xbfb8aa3b, v45
	v_mul_f32_e32 v46, 0xbfb8aa3b, v46
	v_mul_f32_e32 v47, 0xbfb8aa3b, v47
	v_exp_f32_e32 v44, v44
	v_exp_f32_e32 v45, v45
	v_exp_f32_e32 v46, v46
	v_exp_f32_e32 v47, v47
	s_nop 0
	v_add_f32_e32 v44, 1.0, v44
	v_add_f32_e32 v45, 1.0, v45
	v_add_f32_e32 v46, 1.0, v46
	v_add_f32_e32 v47, 1.0, v47
	v_rcp_f32_e32 v44, v44
	v_rcp_f32_e32 v45, v45
	v_rcp_f32_e32 v46, v46
	v_rcp_f32_e32 v47, v47
	v_lshlrev_b32_e32 v154, 16, v238
	v_and_b32_e32 v155, 0xffff0000, v238
	v_lshlrev_b32_e32 v156, 16, v239
	v_and_b32_e32 v157, 0xffff0000, v239
	v_mul_f32_e32 v44, v44, v154
	v_mul_f32_e32 v45, v45, v155
	v_mul_f32_e32 v46, v46, v156
	v_mul_f32_e32 v47, v47, v157
	v_cvt_pk_bf16_f32 v238, v44, v45
	v_cvt_pk_bf16_f32 v239, v46, v47
	v_mul_f32_e32 v40, 0xbfb8aa3b, v40
	v_mul_f32_e32 v41, 0xbfb8aa3b, v41
	v_mul_f32_e32 v42, 0xbfb8aa3b, v42
	v_mul_f32_e32 v43, 0xbfb8aa3b, v43
	v_exp_f32_e32 v40, v40
	v_exp_f32_e32 v41, v41
	v_exp_f32_e32 v42, v42
	v_exp_f32_e32 v43, v43
	s_nop 0
	v_add_f32_e32 v40, 1.0, v40
	v_add_f32_e32 v41, 1.0, v41
	v_add_f32_e32 v42, 1.0, v42
	v_add_f32_e32 v43, 1.0, v43
	v_rcp_f32_e32 v40, v40
	v_rcp_f32_e32 v41, v41
	v_rcp_f32_e32 v42, v42
	v_rcp_f32_e32 v43, v43
	v_lshlrev_b32_e32 v154, 16, v240
	v_and_b32_e32 v155, 0xffff0000, v240
	v_lshlrev_b32_e32 v156, 16, v241
	v_and_b32_e32 v157, 0xffff0000, v241
	v_mul_f32_e32 v40, v40, v154
	v_mul_f32_e32 v41, v41, v155
	v_mul_f32_e32 v42, v42, v156
	v_mul_f32_e32 v43, v43, v157
	v_cvt_pk_bf16_f32 v240, v40, v41
	v_cvt_pk_bf16_f32 v241, v42, v43
	v_mul_f32_e32 v36, 0xbfb8aa3b, v36
	v_mul_f32_e32 v37, 0xbfb8aa3b, v37
	v_mul_f32_e32 v38, 0xbfb8aa3b, v38
	v_mul_f32_e32 v39, 0xbfb8aa3b, v39
	v_exp_f32_e32 v36, v36
	v_exp_f32_e32 v37, v37
	v_exp_f32_e32 v38, v38
	v_exp_f32_e32 v39, v39
	s_nop 0
	v_add_f32_e32 v36, 1.0, v36
	v_add_f32_e32 v37, 1.0, v37
	v_add_f32_e32 v38, 1.0, v38
	v_add_f32_e32 v39, 1.0, v39
	v_rcp_f32_e32 v36, v36
	v_rcp_f32_e32 v37, v37
	v_rcp_f32_e32 v38, v38
	v_rcp_f32_e32 v39, v39
	v_lshlrev_b32_e32 v154, 16, v242
	v_and_b32_e32 v155, 0xffff0000, v242
	v_lshlrev_b32_e32 v156, 16, v243
	v_and_b32_e32 v157, 0xffff0000, v243
	v_mul_f32_e32 v36, v36, v154
	v_mul_f32_e32 v37, v37, v155
	v_mul_f32_e32 v38, v38, v156
	v_mul_f32_e32 v39, v39, v157
	v_cvt_pk_bf16_f32 v242, v36, v37
	v_cvt_pk_bf16_f32 v243, v38, v39
	v_mul_f32_e32 v32, 0xbfb8aa3b, v32
	v_mul_f32_e32 v33, 0xbfb8aa3b, v33
	v_mul_f32_e32 v34, 0xbfb8aa3b, v34
	v_mul_f32_e32 v35, 0xbfb8aa3b, v35
	v_exp_f32_e32 v32, v32
	v_exp_f32_e32 v33, v33
	v_exp_f32_e32 v34, v34
	v_exp_f32_e32 v35, v35
	s_nop 0
	v_add_f32_e32 v32, 1.0, v32
	v_add_f32_e32 v33, 1.0, v33
	v_add_f32_e32 v34, 1.0, v34
	v_add_f32_e32 v35, 1.0, v35
	v_rcp_f32_e32 v32, v32
	v_rcp_f32_e32 v33, v33
	v_rcp_f32_e32 v34, v34
	v_rcp_f32_e32 v35, v35
	v_lshlrev_b32_e32 v154, 16, v244
	v_and_b32_e32 v155, 0xffff0000, v244
	v_lshlrev_b32_e32 v156, 16, v245
	v_and_b32_e32 v157, 0xffff0000, v245
	v_mul_f32_e32 v32, v32, v154
	v_mul_f32_e32 v33, v33, v155
	v_mul_f32_e32 v34, v34, v156
	v_mul_f32_e32 v35, v35, v157
	v_cvt_pk_bf16_f32 v244, v32, v33
	v_cvt_pk_bf16_f32 v245, v34, v35
	global_store_dwordx4 v175, v[238:241], s[4:5]
	global_store_dwordx4 v175, v[242:245], s[4:5] offset:256
	s_waitcnt vmcnt(14)
; __device__ __forceinline__ float sigm(float x) { return __builtin_amdgcn_rcpf(1.f + __expf(-x)); }
; __device__ __forceinline__ f32x4 ld_bf4(const bf16_t* p) { const u32x2 w = *(const u32x2*)p; f32x4 r; r[0] = __uint_as_float(w.x << 16); r[1] = __uint_as_float(w.x & 0xffff0000u); r[2] = __uint_as_float(w.y << 16); r[3] = __uint_as_float(w.y & 0xffff0000u); return r; }
; __device__ __forceinline__ void st_bf4(bf16_t* p, const f32x4 v) { u32x2 w; w.x = cvt_pk_bf16(v[0], v[1]); w.y = cvt_pk_bf16(v[2], v[3]); *(u32x2*)p = w; }
;     __device__ __forceinline__ void operator()(const f32x4 (&acc)[2][2][4][2], const Unit& u, int wr, int wc, int fr, int fq) const {
; #pragma unroll
;         for (int ai = 0; ai < 2; ++ai)
; #pragma unroll
;             for (int m = 0; m < 4; ++m) { const int row = u.pm * 256 + ai * 128 + wr * 64 + m * 16 + fr;
; #pragma unroll
;                 for (int bj = 0; bj < 2; ++bj)
; #pragma unroll
;                     for (int n = 0; n < 2; ++n) { const int col = u.pn * 256 + bj * 128 + wc * 32 + 8 * fq + 4 * n; const f32x4 v = acc[ai][bj][m][n];
;                         const f32x4 y0 = ld_bf4(YC0 + (size_t)row * 512 + col); f32x4 o;
; #pragma unroll
;                         for (int i = 0; i < 4; ++i) o[i] = y0[i] * sigm(v[i]);
;                         st_bf4(YC + (size_t)row * 512 + col, o); } }
	v_mul_f32_e32 v28, 0xbfb8aa3b, v28
	v_mul_f32_e32 v29, 0xbfb8aa3b, v29
	v_mul_f32_e32 v30, 0xbfb8aa3b, v30
	v_mul_f32_e32 v31, 0xbfb8aa3b, v31
	v_exp_f32_e32 v28, v28
	v_exp_f32_e32 v29, v29
	v_exp_f32_e32 v30, v30
	v_exp_f32_e32 v31, v31
	s_nop 0
	v_add_f32_e32 v28, 1.0, v28
	v_add_f32_e32 v29, 1.0, v29
	v_add_f32_e32 v30, 1.0, v30
	v_add_f32_e32 v31, 1.0, v31
	v_rcp_f32_e32 v28, v28
	v_rcp_f32_e32 v29, v29
	v_rcp_f32_e32 v30, v30
	v_rcp_f32_e32 v31, v31
	v_lshlrev_b32_e32 v154, 16, v246
	v_and_b32_e32 v155, 0xffff0000, v246
	v_lshlrev_b32_e32 v156, 16, v247
	v_and_b32_e32 v157, 0xffff0000, v247
	v_mul_f32_e32 v28, v28, v154
	v_mul_f32_e32 v29, v29, v155
	v_mul_f32_e32 v30, v30, v156
	v_mul_f32_e32 v31, v31, v157
	v_cvt_pk_bf16_f32 v246, v28, v29
	v_cvt_pk_bf16_f32 v247, v30, v31
	v_mul_f32_e32 v24, 0xbfb8aa3b, v24
	v_mul_f32_e32 v25, 0xbfb8aa3b, v25
	v_mul_f32_e32 v26, 0xbfb8aa3b, v26
	v_mul_f32_e32 v27, 0xbfb8aa3b, v27
	v_exp_f32_e32 v24, v24
	v_exp_f32_e32 v25, v25
	v_exp_f32_e32 v26, v26
	v_exp_f32_e32 v27, v27
	s_nop 0
	v_add_f32_e32 v24, 1.0, v24
	v_add_f32_e32 v25, 1.0, v25
	v_add_f32_e32 v26, 1.0, v26
	v_add_f32_e32 v27, 1.0, v27
	v_rcp_f32_e32 v24, v24
	v_rcp_f32_e32 v25, v25
	v_rcp_f32_e32 v26, v26
	v_rcp_f32_e32 v27, v27
	v_lshlrev_b32_e32 v154, 16, v248
	v_and_b32_e32 v155, 0xffff0000, v248
	v_lshlrev_b32_e32 v156, 16, v249
	v_and_b32_e32 v157, 0xffff0000, v249
	v_mul_f32_e32 v24, v24, v154
	v_mul_f32_e32 v25, v25, v155
	v_mul_f32_e32 v26, v26, v156
	v_mul_f32_e32 v27, v27, v157
	v_cvt_pk_bf16_f32 v248, v24, v25
	v_cvt_pk_bf16_f32 v249, v26, v27
	v_mul_f32_e32 v20, 0xbfb8aa3b, v20
	v_mul_f32_e32 v21, 0xbfb8aa3b, v21
	v_mul_f32_e32 v22, 0xbfb8aa3b, v22
	v_mul_f32_e32 v23, 0xbfb8aa3b, v23
	v_exp_f32_e32 v20, v20
	v_exp_f32_e32 v21, v21
	v_exp_f32_e32 v22, v22
	v_exp_f32_e32 v23, v23
	s_nop 0
	v_add_f32_e32 v20, 1.0, v20
	v_add_f32_e32 v21, 1.0, v21
	v_add_f32_e32 v22, 1.0, v22
	v_add_f32_e32 v23, 1.0, v23
	v_rcp_f32_e32 v20, v20
	v_rcp_f32_e32 v21, v21
	v_rcp_f32_e32 v22, v22
	v_rcp_f32_e32 v23, v23
	v_lshlrev_b32_e32 v154, 16, v250
	v_and_b32_e32 v155, 0xffff0000, v250
	v_lshlrev_b32_e32 v156, 16, v251
	v_and_b32_e32 v157, 0xffff0000, v251
	v_mul_f32_e32 v20, v20, v154
	v_mul_f32_e32 v21, v21, v155
	v_mul_f32_e32 v22, v22, v156
	v_mul_f32_e32 v23, v23, v157
	v_cvt_pk_bf16_f32 v250, v20, v21
	v_cvt_pk_bf16_f32 v251, v22, v23
	v_mul_f32_e32 v16, 0xbfb8aa3b, v16
	v_mul_f32_e32 v17, 0xbfb8aa3b, v17
	v_mul_f32_e32 v18, 0xbfb8aa3b, v18
	v_mul_f32_e32 v19, 0xbfb8aa3b, v19
	v_exp_f32_e32 v16, v16
	v_exp_f32_e32 v17, v17
	v_exp_f32_e32 v18, v18
	v_exp_f32_e32 v19, v19
	s_nop 0
	v_add_f32_e32 v16, 1.0, v16
	v_add_f32_e32 v17, 1.0, v17
	v_add_f32_e32 v18, 1.0, v18
	v_add_f32_e32 v19, 1.0, v19
	v_rcp_f32_e32 v16, v16
	v_rcp_f32_e32 v17, v17
	v_rcp_f32_e32 v18, v18
	v_rcp_f32_e32 v19, v19
	v_lshlrev_b32_e32 v154, 16, v252
	v_and_b32_e32 v155, 0xffff0000, v252
	v_lshlrev_b32_e32 v156, 16, v253
	v_and_b32_e32 v157, 0xffff0000, v253
	v_mul_f32_e32 v16, v16, v154
	v_mul_f32_e32 v17, v17, v155
	v_mul_f32_e32 v18, v18, v156
	v_mul_f32_e32 v19, v19, v157
	v_cvt_pk_bf16_f32 v252, v16, v17
	v_cvt_pk_bf16_f32 v253, v18, v19
	global_store_dwordx4 v176, v[246:249], s[4:5]
	global_store_dwordx4 v176, v[250:253], s[4:5] offset:256
	s_waitcnt vmcnt(14)
	v_mul_f32_e32 v12, 0xbfb8aa3b, v12
	v_mul_f32_e32 v13, 0xbfb8aa3b, v13
	v_mul_f32_e32 v14, 0xbfb8aa3b, v14
	v_mul_f32_e32 v15, 0xbfb8aa3b, v15
	v_exp_f32_e32 v12, v12
	v_exp_f32_e32 v13, v13
	v_exp_f32_e32 v14, v14
	v_exp_f32_e32 v15, v15
	s_nop 0
	v_add_f32_e32 v12, 1.0, v12
	v_add_f32_e32 v13, 1.0, v13
	v_add_f32_e32 v14, 1.0, v14
	v_add_f32_e32 v15, 1.0, v15
	v_rcp_f32_e32 v12, v12
	v_rcp_f32_e32 v13, v13
	v_rcp_f32_e32 v14, v14
	v_rcp_f32_e32 v15, v15
	v_lshlrev_b32_e32 v154, 16, v182
	v_and_b32_e32 v155, 0xffff0000, v182
	v_lshlrev_b32_e32 v156, 16, v183
	v_and_b32_e32 v157, 0xffff0000, v183
	v_mul_f32_e32 v12, v12, v154
	v_mul_f32_e32 v13, v13, v155
	v_mul_f32_e32 v14, v14, v156
	v_mul_f32_e32 v15, v15, v157
	v_cvt_pk_bf16_f32 v182, v12, v13
	v_cvt_pk_bf16_f32 v183, v14, v15
	v_mul_f32_e32 v8, 0xbfb8aa3b, v8
	v_mul_f32_e32 v9, 0xbfb8aa3b, v9
	v_mul_f32_e32 v10, 0xbfb8aa3b, v10
	v_mul_f32_e32 v11, 0xbfb8aa3b, v11
	v_exp_f32_e32 v8, v8
	v_exp_f32_e32 v9, v9
	v_exp_f32_e32 v10, v10
	v_exp_f32_e32 v11, v11
	s_nop 0
	v_add_f32_e32 v8, 1.0, v8
	v_add_f32_e32 v9, 1.0, v9
	v_add_f32_e32 v10, 1.0, v10
	v_add_f32_e32 v11, 1.0, v11
	v_rcp_f32_e32 v8, v8
	v_rcp_f32_e32 v9, v9
	v_rcp_f32_e32 v10, v10
	v_rcp_f32_e32 v11, v11
	v_lshlrev_b32_e32 v154, 16, v184
	v_and_b32_e32 v155, 0xffff0000, v184
	v_lshlrev_b32_e32 v156, 16, v185
	v_and_b32_e32 v157, 0xffff0000, v185
	v_mul_f32_e32 v8, v8, v154
	v_mul_f32_e32 v9, v9, v155
	v_mul_f32_e32 v10, v10, v156
	v_mul_f32_e32 v11, v11, v157
	v_cvt_pk_bf16_f32 v184, v8, v9
	v_cvt_pk_bf16_f32 v185, v10, v11
	v_mul_f32_e32 v4, 0xbfb8aa3b, v4
	v_mul_f32_e32 v5, 0xbfb8aa3b, v5
	v_mul_f32_e32 v6, 0xbfb8aa3b, v6
	v_mul_f32_e32 v7, 0xbfb8aa3b, v7
	v_exp_f32_e32 v4, v4
	v_exp_f32_e32 v5, v5
	v_exp_f32_e32 v6, v6
	v_exp_f32_e32 v7, v7
	s_nop 0
	v_add_f32_e32 v4, 1.0, v4
	v_add_f32_e32 v5, 1.0, v5
	v_add_f32_e32 v6, 1.0, v6
	v_add_f32_e32 v7, 1.0, v7
	v_rcp_f32_e32 v4, v4
	v_rcp_f32_e32 v5, v5
	v_rcp_f32_e32 v6, v6
	v_rcp_f32_e32 v7, v7
	v_lshlrev_b32_e32 v154, 16, v186
	v_and_b32_e32 v155, 0xffff0000, v186
	v_lshlrev_b32_e32 v156, 16, v187
	v_and_b32_e32 v157, 0xffff0000, v187
	v_mul_f32_e32 v4, v4, v154
	v_mul_f32_e32 v5, v5, v155
	v_mul_f32_e32 v6, v6, v156
	v_mul_f32_e32 v7, v7, v157
	v_cvt_pk_bf16_f32 v186, v4, v5
	v_cvt_pk_bf16_f32 v187, v6, v7
	v_mul_f32_e32 v0, 0xbfb8aa3b, v0
	v_mul_f32_e32 v1, 0xbfb8aa3b, v1
	v_mul_f32_e32 v2, 0xbfb8aa3b, v2
	v_mul_f32_e32 v3, 0xbfb8aa3b, v3
	v_exp_f32_e32 v0, v0
	v_exp_f32_e32 v1, v1
	v_exp_f32_e32 v2, v2
	v_exp_f32_e32 v3, v3
	s_nop 0
	v_add_f32_e32 v0, 1.0, v0
	v_add_f32_e32 v1, 1.0, v1
	v_add_f32_e32 v2, 1.0, v2
	v_add_f32_e32 v3, 1.0, v3
	v_rcp_f32_e32 v0, v0
	v_rcp_f32_e32 v1, v1
	v_rcp_f32_e32 v2, v2
	v_rcp_f32_e32 v3, v3
	v_lshlrev_b32_e32 v154, 16, v188
	v_and_b32_e32 v155, 0xffff0000, v188
	v_lshlrev_b32_e32 v156, 16, v189
	v_and_b32_e32 v157, 0xffff0000, v189
	v_mul_f32_e32 v0, v0, v154
	v_mul_f32_e32 v1, v1, v155
	v_mul_f32_e32 v2, v2, v156
	v_mul_f32_e32 v3, v3, v157
	v_cvt_pk_bf16_f32 v188, v0, v1
	v_cvt_pk_bf16_f32 v189, v2, v3
	global_store_dwordx4 v177, v[182:185], s[4:5]
	global_store_dwordx4 v177, v[186:189], s[4:5] offset:256
	s_cbranch_vccnz .LBB0_460
	s_andn2_b64 vcc, exec, s[2:3]
	s_cbranch_vccnz .LBB0_459
	s_barrier
	s_branch .LBB0_459

;     __device__ __forceinline__ void operator()(const f32x4 (&acc)[2][2][4][2], const Unit& u, int wr, int wc, int fr, int fq) const {
;         const int pn = u.pn;
; #pragma unroll
;         for (int ai = 0; ai < 2; ++ai)
; #pragma unroll
;             for (int m = 0; m < 4; ++m) { const int row = u.pm * 256 + ai * 128 + wr * 64 + m * 16 + fr;
; #pragma unroll
;                 for (int bj = 0; bj < 2; ++bj)
; #pragma unroll
;                     for (int n = 0; n < 2; ++n) { const int tc = bj * 128 + wc * 32 + 8 * fq + 4 * n; f32x4 v = acc[ai][bj][m][n];
;                         if (pn < 2) { *(f32x4*)(XA + (size_t)row * 512 + pn * 256 + tc) = v; }
;                         else if (pn <= 4) {
;                             const bool isv = (pn == 4 && bj == 1);
;                             if (!isv && (wc & 1) == 0) {
;                                 const int tix = row < cfg::MP ? (row & 2047) : 2048 + (row & 3);
;                                 const f32x4 cs = *(const f32x4*)(ropec + tix * 8 + 4 * n), sn = *(const f32x4*)(ropes + tix * 8 + 4 * n);
; #pragma unroll
;                                 for (int i = 0; i < 4; ++i) { const float p = shx16(v[i], fq & 1); const float rv = v[i] * cs[i] + (fq == 0 ? -p : p) * sn[i]; v[i] = fq < 2 ? rv : v[i]; }
;                             }
;                             if (pn < 4) st_bf4(Q + (size_t)row * 512 + (pn - 2) * 256 + tc, v);
;                             else { st_bf4((bj == 0 ? KB : VB) + (size_t)row * 128 + (tc & 127), v);
;                                 bool w = false; size_t o = 0;
;                                 if (row < cfg::MP) { const int t = row & 2047; if (t >= 1920) { w = true; o = (bj == 0 ? cfg::OFF_KP : cfg::OFF_VP) + ((size_t)(layer * 8 + (row >> 11)) * 128 + (t - 1920)) * 128 + (tc & 127); } }
;                                 else { const int rs = row - cfg::MP; w = true; o = (bj == 0 ? cfg::OFF_KS : cfg::OFF_VS) + ((size_t)(layer * 128 + (rs >> 2)) * 128 + 124 + (rs & 3)) * 128 + (tc & 127); }
;                                 if (w) *(f32x4*)(out + o) = v; }
;                         }
;                         else if (pn < 7) { *(f32x4*)(U + (size_t)row * 512 + (pn - 5) * 256 + tc) = v; }
;                         else { f32x4 s; s[0] = sigm(v[0]); s[1] = sigm(v[1]); s[2] = sigm(v[2]); s[3] = sigm(v[3]); st_bf4(GT + (size_t)row * 3072 + (pn - 7) * 256 + tc, s); }
.LBB0_1030:
	s_lshl_b32 s53, s0, 8
	v_readlane_b32 s0, v254, 56
	s_add_i32 s53, s53, s0
	s_cmp_gt_i32 s14, 1
	s_cselect_b64 s[70:71], -1, 0
	s_cmp_gt_u32 s14, 4
	s_cselect_b64 s[78:79], -1, 0
	s_cmp_gt_u32 s14, 6
	s_cselect_b64 s[90:91], -1, 0
	s_lshl_b32 s0, s14, 8
	s_add_i32 s56, s0, 0xfffff900
	s_cmp_lg_u32 s14, 4
	v_or_b32_e32 v172, s53, v143
	s_cselect_b64 s[28:29], -1, 0
	s_cmp_eq_u32 s14, 4
	v_mad_i64_i32 v[180:181], s[14:15], v172, s61, 0
	s_movk_i32 s14, 0x3fff
	s_nop 0
	v_cmp_lt_i32_e64 s[20:21], s14, v172
	v_mov_b32_e32 v96, 0x7cf
	s_movk_i32 s14, 0x4000
	v_bitop3_b32 v96, s53, v96, v143 bitop3:0xc8
	v_cmp_gt_i32_e32 vcc, s14, v172
	s_movk_i32 s14, 0x77f
	v_cmp_lt_u32_e64 s[18:19], s14, v96
	v_cndmask_b32_e32 v130, v151, v96, vcc
	v_add_u32_e32 v96, 0xfffff880, v96
	v_ashrrev_i32_e32 v173, 31, v172
	v_lshlrev_b32_e32 v203, 3, v130
	v_add_u32_e32 v130, 0xffffc000, v172
	v_lshlrev_b64 v[182:183], 7, v[96:97]
	s_mov_b64 s[14:15], 0x1080000
	s_mov_b32 s1, s57
	s_cselect_b64 s[96:97], -1, 0
	s_ashr_i32 s75, s53, 11
	v_lshlrev_b64 v[178:179], 11, v[172:173]
	v_lshlrev_b64 v[176:177], 8, v[172:173]
	v_lshrrev_b32_e32 v202, 2, v130
	v_lshlrev_b64 v[174:175], 10, v[172:173]
	v_lshl_add_u64 v[184:185], v[182:183], 0, s[14:15]
	s_mov_b64 s[14:15], -1
	s_and_b64 vcc, exec, s[90:91]
	s_cbranch_vccnz .Lsp_gt
	s_and_b64 vcc, exec, s[78:79]
	s_cbranch_vccnz .Lsp_u
	s_and_b64 vcc, exec, s[70:71]
	s_cbranch_vccz .Lsp_xa
	s_and_b64 vcc, exec, s[70:71]
	s_cbranch_vccz .LBB0_1045
	s_and_b64 vcc, exec, s[78:79]
	s_cbranch_vccz .LBB0_1037
	s_and_b64 vcc, exec, s[90:91]
	s_cbranch_vccz .LBB0_1034
	v_mul_f32_e32 v96, 0xbfb8aa3b, v126
	v_exp_f32_e32 v96, v96
	v_mul_f32_e32 v130, 0xbfb8aa3b, v127
	v_exp_f32_e32 v130, v130
	v_mul_f32_e32 v131, 0xbfb8aa3b, v129
	v_add_f32_e32 v96, 1.0, v96
	v_rcp_f32_e32 v132, v96
	v_mul_f32_e32 v96, 0xbfb8aa3b, v128
	v_exp_f32_e32 v96, v96
	v_exp_f32_e32 v131, v131
	v_add_f32_e32 v130, 1.0, v130
	v_rcp_f32_e32 v133, v130
	v_add_f32_e32 v96, 1.0, v96
	v_rcp_f32_e32 v146, v96
	v_add_f32_e32 v96, 1.0, v131
	v_lshl_add_u64 v[130:131], s[54:55], 0, v[180:181]
	v_rcp_f32_e32 v147, v96
	v_lshl_add_u64 v[130:131], s[56:57], 1, v[130:131]
	v_lshlrev_b32_e32 v96, 1, v142
	v_lshl_add_u64 v[130:131], v[130:131], 0, v[96:97]
	v_cvt_pk_bf16_f32 v190, v132, v133
	v_cvt_pk_bf16_f32 v191, v146, v147
	s_mov_b64 s[14:15], 0

; __device__ __forceinline__ float sigm(float x) { return __builtin_amdgcn_rcpf(1.f + __expf(-x)); }
; __device__ __forceinline__ void st_bf4(bf16_t* p, const f32x4 v) { u32x2 w; w.x = cvt_pk_bf16(v[0], v[1]); w.y = cvt_pk_bf16(v[2], v[3]); *(u32x2*)p = w; }
;     __device__ __forceinline__ void operator()(const f32x4 (&acc)[2][2][4][2], const Unit& u, int wr, int wc, int fr, int fq) const {
;     ...
;                         else { f32x4 s; s[0] = sigm(v[0]); s[1] = sigm(v[1]); s[2] = sigm(v[2]); s[3] = sigm(v[3]); st_bf4(GT + (size_t)row * 3072 + (pn - 7) * 256 + tc, s); }
.LBB0_1047:
	v_cndmask_b32_e64 v96, 0, 1, s[70:71]
	v_cmp_ne_u32_e64 s[16:17], 1, v96
	v_cndmask_b32_e64 v96, 0, 1, s[78:79]
	s_mov_b64 s[80:81], -1
	s_andn2_b64 vcc, exec, s[70:71]
	v_cmp_ne_u32_e64 s[14:15], 1, v96
	s_cbranch_vccnz .LBB0_1062
	s_and_b64 vcc, exec, s[14:15]
	s_mov_b64 s[70:71], -1
	s_cbranch_vccnz .LBB0_1054
	s_andn2_b64 vcc, exec, s[90:91]
	s_cbranch_vccnz .LBB0_1051
	v_mul_f32_e32 v96, 0xbfb8aa3b, v122
	v_exp_f32_e32 v96, v96
	v_mul_f32_e32 v126, 0xbfb8aa3b, v123
	v_exp_f32_e32 v126, v126
	v_mul_f32_e32 v127, 0xbfb8aa3b, v125
	v_add_f32_e32 v96, 1.0, v96
	v_rcp_f32_e32 v128, v96
	v_mul_f32_e32 v96, 0xbfb8aa3b, v124
	v_exp_f32_e32 v96, v96
	v_exp_f32_e32 v127, v127
	v_add_f32_e32 v126, 1.0, v126
	v_rcp_f32_e32 v129, v126
	v_add_f32_e32 v96, 1.0, v96
	v_rcp_f32_e32 v131, v96
	v_add_f32_e32 v96, 1.0, v127
	v_lshl_add_u64 v[126:127], s[54:55], 0, v[180:181]
	v_rcp_f32_e32 v146, v96
	v_lshl_add_u64 v[126:127], s[56:57], 1, v[126:127]
	v_lshlrev_b32_e32 v96, 1, v142
	v_lshl_add_u64 v[126:127], v[126:127], 0, v[96:97]
	s_mov_b64 s[70:71], 0
	v_cvt_pk_bf16_f32 v192, v128, v129
	v_cvt_pk_bf16_f32 v193, v131, v146
	global_store_dwordx4 v[126:127], v[190:193], off

; __device__ __forceinline__ float sigm(float x) { return __builtin_amdgcn_rcpf(1.f + __expf(-x)); }
; __device__ __forceinline__ void st_bf4(bf16_t* p, const f32x4 v) { u32x2 w; w.x = cvt_pk_bf16(v[0], v[1]); w.y = cvt_pk_bf16(v[2], v[3]); *(u32x2*)p = w; }
;     __device__ __forceinline__ void operator()(const f32x4 (&acc)[2][2][4][2], const Unit& u, int wr, int wc, int fr, int fq) const {
;     ...
;                         else { f32x4 s; s[0] = sigm(v[0]); s[1] = sigm(v[1]); s[2] = sigm(v[2]); s[3] = sigm(v[3]); st_bf4(GT + (size_t)row * 3072 + (pn - 7) * 256 + tc, s); }
.LBB0_1064:
	v_readlane_b32 s70, v254, 59
	v_readlane_b32 s71, v254, 60
	s_and_b64 s[28:29], s[70:71], s[28:29]
	s_mov_b64 s[78:79], 0x1100000
	s_mov_b64 s[70:71], -1
	s_xor_b64 s[28:29], s[28:29], -1
	s_and_b64 vcc, exec, s[16:17]
	v_lshl_add_u64 v[126:127], v[182:183], 0, s[78:79]
	s_cbranch_vccnz .LBB0_1094
	s_and_b64 vcc, exec, s[14:15]
	s_cbranch_vccnz .LBB0_1071
	s_andn2_b64 vcc, exec, s[90:91]
	s_cbranch_vccnz .LBB0_1068
	v_mul_f32_e32 v96, 0xbfb8aa3b, v118
	v_exp_f32_e32 v96, v96
	v_mul_f32_e32 v122, 0xbfb8aa3b, v119
	v_exp_f32_e32 v122, v122
	v_mul_f32_e32 v123, 0xbfb8aa3b, v121
	v_add_f32_e32 v96, 1.0, v96
	v_rcp_f32_e32 v124, v96
	v_mul_f32_e32 v96, 0xbfb8aa3b, v120
	v_exp_f32_e32 v96, v96
	v_exp_f32_e32 v123, v123
	v_add_f32_e32 v122, 1.0, v122
	v_rcp_f32_e32 v125, v122
	v_add_f32_e32 v96, 1.0, v96
	v_rcp_f32_e32 v128, v96
	v_add_f32_e32 v96, 1.0, v123
	v_lshl_add_u64 v[122:123], s[54:55], 0, v[180:181]
	v_rcp_f32_e32 v129, v96
	v_lshl_add_u64 v[122:123], s[56:57], 1, v[122:123]
	v_lshlrev_b32_e32 v96, 1, v142
	v_lshl_add_u64 v[122:123], v[122:123], 0, v[96:97]
	s_mov_b64 s[70:71], 0
	v_cvt_pk_bf16_f32 v198, v124, v125
	v_cvt_pk_bf16_f32 v199, v128, v129

; __device__ __forceinline__ float sigm(float x) { return __builtin_amdgcn_rcpf(1.f + __expf(-x)); }
; __device__ __forceinline__ void st_bf4(bf16_t* p, const f32x4 v) { u32x2 w; w.x = cvt_pk_bf16(v[0], v[1]); w.y = cvt_pk_bf16(v[2], v[3]); *(u32x2*)p = w; }
;     __device__ __forceinline__ void operator()(const f32x4 (&acc)[2][2][4][2], const Unit& u, int wr, int wc, int fr, int fq) const {
;     ...
;                         else { f32x4 s; s[0] = sigm(v[0]); s[1] = sigm(v[1]); s[2] = sigm(v[2]); s[3] = sigm(v[3]); st_bf4(GT + (size_t)row * 3072 + (pn - 7) * 256 + tc, s); }
.LBB0_1080:
	s_and_b64 vcc, exec, s[14:15]
	s_cbranch_vccnz .LBB0_1086
	s_andn2_b64 vcc, exec, s[90:91]
	s_cbranch_vccnz .LBB0_1083
	v_mul_f32_e32 v96, 0xbfb8aa3b, v114
	v_exp_f32_e32 v96, v96
	v_mul_f32_e32 v118, 0xbfb8aa3b, v115
	v_exp_f32_e32 v118, v118
	v_mul_f32_e32 v119, 0xbfb8aa3b, v117
	v_add_f32_e32 v96, 1.0, v96
	v_rcp_f32_e32 v120, v96
	v_mul_f32_e32 v96, 0xbfb8aa3b, v116
	v_exp_f32_e32 v96, v96
	v_exp_f32_e32 v119, v119
	v_add_f32_e32 v118, 1.0, v118
	v_rcp_f32_e32 v121, v118
	v_add_f32_e32 v96, 1.0, v96
	v_rcp_f32_e32 v122, v96
	v_add_f32_e32 v96, 1.0, v119
	v_lshl_add_u64 v[118:119], s[54:55], 0, v[180:181]
	v_rcp_f32_e32 v123, v96
	v_lshl_add_u64 v[118:119], s[56:57], 1, v[118:119]
	v_lshlrev_b32_e32 v96, 1, v142
	v_lshl_add_u64 v[118:119], v[118:119], 0, v[96:97]
	s_mov_b64 s[70:71], 0
	v_cvt_pk_bf16_f32 v200, v120, v121
	v_cvt_pk_bf16_f32 v201, v122, v123
	global_store_dwordx4 v[118:119], v[198:201], off offset:256

; __device__ __forceinline__ float sigm(float x) { return __builtin_amdgcn_rcpf(1.f + __expf(-x)); }
;     __device__ __forceinline__ void operator()(const f32x4 (&acc)[2][2][4][2], const Unit& u, int wr, int wc, int fr, int fq) const {
;     ...
;             for (int m = 0; m < 4; ++m) { const int row = u.pm * 256 + ai * 128 + wr * 64 + m * 16 + fr;
; #pragma unroll
;                 for (int bj = 0; bj < 2; ++bj)
; #pragma unroll
;                     for (int n = 0; n < 2; ++n) { const int tc = bj * 128 + wc * 32 + 8 * fq + 4 * n; f32x4 v = acc[ai][bj][m][n];
;                         if (pn < 2) { *(f32x4*)(XA + (size_t)row * 512 + pn * 256 + tc) = v; }
;                         else if (pn <= 4) {
;                             const bool isv = (pn == 4 && bj == 1);
;                             if (!isv && (wc & 1) == 0) {
;                                 const int tix = row < cfg::MP ? (row & 2047) : 2048 + (row & 3);
;                                 const f32x4 cs = *(const f32x4*)(ropec + tix * 8 + 4 * n), sn = *(const f32x4*)(ropes + tix * 8 + 4 * n);
; #pragma unroll
;                                 for (int i = 0; i < 4; ++i) { const float p = shx16(v[i], fq & 1); const float rv = v[i] * cs[i] + (fq == 0 ? -p : p) * sn[i]; v[i] = fq < 2 ? rv : v[i]; }
;                             }
;                             if (pn < 4) st_bf4(Q + (size_t)row * 512 + (pn - 2) * 256 + tc, v);
;                             else { st_bf4((bj == 0 ? KB : VB) + (size_t)row * 128 + (tc & 127), v);
;                                 bool w = false; size_t o = 0;
;                                 if (row < cfg::MP) { const int t = row & 2047; if (t >= 1920) { w = true; o = (bj == 0 ? cfg::OFF_KP : cfg::OFF_VP) + ((size_t)(layer * 8 + (row >> 11)) * 128 + (t - 1920)) * 128 + (tc & 127); } }
;                                 else { const int rs = row - cfg::MP; w = true; o = (bj == 0 ? cfg::OFF_KS : cfg::OFF_VS) + ((size_t)(layer * 128 + (rs >> 2)) * 128 + 124 + (rs & 3)) * 128 + (tc & 127); }
;                                 if (w) *(f32x4*)(out + o) = v; }
;                         }
;                         else if (pn < 7) { *(f32x4*)(U + (size_t)row * 512 + (pn - 5) * 256 + tc) = v; }
;                         else { f32x4 s; s[0] = sigm(v[0]); s[1] = sigm(v[1]); s[2] = sigm(v[2]); s[3] = sigm(v[3]); st_bf4(GT + (size_t)row * 3072 + (pn - 7) * 256 + tc, s); }
.LBB0_1098:
	s_nop 1
	v_or_b32_e32 v114, 16, v172
	v_mad_i64_i32 v[124:125], s[18:19], v114, s61, 0
	s_movk_i32 s18, 0x3fff
	s_nop 0
	v_cmp_lt_i32_e64 s[20:21], s18, v114
	s_movk_i32 s18, 0x7df
	v_bitop3_b32 v96, v172, s18, 16 bitop3:0xc8
	s_movk_i32 s18, 0x4000
	v_cmp_gt_i32_e32 vcc, s18, v114
	s_movk_i32 s18, 0x77f
	v_cmp_lt_u32_e64 s[18:19], s18, v96
	v_cndmask_b32_e32 v116, v151, v96, vcc
	v_add_u32_e32 v96, 0xfffff880, v96
	v_ashrrev_i32_e32 v115, 31, v114
	v_lshlrev_b32_e32 v176, 3, v116
	v_add_u32_e32 v116, 0xffffc010, v172
	v_lshlrev_b64 v[126:127], 7, v[96:97]
	s_mov_b64 s[70:71], 0x1080000
	v_lshlrev_b64 v[122:123], 11, v[114:115]
	v_lshlrev_b64 v[120:121], 8, v[114:115]
	v_lshrrev_b32_e32 v173, 2, v116
	v_lshlrev_b64 v[118:119], 10, v[114:115]
	v_lshl_add_u64 v[128:129], v[126:127], 0, s[70:71]
	s_and_b64 vcc, exec, s[16:17]
	s_mov_b64 s[70:71], -1
	s_cbranch_vccnz .LBB0_1128
	s_and_b64 vcc, exec, s[14:15]
	s_cbranch_vccnz .LBB0_1105
	s_andn2_b64 vcc, exec, s[90:91]
	s_cbranch_vccnz .LBB0_1102
	v_mul_f32_e32 v96, 0xbfb8aa3b, v110
	v_exp_f32_e32 v96, v96
	v_mul_f32_e32 v114, 0xbfb8aa3b, v111
	v_exp_f32_e32 v114, v114
	v_mul_f32_e32 v115, 0xbfb8aa3b, v113
	v_add_f32_e32 v96, 1.0, v96
	v_rcp_f32_e32 v116, v96
	v_mul_f32_e32 v96, 0xbfb8aa3b, v112
	v_exp_f32_e32 v96, v96
	v_exp_f32_e32 v115, v115
	v_add_f32_e32 v114, 1.0, v114
	v_rcp_f32_e32 v117, v114
	v_add_f32_e32 v96, 1.0, v96
	v_rcp_f32_e32 v131, v96
	v_add_f32_e32 v96, 1.0, v115
	v_lshl_add_u64 v[114:115], s[54:55], 0, v[124:125]
	v_rcp_f32_e32 v132, v96
	v_lshl_add_u64 v[114:115], s[56:57], 1, v[114:115]
	v_lshlrev_b32_e32 v96, 1, v142
	v_lshl_add_u64 v[114:115], v[114:115], 0, v[96:97]
	s_mov_b64 s[70:71], 0
	v_cvt_pk_bf16_f32 v250, v116, v117
	v_cvt_pk_bf16_f32 v251, v131, v132

; __device__ __forceinline__ float sigm(float x) { return __builtin_amdgcn_rcpf(1.f + __expf(-x)); }
; __device__ __forceinline__ void st_bf4(bf16_t* p, const f32x4 v) { u32x2 w; w.x = cvt_pk_bf16(v[0], v[1]); w.y = cvt_pk_bf16(v[2], v[3]); *(u32x2*)p = w; }
;     __device__ __forceinline__ void operator()(const f32x4 (&acc)[2][2][4][2], const Unit& u, int wr, int wc, int fr, int fq) const {
;     ...
;                         else { f32x4 s; s[0] = sigm(v[0]); s[1] = sigm(v[1]); s[2] = sigm(v[2]); s[3] = sigm(v[3]); st_bf4(GT + (size_t)row * 3072 + (pn - 7) * 256 + tc, s); }
.LBB0_1114:
	s_and_b64 vcc, exec, s[14:15]
	s_cbranch_vccnz .LBB0_1120
	s_andn2_b64 vcc, exec, s[90:91]
	s_cbranch_vccnz .LBB0_1117
	v_mul_f32_e32 v96, 0xbfb8aa3b, v106
	v_exp_f32_e32 v96, v96
	v_mul_f32_e32 v110, 0xbfb8aa3b, v107
	v_exp_f32_e32 v110, v110
	v_mul_f32_e32 v111, 0xbfb8aa3b, v109
	v_add_f32_e32 v96, 1.0, v96
	v_rcp_f32_e32 v112, v96
	v_mul_f32_e32 v96, 0xbfb8aa3b, v108
	v_exp_f32_e32 v96, v96
	v_exp_f32_e32 v111, v111
	v_add_f32_e32 v110, 1.0, v110
	v_rcp_f32_e32 v113, v110
	v_add_f32_e32 v96, 1.0, v96
	v_rcp_f32_e32 v116, v96
	v_add_f32_e32 v96, 1.0, v111
	v_lshl_add_u64 v[110:111], s[54:55], 0, v[124:125]
	v_rcp_f32_e32 v117, v96
	v_lshl_add_u64 v[110:111], s[56:57], 1, v[110:111]
	v_lshlrev_b32_e32 v96, 1, v142
	v_lshl_add_u64 v[110:111], v[110:111], 0, v[96:97]
	s_mov_b64 s[70:71], 0
	v_cvt_pk_bf16_f32 v252, v112, v113
	v_cvt_pk_bf16_f32 v253, v116, v117
	global_store_dwordx4 v[110:111], v[250:253], off

; __device__ __forceinline__ float sigm(float x) { return __builtin_amdgcn_rcpf(1.f + __expf(-x)); }
; __device__ __forceinline__ void st_bf4(bf16_t* p, const f32x4 v) { u32x2 w; w.x = cvt_pk_bf16(v[0], v[1]); w.y = cvt_pk_bf16(v[2], v[3]); *(u32x2*)p = w; }
;     __device__ __forceinline__ void operator()(const f32x4 (&acc)[2][2][4][2], const Unit& u, int wr, int wc, int fr, int fq) const {
;     ...
;                         else { f32x4 s; s[0] = sigm(v[0]); s[1] = sigm(v[1]); s[2] = sigm(v[2]); s[3] = sigm(v[3]); st_bf4(GT + (size_t)row * 3072 + (pn - 7) * 256 + tc, s); }
.LBB0_1132:
	s_mov_b64 s[70:71], 0x1100000
	v_lshl_add_u64 v[110:111], v[126:127], 0, s[70:71]
	s_and_b64 vcc, exec, s[16:17]
	s_mov_b64 s[70:71], -1
	s_cbranch_vccnz .LBB0_1162
	s_and_b64 vcc, exec, s[14:15]
	s_cbranch_vccnz .LBB0_1139
	s_andn2_b64 vcc, exec, s[90:91]
	s_cbranch_vccnz .LBB0_1136
	v_mul_f32_e32 v96, 0xbfb8aa3b, v102
	v_exp_f32_e32 v96, v96
	v_mul_f32_e32 v106, 0xbfb8aa3b, v103
	v_exp_f32_e32 v106, v106
	v_mul_f32_e32 v107, 0xbfb8aa3b, v105
	v_add_f32_e32 v96, 1.0, v96
	v_rcp_f32_e32 v108, v96
	v_mul_f32_e32 v96, 0xbfb8aa3b, v104
	v_exp_f32_e32 v96, v96
	v_exp_f32_e32 v107, v107
	v_add_f32_e32 v106, 1.0, v106
	v_rcp_f32_e32 v109, v106
	v_add_f32_e32 v96, 1.0, v96
	v_rcp_f32_e32 v112, v96
	v_add_f32_e32 v96, 1.0, v107
	v_lshl_add_u64 v[106:107], s[54:55], 0, v[124:125]
	v_rcp_f32_e32 v113, v96
	v_lshl_add_u64 v[106:107], s[56:57], 1, v[106:107]
	v_lshlrev_b32_e32 v96, 1, v142
	v_lshl_add_u64 v[106:107], v[106:107], 0, v[96:97]
	s_mov_b64 s[70:71], 0
	v_cvt_pk_bf16_f32 v190, v108, v109
	v_cvt_pk_bf16_f32 v191, v112, v113

; __device__ __forceinline__ float sigm(float x) { return __builtin_amdgcn_rcpf(1.f + __expf(-x)); }
; __device__ __forceinline__ void st_bf4(bf16_t* p, const f32x4 v) { u32x2 w; w.x = cvt_pk_bf16(v[0], v[1]); w.y = cvt_pk_bf16(v[2], v[3]); *(u32x2*)p = w; }
;     __device__ __forceinline__ void operator()(const f32x4 (&acc)[2][2][4][2], const Unit& u, int wr, int wc, int fr, int fq) const {
;     ...
;                         else { f32x4 s; s[0] = sigm(v[0]); s[1] = sigm(v[1]); s[2] = sigm(v[2]); s[3] = sigm(v[3]); st_bf4(GT + (size_t)row * 3072 + (pn - 7) * 256 + tc, s); }
.LBB0_1148:
	s_and_b64 vcc, exec, s[14:15]
	s_cbranch_vccnz .LBB0_1154
	s_andn2_b64 vcc, exec, s[90:91]
	s_cbranch_vccnz .LBB0_1151
	v_mul_f32_e32 v96, 0xbfb8aa3b, v98
	v_exp_f32_e32 v96, v96
	v_mul_f32_e32 v102, 0xbfb8aa3b, v99
	v_exp_f32_e32 v102, v102
	v_mul_f32_e32 v103, 0xbfb8aa3b, v101
	v_add_f32_e32 v96, 1.0, v96
	v_rcp_f32_e32 v104, v96
	v_mul_f32_e32 v96, 0xbfb8aa3b, v100
	v_exp_f32_e32 v96, v96
	v_exp_f32_e32 v103, v103
	v_add_f32_e32 v102, 1.0, v102
	v_rcp_f32_e32 v105, v102
	v_add_f32_e32 v96, 1.0, v96
	v_rcp_f32_e32 v106, v96
	v_add_f32_e32 v96, 1.0, v103
	v_lshl_add_u64 v[102:103], s[54:55], 0, v[124:125]
	v_rcp_f32_e32 v107, v96
	v_lshl_add_u64 v[102:103], s[56:57], 1, v[102:103]
	v_lshlrev_b32_e32 v96, 1, v142
	v_lshl_add_u64 v[102:103], v[102:103], 0, v[96:97]
	s_mov_b64 s[70:71], 0
	v_cvt_pk_bf16_f32 v192, v104, v105
	v_cvt_pk_bf16_f32 v193, v106, v107
	global_store_dwordx4 v[102:103], v[190:193], off offset:256

; __device__ __forceinline__ float sigm(float x) { return __builtin_amdgcn_rcpf(1.f + __expf(-x)); }
;     __device__ __forceinline__ void operator()(const f32x4 (&acc)[2][2][4][2], const Unit& u, int wr, int wc, int fr, int fq) const {
;     ...
;             for (int m = 0; m < 4; ++m) { const int row = u.pm * 256 + ai * 128 + wr * 64 + m * 16 + fr;
; #pragma unroll
;                 for (int bj = 0; bj < 2; ++bj)
; #pragma unroll
;                     for (int n = 0; n < 2; ++n) { const int tc = bj * 128 + wc * 32 + 8 * fq + 4 * n; f32x4 v = acc[ai][bj][m][n];
;                         if (pn < 2) { *(f32x4*)(XA + (size_t)row * 512 + pn * 256 + tc) = v; }
;                         else if (pn <= 4) {
;                             const bool isv = (pn == 4 && bj == 1);
;                             if (!isv && (wc & 1) == 0) {
;                                 const int tix = row < cfg::MP ? (row & 2047) : 2048 + (row & 3);
;                                 const f32x4 cs = *(const f32x4*)(ropec + tix * 8 + 4 * n), sn = *(const f32x4*)(ropes + tix * 8 + 4 * n);
; #pragma unroll
;                                 for (int i = 0; i < 4; ++i) { const float p = shx16(v[i], fq & 1); const float rv = v[i] * cs[i] + (fq == 0 ? -p : p) * sn[i]; v[i] = fq < 2 ? rv : v[i]; }
;                             }
;                             if (pn < 4) st_bf4(Q + (size_t)row * 512 + (pn - 2) * 256 + tc, v);
;                             else { st_bf4((bj == 0 ? KB : VB) + (size_t)row * 128 + (tc & 127), v);
;                                 bool w = false; size_t o = 0;
;                                 if (row < cfg::MP) { const int t = row & 2047; if (t >= 1920) { w = true; o = (bj == 0 ? cfg::OFF_KP : cfg::OFF_VP) + ((size_t)(layer * 8 + (row >> 11)) * 128 + (t - 1920)) * 128 + (tc & 127); } }
;                                 else { const int rs = row - cfg::MP; w = true; o = (bj == 0 ? cfg::OFF_KS : cfg::OFF_VS) + ((size_t)(layer * 128 + (rs >> 2)) * 128 + 124 + (rs & 3)) * 128 + (tc & 127); }
;                                 if (w) *(f32x4*)(out + o) = v; }
;                         }
;                         else if (pn < 7) { *(f32x4*)(U + (size_t)row * 512 + (pn - 5) * 256 + tc) = v; }
;                         else { f32x4 s; s[0] = sigm(v[0]); s[1] = sigm(v[1]); s[2] = sigm(v[2]); s[3] = sigm(v[3]); st_bf4(GT + (size_t)row * 3072 + (pn - 7) * 256 + tc, s); }
.LBB0_1166:
	s_nop 1
	v_or_b32_e32 v98, 32, v172
	v_mad_i64_i32 v[108:109], s[18:19], v98, s61, 0
	s_movk_i32 s18, 0x3fff
	s_nop 0
	v_cmp_lt_i32_e64 s[20:21], s18, v98
	s_movk_i32 s18, 0x7ef
	v_bitop3_b32 v96, v172, s18, 32 bitop3:0xc8
	s_movk_i32 s18, 0x4000
	v_cmp_gt_i32_e32 vcc, s18, v98
	s_movk_i32 s18, 0x77f
	v_cmp_lt_u32_e64 s[18:19], s18, v96
	v_cndmask_b32_e32 v100, v151, v96, vcc
	v_add_u32_e32 v96, 0xfffff880, v96
	v_ashrrev_i32_e32 v99, 31, v98
	v_lshlrev_b32_e32 v119, 3, v100
	v_add_u32_e32 v100, 0xffffc020, v172
	v_lshlrev_b64 v[110:111], 7, v[96:97]
	s_mov_b64 s[70:71], 0x1080000
	v_lshlrev_b64 v[106:107], 11, v[98:99]
	v_lshlrev_b64 v[104:105], 8, v[98:99]
	v_lshrrev_b32_e32 v118, 2, v100
	v_lshlrev_b64 v[102:103], 10, v[98:99]
	v_lshl_add_u64 v[112:113], v[110:111], 0, s[70:71]
	s_and_b64 vcc, exec, s[16:17]
	s_mov_b64 s[70:71], -1
	s_cbranch_vccnz .LBB0_1196
	s_and_b64 vcc, exec, s[14:15]
	s_cbranch_vccnz .LBB0_1173
	s_andn2_b64 vcc, exec, s[90:91]
	s_cbranch_vccnz .LBB0_1170
	v_mul_f32_e32 v96, 0xbfb8aa3b, v92
	v_exp_f32_e32 v96, v96
	v_mul_f32_e32 v98, 0xbfb8aa3b, v93
	v_exp_f32_e32 v98, v98
	v_mul_f32_e32 v99, 0xbfb8aa3b, v95
	v_add_f32_e32 v96, 1.0, v96
	v_rcp_f32_e32 v100, v96
	v_mul_f32_e32 v96, 0xbfb8aa3b, v94
	v_exp_f32_e32 v96, v96
	v_exp_f32_e32 v99, v99
	v_add_f32_e32 v98, 1.0, v98
	v_rcp_f32_e32 v101, v98
	v_add_f32_e32 v96, 1.0, v96
	v_rcp_f32_e32 v114, v96
	v_add_f32_e32 v96, 1.0, v99
	v_lshl_add_u64 v[98:99], s[54:55], 0, v[108:109]
	v_rcp_f32_e32 v115, v96
	v_lshl_add_u64 v[98:99], s[56:57], 1, v[98:99]
	v_lshlrev_b32_e32 v96, 1, v142
	v_lshl_add_u64 v[98:99], v[98:99], 0, v[96:97]
	s_mov_b64 s[70:71], 0
	v_cvt_pk_bf16_f32 v198, v100, v101
	v_cvt_pk_bf16_f32 v199, v114, v115

; __device__ __forceinline__ float sigm(float x) { return __builtin_amdgcn_rcpf(1.f + __expf(-x)); }
; __device__ __forceinline__ void st_bf4(bf16_t* p, const f32x4 v) { u32x2 w; w.x = cvt_pk_bf16(v[0], v[1]); w.y = cvt_pk_bf16(v[2], v[3]); *(u32x2*)p = w; }
;     __device__ __forceinline__ void operator()(const f32x4 (&acc)[2][2][4][2], const Unit& u, int wr, int wc, int fr, int fq) const {
;     ...
;                         else { f32x4 s; s[0] = sigm(v[0]); s[1] = sigm(v[1]); s[2] = sigm(v[2]); s[3] = sigm(v[3]); st_bf4(GT + (size_t)row * 3072 + (pn - 7) * 256 + tc, s); }
.LBB0_1182:
	s_and_b64 vcc, exec, s[14:15]
	s_cbranch_vccnz .LBB0_1188
	s_andn2_b64 vcc, exec, s[90:91]
	s_cbranch_vccnz .LBB0_1185
	v_mul_f32_e32 v92, 0xbfb8aa3b, v88
	v_exp_f32_e32 v92, v92
	v_mul_f32_e32 v93, 0xbfb8aa3b, v89
	v_mul_f32_e32 v95, 0xbfb8aa3b, v91
	v_exp_f32_e32 v93, v93
	v_add_f32_e32 v92, 1.0, v92
	v_rcp_f32_e32 v94, v92
	v_mul_f32_e32 v92, 0xbfb8aa3b, v90
	v_exp_f32_e32 v92, v92
	v_exp_f32_e32 v95, v95
	v_add_f32_e32 v93, 1.0, v93
	v_rcp_f32_e32 v100, v93
	v_add_f32_e32 v92, 1.0, v92
	v_rcp_f32_e32 v101, v92
	v_add_f32_e32 v92, 1.0, v95
	v_rcp_f32_e32 v95, v92
	v_lshl_add_u64 v[92:93], s[54:55], 0, v[108:109]
	v_lshl_add_u64 v[92:93], s[56:57], 1, v[92:93]
	v_lshlrev_b32_e32 v96, 1, v142
	v_lshl_add_u64 v[92:93], v[92:93], 0, v[96:97]
	s_mov_b64 s[70:71], 0
	v_cvt_pk_bf16_f32 v200, v94, v100
	v_cvt_pk_bf16_f32 v201, v101, v95
	global_store_dwordx4 v[92:93], v[198:201], off

; __device__ __forceinline__ float sigm(float x) { return __builtin_amdgcn_rcpf(1.f + __expf(-x)); }
; __device__ __forceinline__ void st_bf4(bf16_t* p, const f32x4 v) { u32x2 w; w.x = cvt_pk_bf16(v[0], v[1]); w.y = cvt_pk_bf16(v[2], v[3]); *(u32x2*)p = w; }
;     __device__ __forceinline__ void operator()(const f32x4 (&acc)[2][2][4][2], const Unit& u, int wr, int wc, int fr, int fq) const {
;     ...
;                         else { f32x4 s; s[0] = sigm(v[0]); s[1] = sigm(v[1]); s[2] = sigm(v[2]); s[3] = sigm(v[3]); st_bf4(GT + (size_t)row * 3072 + (pn - 7) * 256 + tc, s); }
.LBB0_1200:
	s_mov_b64 s[70:71], 0x1100000
	v_lshl_add_u64 v[92:93], v[110:111], 0, s[70:71]
	s_and_b64 vcc, exec, s[16:17]
	s_mov_b64 s[70:71], -1
	s_cbranch_vccnz .LBB0_1230
	s_and_b64 vcc, exec, s[14:15]
	s_cbranch_vccnz .LBB0_1207
	s_andn2_b64 vcc, exec, s[90:91]
	s_cbranch_vccnz .LBB0_1204
	v_mul_f32_e32 v88, 0xbfb8aa3b, v84
	v_exp_f32_e32 v88, v88
	v_mul_f32_e32 v89, 0xbfb8aa3b, v85
	v_mul_f32_e32 v91, 0xbfb8aa3b, v87
	v_exp_f32_e32 v89, v89
	v_add_f32_e32 v88, 1.0, v88
	v_rcp_f32_e32 v90, v88
	v_mul_f32_e32 v88, 0xbfb8aa3b, v86
	v_exp_f32_e32 v88, v88
	v_exp_f32_e32 v91, v91
	v_add_f32_e32 v89, 1.0, v89
	v_rcp_f32_e32 v94, v89
	v_add_f32_e32 v88, 1.0, v88
	v_rcp_f32_e32 v95, v88
	v_add_f32_e32 v88, 1.0, v91
	v_rcp_f32_e32 v91, v88
	v_lshl_add_u64 v[88:89], s[54:55], 0, v[108:109]
	v_lshl_add_u64 v[88:89], s[56:57], 1, v[88:89]
	v_lshlrev_b32_e32 v96, 1, v142
	v_lshl_add_u64 v[88:89], v[88:89], 0, v[96:97]
	s_mov_b64 s[70:71], 0
	v_cvt_pk_bf16_f32 v250, v90, v94
	v_cvt_pk_bf16_f32 v251, v95, v91

; __device__ __forceinline__ float sigm(float x) { return __builtin_amdgcn_rcpf(1.f + __expf(-x)); }
; __device__ __forceinline__ void st_bf4(bf16_t* p, const f32x4 v) { u32x2 w; w.x = cvt_pk_bf16(v[0], v[1]); w.y = cvt_pk_bf16(v[2], v[3]); *(u32x2*)p = w; }
;     __device__ __forceinline__ void operator()(const f32x4 (&acc)[2][2][4][2], const Unit& u, int wr, int wc, int fr, int fq) const {
;     ...
;                         else { f32x4 s; s[0] = sigm(v[0]); s[1] = sigm(v[1]); s[2] = sigm(v[2]); s[3] = sigm(v[3]); st_bf4(GT + (size_t)row * 3072 + (pn - 7) * 256 + tc, s); }
.LBB0_1216:
	s_and_b64 vcc, exec, s[14:15]
	s_cbranch_vccnz .LBB0_1222
	s_andn2_b64 vcc, exec, s[90:91]
	s_cbranch_vccnz .LBB0_1219
	v_mul_f32_e32 v84, 0xbfb8aa3b, v80
	v_exp_f32_e32 v84, v84
	v_mul_f32_e32 v85, 0xbfb8aa3b, v81
	v_mul_f32_e32 v87, 0xbfb8aa3b, v83
	v_exp_f32_e32 v85, v85
	v_add_f32_e32 v84, 1.0, v84
	v_rcp_f32_e32 v86, v84
	v_mul_f32_e32 v84, 0xbfb8aa3b, v82
	v_exp_f32_e32 v84, v84
	v_exp_f32_e32 v87, v87
	v_add_f32_e32 v85, 1.0, v85
	v_rcp_f32_e32 v88, v85
	v_add_f32_e32 v84, 1.0, v84
	v_rcp_f32_e32 v89, v84
	v_add_f32_e32 v84, 1.0, v87
	v_rcp_f32_e32 v87, v84
	v_lshl_add_u64 v[84:85], s[54:55], 0, v[108:109]
	v_lshl_add_u64 v[84:85], s[56:57], 1, v[84:85]
	v_lshlrev_b32_e32 v96, 1, v142
	v_lshl_add_u64 v[84:85], v[84:85], 0, v[96:97]
	s_mov_b64 s[70:71], 0
	v_cvt_pk_bf16_f32 v252, v86, v88
	v_cvt_pk_bf16_f32 v253, v89, v87
	global_store_dwordx4 v[84:85], v[250:253], off offset:256

; __device__ __forceinline__ float sigm(float x) { return __builtin_amdgcn_rcpf(1.f + __expf(-x)); }
;     __device__ __forceinline__ void operator()(const f32x4 (&acc)[2][2][4][2], const Unit& u, int wr, int wc, int fr, int fq) const {
;     ...
;             for (int m = 0; m < 4; ++m) { const int row = u.pm * 256 + ai * 128 + wr * 64 + m * 16 + fr;
; #pragma unroll
;                 for (int bj = 0; bj < 2; ++bj)
; #pragma unroll
;                     for (int n = 0; n < 2; ++n) { const int tc = bj * 128 + wc * 32 + 8 * fq + 4 * n; f32x4 v = acc[ai][bj][m][n];
;                         if (pn < 2) { *(f32x4*)(XA + (size_t)row * 512 + pn * 256 + tc) = v; }
;                         else if (pn <= 4) {
;                             const bool isv = (pn == 4 && bj == 1);
;                             if (!isv && (wc & 1) == 0) {
;                                 const int tix = row < cfg::MP ? (row & 2047) : 2048 + (row & 3);
;                                 const f32x4 cs = *(const f32x4*)(ropec + tix * 8 + 4 * n), sn = *(const f32x4*)(ropes + tix * 8 + 4 * n);
; #pragma unroll
;                                 for (int i = 0; i < 4; ++i) { const float p = shx16(v[i], fq & 1); const float rv = v[i] * cs[i] + (fq == 0 ? -p : p) * sn[i]; v[i] = fq < 2 ? rv : v[i]; }
;                             }
;                             if (pn < 4) st_bf4(Q + (size_t)row * 512 + (pn - 2) * 256 + tc, v);
;                             else { st_bf4((bj == 0 ? KB : VB) + (size_t)row * 128 + (tc & 127), v);
;                                 bool w = false; size_t o = 0;
;                                 if (row < cfg::MP) { const int t = row & 2047; if (t >= 1920) { w = true; o = (bj == 0 ? cfg::OFF_KP : cfg::OFF_VP) + ((size_t)(layer * 8 + (row >> 11)) * 128 + (t - 1920)) * 128 + (tc & 127); } }
;                                 else { const int rs = row - cfg::MP; w = true; o = (bj == 0 ? cfg::OFF_KS : cfg::OFF_VS) + ((size_t)(layer * 128 + (rs >> 2)) * 128 + 124 + (rs & 3)) * 128 + (tc & 127); }
;                                 if (w) *(f32x4*)(out + o) = v; }
;                         }
;                         else if (pn < 7) { *(f32x4*)(U + (size_t)row * 512 + (pn - 5) * 256 + tc) = v; }
;                         else { f32x4 s; s[0] = sigm(v[0]); s[1] = sigm(v[1]); s[2] = sigm(v[2]); s[3] = sigm(v[3]); st_bf4(GT + (size_t)row * 3072 + (pn - 7) * 256 + tc, s); }
.LBB0_1234:
	s_nop 1
	v_or_b32_e32 v80, 48, v172
	v_mad_i64_i32 v[90:91], s[18:19], v80, s61, 0
	s_movk_i32 s18, 0x3fff
	s_nop 0
	v_cmp_lt_i32_e64 s[20:21], s18, v80
	s_movk_i32 s18, 0x7ff
	v_bitop3_b32 v82, v172, s18, 48 bitop3:0xc8
	s_movk_i32 s18, 0x4000
	v_cmp_gt_i32_e32 vcc, s18, v80
	v_add_u32_e32 v96, 0xfffff880, v82
	v_ashrrev_i32_e32 v81, 31, v80
	v_cndmask_b32_e32 v83, v151, v82, vcc
	v_lshlrev_b32_e32 v103, 3, v83
	v_add_u32_e32 v83, 0xffffc030, v172
	s_movk_i32 s18, 0x77f
	v_lshlrev_b64 v[92:93], 7, v[96:97]
	s_mov_b64 s[70:71], 0x1080000
	v_lshlrev_b64 v[88:89], 11, v[80:81]
	v_lshlrev_b64 v[86:87], 8, v[80:81]
	v_lshrrev_b32_e32 v102, 2, v83
	v_cmp_lt_u32_e64 s[18:19], s18, v82
	v_lshlrev_b64 v[84:85], 10, v[80:81]
	v_lshl_add_u64 v[94:95], v[92:93], 0, s[70:71]
	s_and_b64 vcc, exec, s[16:17]
	s_mov_b64 s[70:71], -1
	s_cbranch_vccnz .LBB0_1264
	s_and_b64 vcc, exec, s[14:15]
	s_cbranch_vccnz .LBB0_1241
	s_andn2_b64 vcc, exec, s[90:91]
	s_cbranch_vccnz .LBB0_1238
	v_mul_f32_e32 v80, 0xbfb8aa3b, v76
	v_exp_f32_e32 v80, v80
	v_mul_f32_e32 v81, 0xbfb8aa3b, v77
	v_mul_f32_e32 v83, 0xbfb8aa3b, v79
	v_exp_f32_e32 v81, v81
	v_add_f32_e32 v80, 1.0, v80
	v_rcp_f32_e32 v82, v80
	v_mul_f32_e32 v80, 0xbfb8aa3b, v78
	v_exp_f32_e32 v80, v80
	v_exp_f32_e32 v83, v83
	v_add_f32_e32 v81, 1.0, v81
	v_rcp_f32_e32 v98, v81
	v_add_f32_e32 v80, 1.0, v80
	v_rcp_f32_e32 v99, v80
	v_add_f32_e32 v80, 1.0, v83
	v_rcp_f32_e32 v83, v80
	v_lshl_add_u64 v[80:81], s[54:55], 0, v[90:91]
	v_lshl_add_u64 v[80:81], s[56:57], 1, v[80:81]
	v_lshlrev_b32_e32 v96, 1, v142
	v_lshl_add_u64 v[80:81], v[80:81], 0, v[96:97]
	s_mov_b64 s[70:71], 0
	v_cvt_pk_bf16_f32 v190, v82, v98
	v_cvt_pk_bf16_f32 v191, v99, v83

; __device__ __forceinline__ float sigm(float x) { return __builtin_amdgcn_rcpf(1.f + __expf(-x)); }
; __device__ __forceinline__ void st_bf4(bf16_t* p, const f32x4 v) { u32x2 w; w.x = cvt_pk_bf16(v[0], v[1]); w.y = cvt_pk_bf16(v[2], v[3]); *(u32x2*)p = w; }
;     __device__ __forceinline__ void operator()(const f32x4 (&acc)[2][2][4][2], const Unit& u, int wr, int wc, int fr, int fq) const {
;     ...
;                         else { f32x4 s; s[0] = sigm(v[0]); s[1] = sigm(v[1]); s[2] = sigm(v[2]); s[3] = sigm(v[3]); st_bf4(GT + (size_t)row * 3072 + (pn - 7) * 256 + tc, s); }
.LBB0_1250:
	s_and_b64 vcc, exec, s[14:15]
	s_cbranch_vccnz .LBB0_1256
	s_andn2_b64 vcc, exec, s[90:91]
	s_cbranch_vccnz .LBB0_1253
	v_mul_f32_e32 v76, 0xbfb8aa3b, v72
	v_exp_f32_e32 v76, v76
	v_mul_f32_e32 v77, 0xbfb8aa3b, v73
	v_mul_f32_e32 v79, 0xbfb8aa3b, v75
	v_exp_f32_e32 v77, v77
	v_add_f32_e32 v76, 1.0, v76
	v_rcp_f32_e32 v78, v76
	v_mul_f32_e32 v76, 0xbfb8aa3b, v74
	v_exp_f32_e32 v76, v76
	v_exp_f32_e32 v79, v79
	v_add_f32_e32 v77, 1.0, v77
	v_rcp_f32_e32 v82, v77
	v_add_f32_e32 v76, 1.0, v76
	v_rcp_f32_e32 v83, v76
	v_add_f32_e32 v76, 1.0, v79
	v_rcp_f32_e32 v79, v76
	v_lshl_add_u64 v[76:77], s[54:55], 0, v[90:91]
	v_lshl_add_u64 v[76:77], s[56:57], 1, v[76:77]
	v_lshlrev_b32_e32 v96, 1, v142
	v_lshl_add_u64 v[76:77], v[76:77], 0, v[96:97]
	s_mov_b64 s[70:71], 0
	v_cvt_pk_bf16_f32 v192, v78, v82
	v_cvt_pk_bf16_f32 v193, v83, v79
	global_store_dwordx4 v[76:77], v[190:193], off

; __device__ __forceinline__ float sigm(float x) { return __builtin_amdgcn_rcpf(1.f + __expf(-x)); }
; __device__ __forceinline__ void st_bf4(bf16_t* p, const f32x4 v) { u32x2 w; w.x = cvt_pk_bf16(v[0], v[1]); w.y = cvt_pk_bf16(v[2], v[3]); *(u32x2*)p = w; }
;     __device__ __forceinline__ void operator()(const f32x4 (&acc)[2][2][4][2], const Unit& u, int wr, int wc, int fr, int fq) const {
;     ...
;                         else { f32x4 s; s[0] = sigm(v[0]); s[1] = sigm(v[1]); s[2] = sigm(v[2]); s[3] = sigm(v[3]); st_bf4(GT + (size_t)row * 3072 + (pn - 7) * 256 + tc, s); }
.LBB0_1268:
	s_mov_b64 s[70:71], 0x1100000
	v_lshl_add_u64 v[76:77], v[92:93], 0, s[70:71]
	s_and_b64 vcc, exec, s[16:17]
	s_mov_b64 s[70:71], -1
	s_cbranch_vccnz .LBB0_1298
	s_and_b64 vcc, exec, s[14:15]
	s_cbranch_vccnz .LBB0_1275
	s_andn2_b64 vcc, exec, s[90:91]
	s_cbranch_vccnz .LBB0_1272
	v_mul_f32_e32 v72, 0xbfb8aa3b, v68
	v_exp_f32_e32 v72, v72
	v_mul_f32_e32 v73, 0xbfb8aa3b, v69
	v_mul_f32_e32 v75, 0xbfb8aa3b, v71
	v_exp_f32_e32 v73, v73
	v_add_f32_e32 v72, 1.0, v72
	v_rcp_f32_e32 v74, v72
	v_mul_f32_e32 v72, 0xbfb8aa3b, v70
	v_exp_f32_e32 v72, v72
	v_exp_f32_e32 v75, v75
	v_add_f32_e32 v73, 1.0, v73
	v_rcp_f32_e32 v78, v73
	v_add_f32_e32 v72, 1.0, v72
	v_rcp_f32_e32 v79, v72
	v_add_f32_e32 v72, 1.0, v75
	v_rcp_f32_e32 v75, v72
	v_lshl_add_u64 v[72:73], s[54:55], 0, v[90:91]
	v_lshl_add_u64 v[72:73], s[56:57], 1, v[72:73]
	v_lshlrev_b32_e32 v96, 1, v142
	v_lshl_add_u64 v[72:73], v[72:73], 0, v[96:97]
	s_mov_b64 s[70:71], 0
	v_cvt_pk_bf16_f32 v198, v74, v78
	v_cvt_pk_bf16_f32 v199, v79, v75

; __device__ __forceinline__ float sigm(float x) { return __builtin_amdgcn_rcpf(1.f + __expf(-x)); }
; __device__ __forceinline__ void st_bf4(bf16_t* p, const f32x4 v) { u32x2 w; w.x = cvt_pk_bf16(v[0], v[1]); w.y = cvt_pk_bf16(v[2], v[3]); *(u32x2*)p = w; }
;     __device__ __forceinline__ void operator()(const f32x4 (&acc)[2][2][4][2], const Unit& u, int wr, int wc, int fr, int fq) const {
;     ...
;                         else { f32x4 s; s[0] = sigm(v[0]); s[1] = sigm(v[1]); s[2] = sigm(v[2]); s[3] = sigm(v[3]); st_bf4(GT + (size_t)row * 3072 + (pn - 7) * 256 + tc, s); }
.LBB0_1284:
	s_and_b64 vcc, exec, s[14:15]
	s_cbranch_vccnz .LBB0_1290
	s_andn2_b64 vcc, exec, s[90:91]
	s_cbranch_vccnz .LBB0_1287
	v_mul_f32_e32 v68, 0xbfb8aa3b, v64
	v_exp_f32_e32 v68, v68
	v_mul_f32_e32 v69, 0xbfb8aa3b, v65
	v_mul_f32_e32 v71, 0xbfb8aa3b, v67
	v_exp_f32_e32 v69, v69
	v_add_f32_e32 v68, 1.0, v68
	v_rcp_f32_e32 v70, v68
	v_mul_f32_e32 v68, 0xbfb8aa3b, v66
	v_exp_f32_e32 v68, v68
	v_exp_f32_e32 v71, v71
	v_add_f32_e32 v69, 1.0, v69
	v_rcp_f32_e32 v72, v69
	v_add_f32_e32 v68, 1.0, v68
	v_rcp_f32_e32 v73, v68
	v_add_f32_e32 v68, 1.0, v71
	v_rcp_f32_e32 v71, v68
	v_lshl_add_u64 v[68:69], s[54:55], 0, v[90:91]
	v_lshl_add_u64 v[68:69], s[56:57], 1, v[68:69]
	v_lshlrev_b32_e32 v96, 1, v142
	v_lshl_add_u64 v[68:69], v[68:69], 0, v[96:97]
	s_mov_b64 s[70:71], 0
	v_cvt_pk_bf16_f32 v200, v70, v72
	v_cvt_pk_bf16_f32 v201, v73, v71
	global_store_dwordx4 v[68:69], v[198:201], off offset:256

; __device__ __forceinline__ float sigm(float x) { return __builtin_amdgcn_rcpf(1.f + __expf(-x)); }
;     __device__ __forceinline__ void operator()(const f32x4 (&acc)[2][2][4][2], const Unit& u, int wr, int wc, int fr, int fq) const {
;     ...
;             for (int m = 0; m < 4; ++m) { const int row = u.pm * 256 + ai * 128 + wr * 64 + m * 16 + fr;
; #pragma unroll
;                 for (int bj = 0; bj < 2; ++bj)
; #pragma unroll
;                     for (int n = 0; n < 2; ++n) { const int tc = bj * 128 + wc * 32 + 8 * fq + 4 * n; f32x4 v = acc[ai][bj][m][n];
;                         if (pn < 2) { *(f32x4*)(XA + (size_t)row * 512 + pn * 256 + tc) = v; }
;                         else if (pn <= 4) {
;                             const bool isv = (pn == 4 && bj == 1);
;                             if (!isv && (wc & 1) == 0) {
;                                 const int tix = row < cfg::MP ? (row & 2047) : 2048 + (row & 3);
;                                 const f32x4 cs = *(const f32x4*)(ropec + tix * 8 + 4 * n), sn = *(const f32x4*)(ropes + tix * 8 + 4 * n);
; #pragma unroll
;                                 for (int i = 0; i < 4; ++i) { const float p = shx16(v[i], fq & 1); const float rv = v[i] * cs[i] + (fq == 0 ? -p : p) * sn[i]; v[i] = fq < 2 ? rv : v[i]; }
;                             }
;                             if (pn < 4) st_bf4(Q + (size_t)row * 512 + (pn - 2) * 256 + tc, v);
;                             else { st_bf4((bj == 0 ? KB : VB) + (size_t)row * 128 + (tc & 127), v);
;                                 bool w = false; size_t o = 0;
;                                 if (row < cfg::MP) { const int t = row & 2047; if (t >= 1920) { w = true; o = (bj == 0 ? cfg::OFF_KP : cfg::OFF_VP) + ((size_t)(layer * 8 + (row >> 11)) * 128 + (t - 1920)) * 128 + (tc & 127); } }
;                                 else { const int rs = row - cfg::MP; w = true; o = (bj == 0 ? cfg::OFF_KS : cfg::OFF_VS) + ((size_t)(layer * 128 + (rs >> 2)) * 128 + 124 + (rs & 3)) * 128 + (tc & 127); }
;                                 if (w) *(f32x4*)(out + o) = v; }
;                         }
;                         else if (pn < 7) { *(f32x4*)(U + (size_t)row * 512 + (pn - 5) * 256 + tc) = v; }
;                         else { f32x4 s; s[0] = sigm(v[0]); s[1] = sigm(v[1]); s[2] = sigm(v[2]); s[3] = sigm(v[3]); st_bf4(GT + (size_t)row * 3072 + (pn - 7) * 256 + tc, s); }
.LBB0_1302:
	s_add_i32 s46, s53, 0x80
	v_or_b32_e32 v68, s46, v143
	v_mad_i64_i32 v[76:77], s[18:19], v68, s61, 0
	s_movk_i32 s18, 0x3fff
	s_nop 0
	v_cmp_lt_i32_e64 s[20:21], s18, v68
	v_mov_b32_e32 v64, 0x7cf
	s_movk_i32 s18, 0x4000
	v_bitop3_b32 v64, s46, v64, v143 bitop3:0xc8
	v_cmp_gt_i32_e32 vcc, s18, v68
	v_add_u32_e32 v96, 0xfffff880, v64
	v_ashrrev_i32_e32 v69, 31, v68
	v_cndmask_b32_e32 v65, v151, v64, vcc
	v_lshlrev_b32_e32 v87, 3, v65
	v_add_u32_e32 v65, 0xffffc000, v68
	s_movk_i32 s18, 0x77f
	v_lshlrev_b64 v[78:79], 7, v[96:97]
	s_mov_b64 s[70:71], 0x1080000
	s_ashr_i32 s53, s46, 11
	v_lshlrev_b64 v[74:75], 11, v[68:69]
	v_lshlrev_b64 v[72:73], 8, v[68:69]
	v_lshrrev_b32_e32 v86, 2, v65
	v_cmp_lt_u32_e64 s[18:19], s18, v64
	v_lshlrev_b64 v[70:71], 10, v[68:69]
	v_lshl_add_u64 v[80:81], v[78:79], 0, s[70:71]
	s_and_b64 vcc, exec, s[16:17]
	s_mov_b64 s[70:71], -1
	s_mov_b32 s75, 0x400000
	s_cbranch_vccnz .LBB0_1332
	s_and_b64 vcc, exec, s[14:15]
	s_cbranch_vccnz .LBB0_1309
	s_andn2_b64 vcc, exec, s[90:91]
	s_cbranch_vccnz .LBB0_1306
	v_mul_f32_e32 v64, 0xbfb8aa3b, v60
	v_exp_f32_e32 v64, v64
	v_mul_f32_e32 v65, 0xbfb8aa3b, v61
	v_mul_f32_e32 v67, 0xbfb8aa3b, v63
	v_exp_f32_e32 v65, v65
	v_add_f32_e32 v64, 1.0, v64
	v_rcp_f32_e32 v66, v64
	v_mul_f32_e32 v64, 0xbfb8aa3b, v62
	v_exp_f32_e32 v64, v64
	v_exp_f32_e32 v67, v67
	v_add_f32_e32 v65, 1.0, v65
	v_rcp_f32_e32 v69, v65
	v_add_f32_e32 v64, 1.0, v64
	v_rcp_f32_e32 v82, v64
	v_add_f32_e32 v64, 1.0, v67
	v_rcp_f32_e32 v67, v64
	v_lshl_add_u64 v[64:65], s[54:55], 0, v[76:77]
	v_lshl_add_u64 v[64:65], s[56:57], 1, v[64:65]
	v_lshlrev_b32_e32 v96, 1, v142
	v_lshl_add_u64 v[64:65], v[64:65], 0, v[96:97]
	s_mov_b64 s[70:71], 0
	v_cvt_pk_bf16_f32 v250, v66, v69
	v_cvt_pk_bf16_f32 v251, v82, v67

; __device__ __forceinline__ float sigm(float x) { return __builtin_amdgcn_rcpf(1.f + __expf(-x)); }
; __device__ __forceinline__ void st_bf4(bf16_t* p, const f32x4 v) { u32x2 w; w.x = cvt_pk_bf16(v[0], v[1]); w.y = cvt_pk_bf16(v[2], v[3]); *(u32x2*)p = w; }
;     __device__ __forceinline__ void operator()(const f32x4 (&acc)[2][2][4][2], const Unit& u, int wr, int wc, int fr, int fq) const {
;     ...
;                         else { f32x4 s; s[0] = sigm(v[0]); s[1] = sigm(v[1]); s[2] = sigm(v[2]); s[3] = sigm(v[3]); st_bf4(GT + (size_t)row * 3072 + (pn - 7) * 256 + tc, s); }
.LBB0_1318:
	s_and_b64 vcc, exec, s[14:15]
	s_cbranch_vccnz .LBB0_1324
	s_andn2_b64 vcc, exec, s[90:91]
	s_cbranch_vccnz .LBB0_1321
	v_mul_f32_e32 v60, 0xbfb8aa3b, v56
	v_exp_f32_e32 v60, v60
	v_mul_f32_e32 v61, 0xbfb8aa3b, v57
	v_mul_f32_e32 v63, 0xbfb8aa3b, v59
	v_exp_f32_e32 v61, v61
	v_add_f32_e32 v60, 1.0, v60
	v_rcp_f32_e32 v62, v60
	v_mul_f32_e32 v60, 0xbfb8aa3b, v58
	v_exp_f32_e32 v60, v60
	v_exp_f32_e32 v63, v63
	v_add_f32_e32 v61, 1.0, v61
	v_rcp_f32_e32 v66, v61
	v_add_f32_e32 v60, 1.0, v60
	v_rcp_f32_e32 v67, v60
	v_add_f32_e32 v60, 1.0, v63
	v_rcp_f32_e32 v63, v60
	v_lshl_add_u64 v[60:61], s[54:55], 0, v[76:77]
	v_lshl_add_u64 v[60:61], s[56:57], 1, v[60:61]
	v_lshlrev_b32_e32 v96, 1, v142
	v_lshl_add_u64 v[60:61], v[60:61], 0, v[96:97]
	s_mov_b64 s[70:71], 0
	v_cvt_pk_bf16_f32 v252, v62, v66
	v_cvt_pk_bf16_f32 v253, v67, v63
	global_store_dwordx4 v[60:61], v[250:253], off

; __device__ __forceinline__ float sigm(float x) { return __builtin_amdgcn_rcpf(1.f + __expf(-x)); }
; __device__ __forceinline__ void st_bf4(bf16_t* p, const f32x4 v) { u32x2 w; w.x = cvt_pk_bf16(v[0], v[1]); w.y = cvt_pk_bf16(v[2], v[3]); *(u32x2*)p = w; }
;     __device__ __forceinline__ void operator()(const f32x4 (&acc)[2][2][4][2], const Unit& u, int wr, int wc, int fr, int fq) const {
;     ...
;                         else { f32x4 s; s[0] = sigm(v[0]); s[1] = sigm(v[1]); s[2] = sigm(v[2]); s[3] = sigm(v[3]); st_bf4(GT + (size_t)row * 3072 + (pn - 7) * 256 + tc, s); }
.LBB0_1336:
	s_mov_b64 s[70:71], 0x1100000
	v_lshl_add_u64 v[60:61], v[78:79], 0, s[70:71]
	s_and_b64 vcc, exec, s[16:17]
	s_mov_b64 s[70:71], -1
	s_cbranch_vccnz .LBB0_1366
	s_and_b64 vcc, exec, s[14:15]
	s_cbranch_vccnz .LBB0_1343
	s_andn2_b64 vcc, exec, s[90:91]
	s_cbranch_vccnz .LBB0_1340
	v_mul_f32_e32 v56, 0xbfb8aa3b, v52
	v_exp_f32_e32 v56, v56
	v_mul_f32_e32 v57, 0xbfb8aa3b, v53
	v_mul_f32_e32 v59, 0xbfb8aa3b, v55
	v_exp_f32_e32 v57, v57
	v_add_f32_e32 v56, 1.0, v56
	v_rcp_f32_e32 v58, v56
	v_mul_f32_e32 v56, 0xbfb8aa3b, v54
	v_exp_f32_e32 v56, v56
	v_exp_f32_e32 v59, v59
	v_add_f32_e32 v57, 1.0, v57
	v_rcp_f32_e32 v62, v57
	v_add_f32_e32 v56, 1.0, v56
	v_rcp_f32_e32 v63, v56
	v_add_f32_e32 v56, 1.0, v59
	v_rcp_f32_e32 v59, v56
	v_lshl_add_u64 v[56:57], s[54:55], 0, v[76:77]
	v_lshl_add_u64 v[56:57], s[56:57], 1, v[56:57]
	v_lshlrev_b32_e32 v96, 1, v142
	v_lshl_add_u64 v[56:57], v[56:57], 0, v[96:97]
	s_mov_b64 s[70:71], 0
	v_cvt_pk_bf16_f32 v190, v58, v62
	v_cvt_pk_bf16_f32 v191, v63, v59

; __device__ __forceinline__ float sigm(float x) { return __builtin_amdgcn_rcpf(1.f + __expf(-x)); }
; __device__ __forceinline__ void st_bf4(bf16_t* p, const f32x4 v) { u32x2 w; w.x = cvt_pk_bf16(v[0], v[1]); w.y = cvt_pk_bf16(v[2], v[3]); *(u32x2*)p = w; }
;     __device__ __forceinline__ void operator()(const f32x4 (&acc)[2][2][4][2], const Unit& u, int wr, int wc, int fr, int fq) const {
;     ...
;                         else { f32x4 s; s[0] = sigm(v[0]); s[1] = sigm(v[1]); s[2] = sigm(v[2]); s[3] = sigm(v[3]); st_bf4(GT + (size_t)row * 3072 + (pn - 7) * 256 + tc, s); }
.LBB0_1352:
	s_and_b64 vcc, exec, s[14:15]
	s_cbranch_vccnz .LBB0_1358
	s_andn2_b64 vcc, exec, s[90:91]
	s_cbranch_vccnz .LBB0_1355
	v_mul_f32_e32 v52, 0xbfb8aa3b, v48
	v_exp_f32_e32 v52, v52
	v_mul_f32_e32 v53, 0xbfb8aa3b, v49
	v_mul_f32_e32 v55, 0xbfb8aa3b, v51
	v_exp_f32_e32 v53, v53
	v_add_f32_e32 v52, 1.0, v52
	v_rcp_f32_e32 v54, v52
	v_mul_f32_e32 v52, 0xbfb8aa3b, v50
	v_exp_f32_e32 v52, v52
	v_exp_f32_e32 v55, v55
	v_add_f32_e32 v53, 1.0, v53
	v_rcp_f32_e32 v56, v53
	v_add_f32_e32 v52, 1.0, v52
	v_rcp_f32_e32 v57, v52
	v_add_f32_e32 v52, 1.0, v55
	v_rcp_f32_e32 v55, v52
	v_lshl_add_u64 v[52:53], s[54:55], 0, v[76:77]
	v_lshl_add_u64 v[52:53], s[56:57], 1, v[52:53]
	v_lshlrev_b32_e32 v96, 1, v142
	v_lshl_add_u64 v[52:53], v[52:53], 0, v[96:97]
	s_mov_b64 s[70:71], 0
	v_cvt_pk_bf16_f32 v192, v54, v56
	v_cvt_pk_bf16_f32 v193, v57, v55
	global_store_dwordx4 v[52:53], v[190:193], off offset:256

; __device__ __forceinline__ float sigm(float x) { return __builtin_amdgcn_rcpf(1.f + __expf(-x)); }
;     __device__ __forceinline__ void operator()(const f32x4 (&acc)[2][2][4][2], const Unit& u, int wr, int wc, int fr, int fq) const {
;     ...
;             for (int m = 0; m < 4; ++m) { const int row = u.pm * 256 + ai * 128 + wr * 64 + m * 16 + fr;
; #pragma unroll
;                 for (int bj = 0; bj < 2; ++bj)
; #pragma unroll
;                     for (int n = 0; n < 2; ++n) { const int tc = bj * 128 + wc * 32 + 8 * fq + 4 * n; f32x4 v = acc[ai][bj][m][n];
;                         if (pn < 2) { *(f32x4*)(XA + (size_t)row * 512 + pn * 256 + tc) = v; }
;                         else if (pn <= 4) {
;                             const bool isv = (pn == 4 && bj == 1);
;                             if (!isv && (wc & 1) == 0) {
;                                 const int tix = row < cfg::MP ? (row & 2047) : 2048 + (row & 3);
;                                 const f32x4 cs = *(const f32x4*)(ropec + tix * 8 + 4 * n), sn = *(const f32x4*)(ropes + tix * 8 + 4 * n);
; #pragma unroll
;                                 for (int i = 0; i < 4; ++i) { const float p = shx16(v[i], fq & 1); const float rv = v[i] * cs[i] + (fq == 0 ? -p : p) * sn[i]; v[i] = fq < 2 ? rv : v[i]; }
;                             }
;                             if (pn < 4) st_bf4(Q + (size_t)row * 512 + (pn - 2) * 256 + tc, v);
;                             else { st_bf4((bj == 0 ? KB : VB) + (size_t)row * 128 + (tc & 127), v);
;                                 bool w = false; size_t o = 0;
;                                 if (row < cfg::MP) { const int t = row & 2047; if (t >= 1920) { w = true; o = (bj == 0 ? cfg::OFF_KP : cfg::OFF_VP) + ((size_t)(layer * 8 + (row >> 11)) * 128 + (t - 1920)) * 128 + (tc & 127); } }
;                                 else { const int rs = row - cfg::MP; w = true; o = (bj == 0 ? cfg::OFF_KS : cfg::OFF_VS) + ((size_t)(layer * 128 + (rs >> 2)) * 128 + 124 + (rs & 3)) * 128 + (tc & 127); }
;                                 if (w) *(f32x4*)(out + o) = v; }
;                         }
;                         else if (pn < 7) { *(f32x4*)(U + (size_t)row * 512 + (pn - 5) * 256 + tc) = v; }
;                         else { f32x4 s; s[0] = sigm(v[0]); s[1] = sigm(v[1]); s[2] = sigm(v[2]); s[3] = sigm(v[3]); st_bf4(GT + (size_t)row * 3072 + (pn - 7) * 256 + tc, s); }
.LBB0_1370:
	s_nop 1
	v_or_b32_e32 v48, 16, v68
	v_mad_i64_i32 v[58:59], s[18:19], v48, s61, 0
	s_movk_i32 s18, 0x3fff
	s_nop 0
	v_cmp_lt_i32_e64 s[20:21], s18, v48
	s_movk_i32 s18, 0x7df
	v_bitop3_b32 v50, v68, s18, 16 bitop3:0xc8
	s_movk_i32 s18, 0x4000
	v_cmp_gt_i32_e32 vcc, s18, v48
	v_add_u32_e32 v96, 0xfffff880, v50
	v_ashrrev_i32_e32 v49, 31, v48
	v_cndmask_b32_e32 v51, v151, v50, vcc
	v_lshlrev_b32_e32 v70, 3, v51
	v_add_u32_e32 v51, 0xffffc010, v68
	s_movk_i32 s18, 0x77f
	v_lshlrev_b64 v[60:61], 7, v[96:97]
	s_mov_b64 s[70:71], 0x1080000
	v_lshlrev_b64 v[56:57], 11, v[48:49]
	v_lshlrev_b64 v[54:55], 8, v[48:49]
	v_lshrrev_b32_e32 v69, 2, v51
	v_cmp_lt_u32_e64 s[18:19], s18, v50
	v_lshlrev_b64 v[52:53], 10, v[48:49]
	v_lshl_add_u64 v[62:63], v[60:61], 0, s[70:71]
	s_and_b64 vcc, exec, s[16:17]
	s_mov_b64 s[70:71], -1
	s_cbranch_vccnz .LBB0_1400
	s_and_b64 vcc, exec, s[14:15]
	s_cbranch_vccnz .LBB0_1377
	s_andn2_b64 vcc, exec, s[90:91]
	s_cbranch_vccnz .LBB0_1374
	v_mul_f32_e32 v48, 0xbfb8aa3b, v44
	v_exp_f32_e32 v48, v48
	v_mul_f32_e32 v49, 0xbfb8aa3b, v45
	v_mul_f32_e32 v51, 0xbfb8aa3b, v47
	v_exp_f32_e32 v49, v49
	v_add_f32_e32 v48, 1.0, v48
	v_rcp_f32_e32 v50, v48
	v_mul_f32_e32 v48, 0xbfb8aa3b, v46
	v_exp_f32_e32 v48, v48
	v_exp_f32_e32 v51, v51
	v_add_f32_e32 v49, 1.0, v49
	v_rcp_f32_e32 v64, v49
	v_add_f32_e32 v48, 1.0, v48
	v_rcp_f32_e32 v65, v48
	v_add_f32_e32 v48, 1.0, v51
	v_rcp_f32_e32 v51, v48
	v_lshl_add_u64 v[48:49], s[54:55], 0, v[58:59]
	v_lshl_add_u64 v[48:49], s[56:57], 1, v[48:49]
	v_lshlrev_b32_e32 v96, 1, v142
	v_lshl_add_u64 v[48:49], v[48:49], 0, v[96:97]
	s_mov_b64 s[70:71], 0
	v_cvt_pk_bf16_f32 v198, v50, v64
	v_cvt_pk_bf16_f32 v199, v65, v51

; __device__ __forceinline__ float sigm(float x) { return __builtin_amdgcn_rcpf(1.f + __expf(-x)); }
; __device__ __forceinline__ void st_bf4(bf16_t* p, const f32x4 v) { u32x2 w; w.x = cvt_pk_bf16(v[0], v[1]); w.y = cvt_pk_bf16(v[2], v[3]); *(u32x2*)p = w; }
;     __device__ __forceinline__ void operator()(const f32x4 (&acc)[2][2][4][2], const Unit& u, int wr, int wc, int fr, int fq) const {
;     ...
;                         else { f32x4 s; s[0] = sigm(v[0]); s[1] = sigm(v[1]); s[2] = sigm(v[2]); s[3] = sigm(v[3]); st_bf4(GT + (size_t)row * 3072 + (pn - 7) * 256 + tc, s); }
.LBB0_1386:
	s_and_b64 vcc, exec, s[14:15]
	s_cbranch_vccnz .LBB0_1392
	s_andn2_b64 vcc, exec, s[90:91]
	s_cbranch_vccnz .LBB0_1389
	v_mul_f32_e32 v44, 0xbfb8aa3b, v40
	v_exp_f32_e32 v44, v44
	v_mul_f32_e32 v45, 0xbfb8aa3b, v41
	v_mul_f32_e32 v47, 0xbfb8aa3b, v43
	v_exp_f32_e32 v45, v45
	v_add_f32_e32 v44, 1.0, v44
	v_rcp_f32_e32 v46, v44
	v_mul_f32_e32 v44, 0xbfb8aa3b, v42
	v_exp_f32_e32 v44, v44
	v_exp_f32_e32 v47, v47
	v_add_f32_e32 v45, 1.0, v45
	v_rcp_f32_e32 v50, v45
	v_add_f32_e32 v44, 1.0, v44
	v_rcp_f32_e32 v51, v44
	v_add_f32_e32 v44, 1.0, v47
	v_rcp_f32_e32 v47, v44
	v_lshl_add_u64 v[44:45], s[54:55], 0, v[58:59]
	v_lshl_add_u64 v[44:45], s[56:57], 1, v[44:45]
	v_lshlrev_b32_e32 v96, 1, v142
	v_lshl_add_u64 v[44:45], v[44:45], 0, v[96:97]
	s_mov_b64 s[70:71], 0
	v_cvt_pk_bf16_f32 v200, v46, v50
	v_cvt_pk_bf16_f32 v201, v51, v47
	global_store_dwordx4 v[44:45], v[198:201], off

; __device__ __forceinline__ float sigm(float x) { return __builtin_amdgcn_rcpf(1.f + __expf(-x)); }
; __device__ __forceinline__ void st_bf4(bf16_t* p, const f32x4 v) { u32x2 w; w.x = cvt_pk_bf16(v[0], v[1]); w.y = cvt_pk_bf16(v[2], v[3]); *(u32x2*)p = w; }
;     __device__ __forceinline__ void operator()(const f32x4 (&acc)[2][2][4][2], const Unit& u, int wr, int wc, int fr, int fq) const {
;     ...
;                         else { f32x4 s; s[0] = sigm(v[0]); s[1] = sigm(v[1]); s[2] = sigm(v[2]); s[3] = sigm(v[3]); st_bf4(GT + (size_t)row * 3072 + (pn - 7) * 256 + tc, s); }
.LBB0_1404:
	s_mov_b64 s[70:71], 0x1100000
	v_lshl_add_u64 v[44:45], v[60:61], 0, s[70:71]
	s_and_b64 vcc, exec, s[16:17]
	s_mov_b64 s[70:71], -1
	s_cbranch_vccnz .LBB0_1434
	s_and_b64 vcc, exec, s[14:15]
	s_cbranch_vccnz .LBB0_1411
	s_andn2_b64 vcc, exec, s[90:91]
	s_cbranch_vccnz .LBB0_1408
	v_mul_f32_e32 v40, 0xbfb8aa3b, v36
	v_exp_f32_e32 v40, v40
	v_mul_f32_e32 v41, 0xbfb8aa3b, v37
	v_mul_f32_e32 v43, 0xbfb8aa3b, v39
	v_exp_f32_e32 v41, v41
	v_add_f32_e32 v40, 1.0, v40
	v_rcp_f32_e32 v42, v40
	v_mul_f32_e32 v40, 0xbfb8aa3b, v38
	v_exp_f32_e32 v40, v40
	v_exp_f32_e32 v43, v43
	v_add_f32_e32 v41, 1.0, v41
	v_rcp_f32_e32 v46, v41
	v_add_f32_e32 v40, 1.0, v40
	v_rcp_f32_e32 v47, v40
	v_add_f32_e32 v40, 1.0, v43
	v_rcp_f32_e32 v43, v40
	v_lshl_add_u64 v[40:41], s[54:55], 0, v[58:59]
	v_lshl_add_u64 v[40:41], s[56:57], 1, v[40:41]
	v_lshlrev_b32_e32 v96, 1, v142
	v_lshl_add_u64 v[40:41], v[40:41], 0, v[96:97]
	s_mov_b64 s[70:71], 0
	v_cvt_pk_bf16_f32 v250, v42, v46
	v_cvt_pk_bf16_f32 v251, v47, v43

; __device__ __forceinline__ float sigm(float x) { return __builtin_amdgcn_rcpf(1.f + __expf(-x)); }
; __device__ __forceinline__ void st_bf4(bf16_t* p, const f32x4 v) { u32x2 w; w.x = cvt_pk_bf16(v[0], v[1]); w.y = cvt_pk_bf16(v[2], v[3]); *(u32x2*)p = w; }
;     __device__ __forceinline__ void operator()(const f32x4 (&acc)[2][2][4][2], const Unit& u, int wr, int wc, int fr, int fq) const {
;     ...
;                         else { f32x4 s; s[0] = sigm(v[0]); s[1] = sigm(v[1]); s[2] = sigm(v[2]); s[3] = sigm(v[3]); st_bf4(GT + (size_t)row * 3072 + (pn - 7) * 256 + tc, s); }
.LBB0_1420:
	s_and_b64 vcc, exec, s[14:15]
	s_cbranch_vccnz .LBB0_1426
	s_andn2_b64 vcc, exec, s[90:91]
	s_cbranch_vccnz .LBB0_1423
	v_mul_f32_e32 v36, 0xbfb8aa3b, v32
	v_exp_f32_e32 v36, v36
	v_mul_f32_e32 v37, 0xbfb8aa3b, v33
	v_mul_f32_e32 v39, 0xbfb8aa3b, v35
	v_exp_f32_e32 v37, v37
	v_add_f32_e32 v36, 1.0, v36
	v_rcp_f32_e32 v38, v36
	v_mul_f32_e32 v36, 0xbfb8aa3b, v34
	v_exp_f32_e32 v36, v36
	v_exp_f32_e32 v39, v39
	v_add_f32_e32 v37, 1.0, v37
	v_rcp_f32_e32 v40, v37
	v_add_f32_e32 v36, 1.0, v36
	v_rcp_f32_e32 v41, v36
	v_add_f32_e32 v36, 1.0, v39
	v_rcp_f32_e32 v39, v36
	v_lshl_add_u64 v[36:37], s[54:55], 0, v[58:59]
	v_lshl_add_u64 v[36:37], s[56:57], 1, v[36:37]
	v_lshlrev_b32_e32 v96, 1, v142
	v_lshl_add_u64 v[36:37], v[36:37], 0, v[96:97]
	s_mov_b64 s[70:71], 0
	v_cvt_pk_bf16_f32 v252, v38, v40
	v_cvt_pk_bf16_f32 v253, v41, v39
	global_store_dwordx4 v[36:37], v[250:253], off offset:256

; __device__ __forceinline__ float sigm(float x) { return __builtin_amdgcn_rcpf(1.f + __expf(-x)); }
;     __device__ __forceinline__ void operator()(const f32x4 (&acc)[2][2][4][2], const Unit& u, int wr, int wc, int fr, int fq) const {
;     ...
;             for (int m = 0; m < 4; ++m) { const int row = u.pm * 256 + ai * 128 + wr * 64 + m * 16 + fr;
; #pragma unroll
;                 for (int bj = 0; bj < 2; ++bj)
; #pragma unroll
;                     for (int n = 0; n < 2; ++n) { const int tc = bj * 128 + wc * 32 + 8 * fq + 4 * n; f32x4 v = acc[ai][bj][m][n];
;                         if (pn < 2) { *(f32x4*)(XA + (size_t)row * 512 + pn * 256 + tc) = v; }
;                         else if (pn <= 4) {
;                             const bool isv = (pn == 4 && bj == 1);
;                             if (!isv && (wc & 1) == 0) {
;                                 const int tix = row < cfg::MP ? (row & 2047) : 2048 + (row & 3);
;                                 const f32x4 cs = *(const f32x4*)(ropec + tix * 8 + 4 * n), sn = *(const f32x4*)(ropes + tix * 8 + 4 * n);
; #pragma unroll
;                                 for (int i = 0; i < 4; ++i) { const float p = shx16(v[i], fq & 1); const float rv = v[i] * cs[i] + (fq == 0 ? -p : p) * sn[i]; v[i] = fq < 2 ? rv : v[i]; }
;                             }
;                             if (pn < 4) st_bf4(Q + (size_t)row * 512 + (pn - 2) * 256 + tc, v);
;                             else { st_bf4((bj == 0 ? KB : VB) + (size_t)row * 128 + (tc & 127), v);
;                                 bool w = false; size_t o = 0;
;                                 if (row < cfg::MP) { const int t = row & 2047; if (t >= 1920) { w = true; o = (bj == 0 ? cfg::OFF_KP : cfg::OFF_VP) + ((size_t)(layer * 8 + (row >> 11)) * 128 + (t - 1920)) * 128 + (tc & 127); } }
;                                 else { const int rs = row - cfg::MP; w = true; o = (bj == 0 ? cfg::OFF_KS : cfg::OFF_VS) + ((size_t)(layer * 128 + (rs >> 2)) * 128 + 124 + (rs & 3)) * 128 + (tc & 127); }
;                                 if (w) *(f32x4*)(out + o) = v; }
;                         }
;                         else if (pn < 7) { *(f32x4*)(U + (size_t)row * 512 + (pn - 5) * 256 + tc) = v; }
;                         else { f32x4 s; s[0] = sigm(v[0]); s[1] = sigm(v[1]); s[2] = sigm(v[2]); s[3] = sigm(v[3]); st_bf4(GT + (size_t)row * 3072 + (pn - 7) * 256 + tc, s); }
.LBB0_1438:
	s_nop 1
	v_or_b32_e32 v32, 32, v68
	v_mad_i64_i32 v[42:43], s[18:19], v32, s61, 0
	s_movk_i32 s18, 0x3fff
	s_nop 0
	v_cmp_lt_i32_e64 s[20:21], s18, v32
	s_movk_i32 s18, 0x7ef
	v_bitop3_b32 v34, v68, s18, 32 bitop3:0xc8
	s_movk_i32 s18, 0x4000
	v_cmp_gt_i32_e32 vcc, s18, v32
	v_add_u32_e32 v96, 0xfffff880, v34
	v_ashrrev_i32_e32 v33, 31, v32
	v_cndmask_b32_e32 v35, v151, v34, vcc
	v_lshlrev_b32_e32 v53, 3, v35
	v_add_u32_e32 v35, 0xffffc020, v68
	s_movk_i32 s18, 0x77f
	v_lshlrev_b64 v[44:45], 7, v[96:97]
	s_mov_b64 s[70:71], 0x1080000
	v_lshlrev_b64 v[40:41], 11, v[32:33]
	v_lshlrev_b64 v[38:39], 8, v[32:33]
	v_lshrrev_b32_e32 v52, 2, v35
	v_cmp_lt_u32_e64 s[18:19], s18, v34
	v_lshlrev_b64 v[36:37], 10, v[32:33]
	v_lshl_add_u64 v[46:47], v[44:45], 0, s[70:71]
	s_and_b64 vcc, exec, s[16:17]
	s_mov_b64 s[70:71], -1
	s_cbranch_vccnz .LBB0_1468
	s_and_b64 vcc, exec, s[14:15]
	s_cbranch_vccnz .LBB0_1445
	s_andn2_b64 vcc, exec, s[90:91]
	s_cbranch_vccnz .LBB0_1442
	v_mul_f32_e32 v32, 0xbfb8aa3b, v28
	v_exp_f32_e32 v32, v32
	v_mul_f32_e32 v33, 0xbfb8aa3b, v29
	v_mul_f32_e32 v35, 0xbfb8aa3b, v31
	v_exp_f32_e32 v33, v33
	v_add_f32_e32 v32, 1.0, v32
	v_rcp_f32_e32 v34, v32
	v_mul_f32_e32 v32, 0xbfb8aa3b, v30
	v_exp_f32_e32 v32, v32
	v_exp_f32_e32 v35, v35
	v_add_f32_e32 v33, 1.0, v33
	v_rcp_f32_e32 v48, v33
	v_add_f32_e32 v32, 1.0, v32
	v_rcp_f32_e32 v49, v32
	v_add_f32_e32 v32, 1.0, v35
	v_rcp_f32_e32 v35, v32
	v_lshl_add_u64 v[32:33], s[54:55], 0, v[42:43]
	v_lshl_add_u64 v[32:33], s[56:57], 1, v[32:33]
	v_lshlrev_b32_e32 v96, 1, v142
	v_lshl_add_u64 v[32:33], v[32:33], 0, v[96:97]
	s_mov_b64 s[70:71], 0
	v_cvt_pk_bf16_f32 v190, v34, v48
	v_cvt_pk_bf16_f32 v191, v49, v35

; __device__ __forceinline__ float sigm(float x) { return __builtin_amdgcn_rcpf(1.f + __expf(-x)); }
; __device__ __forceinline__ void st_bf4(bf16_t* p, const f32x4 v) { u32x2 w; w.x = cvt_pk_bf16(v[0], v[1]); w.y = cvt_pk_bf16(v[2], v[3]); *(u32x2*)p = w; }
;     __device__ __forceinline__ void operator()(const f32x4 (&acc)[2][2][4][2], const Unit& u, int wr, int wc, int fr, int fq) const {
;     ...
;                         else { f32x4 s; s[0] = sigm(v[0]); s[1] = sigm(v[1]); s[2] = sigm(v[2]); s[3] = sigm(v[3]); st_bf4(GT + (size_t)row * 3072 + (pn - 7) * 256 + tc, s); }
.LBB0_1454:
	s_and_b64 vcc, exec, s[14:15]
	s_cbranch_vccnz .LBB0_1460
	s_andn2_b64 vcc, exec, s[90:91]
	s_cbranch_vccnz .LBB0_1457
	v_mul_f32_e32 v28, 0xbfb8aa3b, v24
	v_exp_f32_e32 v28, v28
	v_mul_f32_e32 v29, 0xbfb8aa3b, v25
	v_mul_f32_e32 v31, 0xbfb8aa3b, v27
	v_exp_f32_e32 v29, v29
	v_add_f32_e32 v28, 1.0, v28
	v_rcp_f32_e32 v30, v28
	v_mul_f32_e32 v28, 0xbfb8aa3b, v26
	v_exp_f32_e32 v28, v28
	v_exp_f32_e32 v31, v31
	v_add_f32_e32 v29, 1.0, v29
	v_rcp_f32_e32 v34, v29
	v_add_f32_e32 v28, 1.0, v28
	v_rcp_f32_e32 v35, v28
	v_add_f32_e32 v28, 1.0, v31
	v_rcp_f32_e32 v31, v28
	v_lshl_add_u64 v[28:29], s[54:55], 0, v[42:43]
	v_lshl_add_u64 v[28:29], s[56:57], 1, v[28:29]
	v_lshlrev_b32_e32 v96, 1, v142
	v_lshl_add_u64 v[28:29], v[28:29], 0, v[96:97]
	s_mov_b64 s[70:71], 0
	v_cvt_pk_bf16_f32 v192, v30, v34
	v_cvt_pk_bf16_f32 v193, v35, v31
	global_store_dwordx4 v[28:29], v[190:193], off

; __device__ __forceinline__ float sigm(float x) { return __builtin_amdgcn_rcpf(1.f + __expf(-x)); }
; __device__ __forceinline__ void st_bf4(bf16_t* p, const f32x4 v) { u32x2 w; w.x = cvt_pk_bf16(v[0], v[1]); w.y = cvt_pk_bf16(v[2], v[3]); *(u32x2*)p = w; }
;     __device__ __forceinline__ void operator()(const f32x4 (&acc)[2][2][4][2], const Unit& u, int wr, int wc, int fr, int fq) const {
;     ...
;                         else { f32x4 s; s[0] = sigm(v[0]); s[1] = sigm(v[1]); s[2] = sigm(v[2]); s[3] = sigm(v[3]); st_bf4(GT + (size_t)row * 3072 + (pn - 7) * 256 + tc, s); }
.LBB0_1472:
	s_mov_b64 s[70:71], 0x1100000
	v_lshl_add_u64 v[28:29], v[44:45], 0, s[70:71]
	s_and_b64 vcc, exec, s[16:17]
	s_mov_b64 s[70:71], -1
	s_cbranch_vccnz .LBB0_1502
	s_and_b64 vcc, exec, s[14:15]
	s_cbranch_vccnz .LBB0_1479
	s_andn2_b64 vcc, exec, s[90:91]
	s_cbranch_vccnz .LBB0_1476
	v_mul_f32_e32 v24, 0xbfb8aa3b, v20
	v_exp_f32_e32 v24, v24
	v_mul_f32_e32 v25, 0xbfb8aa3b, v21
	v_mul_f32_e32 v27, 0xbfb8aa3b, v23
	v_exp_f32_e32 v25, v25
	v_add_f32_e32 v24, 1.0, v24
	v_rcp_f32_e32 v26, v24
	v_mul_f32_e32 v24, 0xbfb8aa3b, v22
	v_exp_f32_e32 v24, v24
	v_exp_f32_e32 v27, v27
	v_add_f32_e32 v25, 1.0, v25
	v_rcp_f32_e32 v30, v25
	v_add_f32_e32 v24, 1.0, v24
	v_rcp_f32_e32 v31, v24
	v_add_f32_e32 v24, 1.0, v27
	v_rcp_f32_e32 v27, v24
	v_lshl_add_u64 v[24:25], s[54:55], 0, v[42:43]
	v_lshl_add_u64 v[24:25], s[56:57], 1, v[24:25]
	v_lshlrev_b32_e32 v96, 1, v142
	v_lshl_add_u64 v[24:25], v[24:25], 0, v[96:97]
	s_mov_b64 s[70:71], 0
	v_cvt_pk_bf16_f32 v198, v26, v30
	v_cvt_pk_bf16_f32 v199, v31, v27

; __device__ __forceinline__ float sigm(float x) { return __builtin_amdgcn_rcpf(1.f + __expf(-x)); }
; __device__ __forceinline__ void st_bf4(bf16_t* p, const f32x4 v) { u32x2 w; w.x = cvt_pk_bf16(v[0], v[1]); w.y = cvt_pk_bf16(v[2], v[3]); *(u32x2*)p = w; }
;     __device__ __forceinline__ void operator()(const f32x4 (&acc)[2][2][4][2], const Unit& u, int wr, int wc, int fr, int fq) const {
;     ...
;                         else { f32x4 s; s[0] = sigm(v[0]); s[1] = sigm(v[1]); s[2] = sigm(v[2]); s[3] = sigm(v[3]); st_bf4(GT + (size_t)row * 3072 + (pn - 7) * 256 + tc, s); }
.LBB0_1488:
	s_and_b64 vcc, exec, s[14:15]
	s_cbranch_vccnz .LBB0_1494
	s_andn2_b64 vcc, exec, s[90:91]
	s_cbranch_vccnz .LBB0_1491
	v_mul_f32_e32 v20, 0xbfb8aa3b, v16
	v_exp_f32_e32 v20, v20
	v_mul_f32_e32 v21, 0xbfb8aa3b, v17
	v_mul_f32_e32 v23, 0xbfb8aa3b, v19
	v_exp_f32_e32 v21, v21
	v_add_f32_e32 v20, 1.0, v20
	v_rcp_f32_e32 v22, v20
	v_mul_f32_e32 v20, 0xbfb8aa3b, v18
	v_exp_f32_e32 v20, v20
	v_exp_f32_e32 v23, v23
	v_add_f32_e32 v21, 1.0, v21
	v_rcp_f32_e32 v24, v21
	v_add_f32_e32 v20, 1.0, v20
	v_rcp_f32_e32 v25, v20
	v_add_f32_e32 v20, 1.0, v23
	v_rcp_f32_e32 v23, v20
	v_lshl_add_u64 v[20:21], s[54:55], 0, v[42:43]
	v_lshl_add_u64 v[20:21], s[56:57], 1, v[20:21]
	v_lshlrev_b32_e32 v96, 1, v142
	v_lshl_add_u64 v[20:21], v[20:21], 0, v[96:97]
	s_mov_b64 s[70:71], 0
	v_cvt_pk_bf16_f32 v200, v22, v24
	v_cvt_pk_bf16_f32 v201, v25, v23
	global_store_dwordx4 v[20:21], v[198:201], off offset:256

; __device__ __forceinline__ float sigm(float x) { return __builtin_amdgcn_rcpf(1.f + __expf(-x)); }
;     __device__ __forceinline__ void operator()(const f32x4 (&acc)[2][2][4][2], const Unit& u, int wr, int wc, int fr, int fq) const {
;     ...
;             for (int m = 0; m < 4; ++m) { const int row = u.pm * 256 + ai * 128 + wr * 64 + m * 16 + fr;
; #pragma unroll
;                 for (int bj = 0; bj < 2; ++bj)
; #pragma unroll
;                     for (int n = 0; n < 2; ++n) { const int tc = bj * 128 + wc * 32 + 8 * fq + 4 * n; f32x4 v = acc[ai][bj][m][n];
;                         if (pn < 2) { *(f32x4*)(XA + (size_t)row * 512 + pn * 256 + tc) = v; }
;                         else if (pn <= 4) {
;                             const bool isv = (pn == 4 && bj == 1);
;                             if (!isv && (wc & 1) == 0) {
;                                 const int tix = row < cfg::MP ? (row & 2047) : 2048 + (row & 3);
;                                 const f32x4 cs = *(const f32x4*)(ropec + tix * 8 + 4 * n), sn = *(const f32x4*)(ropes + tix * 8 + 4 * n);
; #pragma unroll
;                                 for (int i = 0; i < 4; ++i) { const float p = shx16(v[i], fq & 1); const float rv = v[i] * cs[i] + (fq == 0 ? -p : p) * sn[i]; v[i] = fq < 2 ? rv : v[i]; }
;                             }
;                             if (pn < 4) st_bf4(Q + (size_t)row * 512 + (pn - 2) * 256 + tc, v);
;                             else { st_bf4((bj == 0 ? KB : VB) + (size_t)row * 128 + (tc & 127), v);
;                                 bool w = false; size_t o = 0;
;                                 if (row < cfg::MP) { const int t = row & 2047; if (t >= 1920) { w = true; o = (bj == 0 ? cfg::OFF_KP : cfg::OFF_VP) + ((size_t)(layer * 8 + (row >> 11)) * 128 + (t - 1920)) * 128 + (tc & 127); } }
;                                 else { const int rs = row - cfg::MP; w = true; o = (bj == 0 ? cfg::OFF_KS : cfg::OFF_VS) + ((size_t)(layer * 128 + (rs >> 2)) * 128 + 124 + (rs & 3)) * 128 + (tc & 127); }
;                                 if (w) *(f32x4*)(out + o) = v; }
;                         }
;                         else if (pn < 7) { *(f32x4*)(U + (size_t)row * 512 + (pn - 5) * 256 + tc) = v; }
;                         else { f32x4 s; s[0] = sigm(v[0]); s[1] = sigm(v[1]); s[2] = sigm(v[2]); s[3] = sigm(v[3]); st_bf4(GT + (size_t)row * 3072 + (pn - 7) * 256 + tc, s); }
.LBB0_1506:
	s_nop 1
	v_or_b32_e32 v16, 48, v68
	v_mad_i64_i32 v[26:27], s[18:19], v16, s61, 0
	s_movk_i32 s18, 0x3fff
	s_nop 0
	v_cmp_lt_i32_e64 s[20:21], s18, v16
	s_movk_i32 s18, 0x7ff
	v_bitop3_b32 v18, v68, s18, 48 bitop3:0xc8
	s_movk_i32 s18, 0x4000
	v_cmp_gt_i32_e32 vcc, s18, v16
	v_add_u32_e32 v96, 0xfffff880, v18
	v_ashrrev_i32_e32 v17, 31, v16
	v_cndmask_b32_e32 v19, v151, v18, vcc
	v_lshlrev_b32_e32 v37, 3, v19
	v_add_u32_e32 v19, 0xffffc030, v68
	s_movk_i32 s18, 0x77f
	v_lshlrev_b64 v[28:29], 7, v[96:97]
	s_mov_b64 s[70:71], 0x1080000
	v_lshlrev_b64 v[24:25], 11, v[16:17]
	v_lshlrev_b64 v[22:23], 8, v[16:17]
	v_lshrrev_b32_e32 v36, 2, v19
	v_cmp_lt_u32_e64 s[18:19], s18, v18
	v_lshlrev_b64 v[20:21], 10, v[16:17]
	v_lshl_add_u64 v[30:31], v[28:29], 0, s[70:71]
	s_and_b64 vcc, exec, s[16:17]
	s_mov_b64 s[70:71], -1
	s_cbranch_vccnz .LBB0_1536
	s_and_b64 vcc, exec, s[14:15]
	s_cbranch_vccnz .LBB0_1513
	s_andn2_b64 vcc, exec, s[90:91]
	s_cbranch_vccnz .LBB0_1510
	v_mul_f32_e32 v16, 0xbfb8aa3b, v12
	v_exp_f32_e32 v16, v16
	v_mul_f32_e32 v17, 0xbfb8aa3b, v13
	v_mul_f32_e32 v19, 0xbfb8aa3b, v15
	v_exp_f32_e32 v17, v17
	v_add_f32_e32 v16, 1.0, v16
	v_rcp_f32_e32 v18, v16
	v_mul_f32_e32 v16, 0xbfb8aa3b, v14
	v_exp_f32_e32 v16, v16
	v_exp_f32_e32 v19, v19
	v_add_f32_e32 v17, 1.0, v17
	v_rcp_f32_e32 v32, v17
	v_add_f32_e32 v16, 1.0, v16
	v_rcp_f32_e32 v33, v16
	v_add_f32_e32 v16, 1.0, v19
	v_rcp_f32_e32 v19, v16
	v_lshl_add_u64 v[16:17], s[54:55], 0, v[26:27]
	v_lshl_add_u64 v[16:17], s[56:57], 1, v[16:17]
	v_lshlrev_b32_e32 v96, 1, v142
	v_lshl_add_u64 v[16:17], v[16:17], 0, v[96:97]
	s_mov_b64 s[70:71], 0
	v_cvt_pk_bf16_f32 v250, v18, v32
	v_cvt_pk_bf16_f32 v251, v33, v19

; __device__ __forceinline__ float sigm(float x) { return __builtin_amdgcn_rcpf(1.f + __expf(-x)); }
; __device__ __forceinline__ void st_bf4(bf16_t* p, const f32x4 v) { u32x2 w; w.x = cvt_pk_bf16(v[0], v[1]); w.y = cvt_pk_bf16(v[2], v[3]); *(u32x2*)p = w; }
;     __device__ __forceinline__ void operator()(const f32x4 (&acc)[2][2][4][2], const Unit& u, int wr, int wc, int fr, int fq) const {
;     ...
;                         else { f32x4 s; s[0] = sigm(v[0]); s[1] = sigm(v[1]); s[2] = sigm(v[2]); s[3] = sigm(v[3]); st_bf4(GT + (size_t)row * 3072 + (pn - 7) * 256 + tc, s); }
.LBB0_1522:
	s_and_b64 vcc, exec, s[14:15]
	s_cbranch_vccnz .LBB0_1528
	s_andn2_b64 vcc, exec, s[90:91]
	s_cbranch_vccnz .LBB0_1525
	v_mul_f32_e32 v12, 0xbfb8aa3b, v8
	v_exp_f32_e32 v12, v12
	v_mul_f32_e32 v13, 0xbfb8aa3b, v9
	v_mul_f32_e32 v15, 0xbfb8aa3b, v11
	v_exp_f32_e32 v13, v13
	v_add_f32_e32 v12, 1.0, v12
	v_rcp_f32_e32 v14, v12
	v_mul_f32_e32 v12, 0xbfb8aa3b, v10
	v_exp_f32_e32 v12, v12
	v_exp_f32_e32 v15, v15
	v_add_f32_e32 v13, 1.0, v13
	v_rcp_f32_e32 v18, v13
	v_add_f32_e32 v12, 1.0, v12
	v_rcp_f32_e32 v19, v12
	v_add_f32_e32 v12, 1.0, v15
	v_rcp_f32_e32 v15, v12
	v_lshl_add_u64 v[12:13], s[54:55], 0, v[26:27]
	v_lshl_add_u64 v[12:13], s[56:57], 1, v[12:13]
	v_lshlrev_b32_e32 v96, 1, v142
	v_lshl_add_u64 v[12:13], v[12:13], 0, v[96:97]
	s_mov_b64 s[70:71], 0
	v_cvt_pk_bf16_f32 v252, v14, v18
	v_cvt_pk_bf16_f32 v253, v19, v15
	global_store_dwordx4 v[12:13], v[250:253], off

; __device__ __forceinline__ float sigm(float x) { return __builtin_amdgcn_rcpf(1.f + __expf(-x)); }
; __device__ __forceinline__ void st_bf4(bf16_t* p, const f32x4 v) { u32x2 w; w.x = cvt_pk_bf16(v[0], v[1]); w.y = cvt_pk_bf16(v[2], v[3]); *(u32x2*)p = w; }
;     __device__ __forceinline__ void operator()(const f32x4 (&acc)[2][2][4][2], const Unit& u, int wr, int wc, int fr, int fq) const {
;     ...
;                         else { f32x4 s; s[0] = sigm(v[0]); s[1] = sigm(v[1]); s[2] = sigm(v[2]); s[3] = sigm(v[3]); st_bf4(GT + (size_t)row * 3072 + (pn - 7) * 256 + tc, s); }
.LBB0_1540:
	s_mov_b64 s[70:71], 0x1100000
	v_lshl_add_u64 v[12:13], v[28:29], 0, s[70:71]
	s_and_b64 vcc, exec, s[16:17]
	s_mov_b64 s[70:71], -1
	s_cbranch_vccnz .LBB0_1555
	s_and_b64 vcc, exec, s[14:15]
	s_cbranch_vccnz .LBB0_1547
	s_andn2_b64 vcc, exec, s[90:91]
	s_cbranch_vccnz .LBB0_1544
	v_mul_f32_e32 v8, 0xbfb8aa3b, v4
	v_exp_f32_e32 v8, v8
	v_mul_f32_e32 v9, 0xbfb8aa3b, v5
	v_mul_f32_e32 v11, 0xbfb8aa3b, v7
	v_exp_f32_e32 v9, v9
	v_add_f32_e32 v8, 1.0, v8
	v_rcp_f32_e32 v10, v8
	v_mul_f32_e32 v8, 0xbfb8aa3b, v6
	v_exp_f32_e32 v8, v8
	v_exp_f32_e32 v11, v11
	v_add_f32_e32 v9, 1.0, v9
	v_rcp_f32_e32 v14, v9
	v_add_f32_e32 v8, 1.0, v8
	v_rcp_f32_e32 v15, v8
	v_add_f32_e32 v8, 1.0, v11
	v_rcp_f32_e32 v11, v8
	v_lshl_add_u64 v[8:9], s[54:55], 0, v[26:27]
	v_lshl_add_u64 v[8:9], s[56:57], 1, v[8:9]
	v_lshlrev_b32_e32 v96, 1, v142
	v_lshl_add_u64 v[8:9], v[8:9], 0, v[96:97]
	s_mov_b64 s[70:71], 0
	v_cvt_pk_bf16_f32 v190, v10, v14
	v_cvt_pk_bf16_f32 v191, v15, v11

; __device__ __forceinline__ float sigm(float x) { return __builtin_amdgcn_rcpf(1.f + __expf(-x)); }
; __device__ __forceinline__ void st_bf4(bf16_t* p, const f32x4 v) { u32x2 w; w.x = cvt_pk_bf16(v[0], v[1]); w.y = cvt_pk_bf16(v[2], v[3]); *(u32x2*)p = w; }
;     __device__ __forceinline__ void operator()(const f32x4 (&acc)[2][2][4][2], const Unit& u, int wr, int wc, int fr, int fq) const {
;     ...
;                         else { f32x4 s; s[0] = sigm(v[0]); s[1] = sigm(v[1]); s[2] = sigm(v[2]); s[3] = sigm(v[3]); st_bf4(GT + (size_t)row * 3072 + (pn - 7) * 256 + tc, s); }
.LBB0_1557:
	s_and_b64 vcc, exec, s[16:17]
	s_mov_b64 s[16:17], -1
	s_mov_b32 s70, 0x1200000
	s_mov_b32 s71, 0x1400000
	s_cbranch_vccnz .LBB0_1572
	s_and_b64 vcc, exec, s[14:15]
	s_mov_b64 s[14:15], -1
	s_cbranch_vccnz .LBB0_1564
	s_andn2_b64 vcc, exec, s[90:91]
	s_cbranch_vccnz .LBB0_1561
	v_mul_f32_e32 v4, 0xbfb8aa3b, v0
	v_exp_f32_e32 v4, v4
	v_mul_f32_e32 v5, 0xbfb8aa3b, v1
	v_mul_f32_e32 v7, 0xbfb8aa3b, v3
	v_exp_f32_e32 v5, v5
	v_add_f32_e32 v4, 1.0, v4
	v_rcp_f32_e32 v6, v4
	v_mul_f32_e32 v4, 0xbfb8aa3b, v2
	v_exp_f32_e32 v4, v4
	v_exp_f32_e32 v7, v7
	v_add_f32_e32 v5, 1.0, v5
	v_rcp_f32_e32 v8, v5
	v_add_f32_e32 v4, 1.0, v4
	v_rcp_f32_e32 v9, v4
	v_add_f32_e32 v4, 1.0, v7
	v_rcp_f32_e32 v7, v4
	v_lshl_add_u64 v[4:5], s[54:55], 0, v[26:27]
	v_lshl_add_u64 v[4:5], s[56:57], 1, v[4:5]
	v_lshlrev_b32_e32 v96, 1, v142
	v_lshl_add_u64 v[4:5], v[4:5], 0, v[96:97]
	s_mov_b64 s[14:15], 0
	v_cvt_pk_bf16_f32 v192, v6, v8
	v_cvt_pk_bf16_f32 v193, v9, v7
	global_store_dwordx4 v[4:5], v[190:193], off offset:256

; __device__ __forceinline__ float sigm(float x) { return __builtin_amdgcn_rcpf(1.f + __expf(-x)); }
;     __device__ __forceinline__ void operator()(const f32x4 (&acc)[2][2][4][2], const Unit& u, int wr, int wc, int fr, int fq) const {
;     ...
;             for (int m = 0; m < 4; ++m) { const int row = u.pm * 256 + ai * 128 + wr * 64 + m * 16 + fr;
; #pragma unroll
;                 for (int bj = 0; bj < 2; ++bj)
; #pragma unroll
;                     for (int n = 0; n < 2; ++n) { const int tc = bj * 128 + wc * 32 + 8 * fq + 4 * n; f32x4 v = acc[ai][bj][m][n];
;                         if (pn < 2) { *(f32x4*)(XA + (size_t)row * 512 + pn * 256 + tc) = v; }
;                         else if (pn <= 4) {
;                             const bool isv = (pn == 4 && bj == 1);
;                             if (!isv && (wc & 1) == 0) {
;                                 const int tix = row < cfg::MP ? (row & 2047) : 2048 + (row & 3);
;                                 const f32x4 cs = *(const f32x4*)(ropec + tix * 8 + 4 * n), sn = *(const f32x4*)(ropes + tix * 8 + 4 * n);
; #pragma unroll
;                                 for (int i = 0; i < 4; ++i) { const float p = shx16(v[i], fq & 1); const float rv = v[i] * cs[i] + (fq == 0 ? -p : p) * sn[i]; v[i] = fq < 2 ? rv : v[i]; }
;                             }
;                             if (pn < 4) st_bf4(Q + (size_t)row * 512 + (pn - 2) * 256 + tc, v);
;                             else { st_bf4((bj == 0 ? KB : VB) + (size_t)row * 128 + (tc & 127), v);
;                                 bool w = false; size_t o = 0;
;                                 if (row < cfg::MP) { const int t = row & 2047; if (t >= 1920) { w = true; o = (bj == 0 ? cfg::OFF_KP : cfg::OFF_VP) + ((size_t)(layer * 8 + (row >> 11)) * 128 + (t - 1920)) * 128 + (tc & 127); } }
;                                 else { const int rs = row - cfg::MP; w = true; o = (bj == 0 ? cfg::OFF_KS : cfg::OFF_VS) + ((size_t)(layer * 128 + (rs >> 2)) * 128 + 124 + (rs & 3)) * 128 + (tc & 127); }
;                                 if (w) *(f32x4*)(out + o) = v; }
;                         }
;                         else if (pn < 7) { *(f32x4*)(U + (size_t)row * 512 + (pn - 5) * 256 + tc) = v; }
;                         else { f32x4 s; s[0] = sigm(v[0]); s[1] = sigm(v[1]); s[2] = sigm(v[2]); s[3] = sigm(v[3]); st_bf4(GT + (size_t)row * 3072 + (pn - 7) * 256 + tc, s); }
.Lsp_gt:
	s_nop 7
	v_mul_f32_e32 v96, 0xbfb8aa3b, v126
	v_exp_f32_e32 v96, v96
	v_mul_f32_e32 v130, 0xbfb8aa3b, v127
	v_exp_f32_e32 v130, v130
	v_mul_f32_e32 v131, 0xbfb8aa3b, v129
	v_add_f32_e32 v96, 1.0, v96
	v_rcp_f32_e32 v132, v96
	v_mul_f32_e32 v96, 0xbfb8aa3b, v128
	v_exp_f32_e32 v96, v96
	v_exp_f32_e32 v131, v131
	v_add_f32_e32 v130, 1.0, v130
	v_rcp_f32_e32 v133, v130
	v_add_f32_e32 v96, 1.0, v96
	v_rcp_f32_e32 v146, v96
	v_add_f32_e32 v96, 1.0, v131
	v_rcp_f32_e32 v147, v96
	v_cvt_pk_bf16_f32 v190, v132, v133
	v_cvt_pk_bf16_f32 v191, v146, v147
	s_ashr_i32 s93, s0, 31
	s_mov_b32 s92, s0
	v_lshl_add_u64 v[130:131], s[30:31], 0, v[178:179]
	v_lshl_add_u64 v[132:133], s[92:93], 2, v[130:131]
	v_lshlrev_b32_e32 v130, 2, v142
	v_mul_f32_e32 v96, 0xbfb8aa3b, v122
	v_exp_f32_e32 v96, v96
	v_mul_f32_e32 v126, 0xbfb8aa3b, v123
	v_exp_f32_e32 v126, v126
	v_mul_f32_e32 v127, 0xbfb8aa3b, v125
	v_add_f32_e32 v96, 1.0, v96
	v_rcp_f32_e32 v128, v96
	v_mul_f32_e32 v96, 0xbfb8aa3b, v124
	v_exp_f32_e32 v96, v96
	v_exp_f32_e32 v127, v127
	v_add_f32_e32 v126, 1.0, v126
	v_rcp_f32_e32 v129, v126
	v_add_f32_e32 v96, 1.0, v96
	v_rcp_f32_e32 v131, v96
	v_add_f32_e32 v96, 1.0, v127
	v_lshl_add_u64 v[126:127], s[54:55], 0, v[180:181]
	v_rcp_f32_e32 v146, v96
	v_lshl_add_u64 v[126:127], s[56:57], 1, v[126:127]
	v_lshlrev_b32_e32 v96, 1, v142
	v_lshl_add_u64 v[126:127], v[126:127], 0, v[96:97]
	v_cvt_pk_bf16_f32 v192, v128, v129
	v_cvt_pk_bf16_f32 v193, v131, v146
	global_store_dwordx4 v[126:127], v[190:193], off
	v_readlane_b32 s70, v254, 59
	v_readlane_b32 s71, v254, 60
	v_mul_f32_e32 v96, 0xbfb8aa3b, v118
	v_exp_f32_e32 v96, v96
	v_mul_f32_e32 v122, 0xbfb8aa3b, v119
	v_exp_f32_e32 v122, v122
	v_mul_f32_e32 v123, 0xbfb8aa3b, v121
	v_add_f32_e32 v96, 1.0, v96
	v_rcp_f32_e32 v124, v96
	v_mul_f32_e32 v96, 0xbfb8aa3b, v120
	v_exp_f32_e32 v96, v96
	v_exp_f32_e32 v123, v123
	v_add_f32_e32 v122, 1.0, v122
	v_rcp_f32_e32 v125, v122
	v_add_f32_e32 v96, 1.0, v96
	v_rcp_f32_e32 v128, v96
	v_add_f32_e32 v96, 1.0, v123
	v_rcp_f32_e32 v129, v96
	v_cvt_pk_bf16_f32 v198, v124, v125
	v_cvt_pk_bf16_f32 v199, v128, v129
	v_mul_f32_e32 v96, 0xbfb8aa3b, v114
	v_exp_f32_e32 v96, v96
	v_mul_f32_e32 v118, 0xbfb8aa3b, v115
	v_exp_f32_e32 v118, v118
	v_mul_f32_e32 v119, 0xbfb8aa3b, v117
	v_add_f32_e32 v96, 1.0, v96
	v_rcp_f32_e32 v120, v96
	v_mul_f32_e32 v96, 0xbfb8aa3b, v116
	v_exp_f32_e32 v96, v96
	v_exp_f32_e32 v119, v119
	v_add_f32_e32 v118, 1.0, v118
	v_rcp_f32_e32 v121, v118
	v_add_f32_e32 v96, 1.0, v96
	v_rcp_f32_e32 v122, v96
	v_add_f32_e32 v96, 1.0, v119
	v_lshl_add_u64 v[118:119], s[54:55], 0, v[180:181]
	v_rcp_f32_e32 v123, v96
	v_lshl_add_u64 v[118:119], s[56:57], 1, v[118:119]
	v_lshlrev_b32_e32 v96, 1, v142
	v_lshl_add_u64 v[118:119], v[118:119], 0, v[96:97]
	v_cvt_pk_bf16_f32 v200, v120, v121
	v_cvt_pk_bf16_f32 v201, v122, v123
	global_store_dwordx4 v[118:119], v[198:201], off offset:256
	s_mov_b64 s[70:71], 0
	s_andn2_b64 vcc, exec, s[70:71]
	v_or_b32_e32 v114, 16, v172
	v_mad_i64_i32 v[124:125], s[18:19], v114, s61, 0
	s_movk_i32 s18, 0x7df
	s_nop 0
	v_bitop3_b32 v96, v172, s18, 16 bitop3:0xc8
	s_movk_i32 s18, 0x4000
	v_cmp_gt_i32_e32 vcc, s18, v114
	s_nop 1
	v_cndmask_b32_e32 v116, v151, v96, vcc
	v_add_u32_e32 v96, 0xfffff880, v96
	v_ashrrev_i32_e32 v115, 31, v114
	v_lshlrev_b32_e32 v176, 3, v116
	v_add_u32_e32 v116, 0xffffc010, v172
	v_lshlrev_b64 v[126:127], 7, v[96:97]
	s_mov_b64 s[70:71], 0x1080000
	v_lshlrev_b64 v[122:123], 11, v[114:115]
	v_lshlrev_b64 v[120:121], 8, v[114:115]
	v_lshrrev_b32_e32 v173, 2, v116
	v_lshl_add_u64 v[128:129], v[126:127], 0, s[70:71]
	v_mul_f32_e32 v96, 0xbfb8aa3b, v110
	v_exp_f32_e32 v96, v96
	v_mul_f32_e32 v114, 0xbfb8aa3b, v111
	v_exp_f32_e32 v114, v114
	v_mul_f32_e32 v115, 0xbfb8aa3b, v113
	v_add_f32_e32 v96, 1.0, v96
	v_rcp_f32_e32 v116, v96
	v_mul_f32_e32 v96, 0xbfb8aa3b, v112
	v_exp_f32_e32 v96, v96
	v_exp_f32_e32 v115, v115
	v_add_f32_e32 v114, 1.0, v114
	v_rcp_f32_e32 v117, v114
	v_add_f32_e32 v96, 1.0, v96
	v_rcp_f32_e32 v131, v96
	v_add_f32_e32 v96, 1.0, v115
	v_rcp_f32_e32 v132, v96
	v_cvt_pk_bf16_f32 v250, v116, v117
	v_cvt_pk_bf16_f32 v251, v131, v132
	v_mul_f32_e32 v96, 0xbfb8aa3b, v106
	v_exp_f32_e32 v96, v96
	v_mul_f32_e32 v110, 0xbfb8aa3b, v107
	v_exp_f32_e32 v110, v110
	v_mul_f32_e32 v111, 0xbfb8aa3b, v109
	v_add_f32_e32 v96, 1.0, v96
	v_rcp_f32_e32 v112, v96
	v_mul_f32_e32 v96, 0xbfb8aa3b, v108
	v_exp_f32_e32 v96, v96
	v_exp_f32_e32 v111, v111
	v_add_f32_e32 v110, 1.0, v110
	v_rcp_f32_e32 v113, v110
	v_add_f32_e32 v96, 1.0, v96
	v_rcp_f32_e32 v116, v96
	v_add_f32_e32 v96, 1.0, v111
	v_lshl_add_u64 v[110:111], s[54:55], 0, v[124:125]
	v_rcp_f32_e32 v117, v96
	v_lshl_add_u64 v[110:111], s[56:57], 1, v[110:111]
	v_lshlrev_b32_e32 v96, 1, v142
	v_lshl_add_u64 v[110:111], v[110:111], 0, v[96:97]
	v_cvt_pk_bf16_f32 v252, v112, v113
	v_cvt_pk_bf16_f32 v253, v116, v117
	global_store_dwordx4 v[110:111], v[250:253], off
	v_mul_f32_e32 v96, 0xbfb8aa3b, v102
	v_exp_f32_e32 v96, v96
	v_mul_f32_e32 v106, 0xbfb8aa3b, v103
	v_exp_f32_e32 v106, v106
	v_mul_f32_e32 v107, 0xbfb8aa3b, v105
	v_add_f32_e32 v96, 1.0, v96
	v_rcp_f32_e32 v108, v96
	v_mul_f32_e32 v96, 0xbfb8aa3b, v104
	v_exp_f32_e32 v96, v96
	v_exp_f32_e32 v107, v107
	v_add_f32_e32 v106, 1.0, v106
	v_rcp_f32_e32 v109, v106
	v_add_f32_e32 v96, 1.0, v96
	v_rcp_f32_e32 v112, v96
	v_add_f32_e32 v96, 1.0, v107
	v_rcp_f32_e32 v113, v96
	v_cvt_pk_bf16_f32 v190, v108, v109
	v_cvt_pk_bf16_f32 v191, v112, v113
	v_mul_f32_e32 v96, 0xbfb8aa3b, v98
	v_exp_f32_e32 v96, v96
	v_mul_f32_e32 v102, 0xbfb8aa3b, v99
	v_exp_f32_e32 v102, v102
	v_mul_f32_e32 v103, 0xbfb8aa3b, v101
; __device__ __forceinline__ float sigm(float x) { return __builtin_amdgcn_rcpf(1.f + __expf(-x)); }
; __device__ __forceinline__ void st_bf4(bf16_t* p, const f32x4 v) { u32x2 w; w.x = cvt_pk_bf16(v[0], v[1]); w.y = cvt_pk_bf16(v[2], v[3]); *(u32x2*)p = w; }
;     __device__ __forceinline__ void operator()(const f32x4 (&acc)[2][2][4][2], const Unit& u, int wr, int wc, int fr, int fq) const {
;     ...
;         for (int ai = 0; ai < 2; ++ai)
; #pragma unroll
;             for (int m = 0; m < 4; ++m) { const int row = u.pm * 256 + ai * 128 + wr * 64 + m * 16 + fr;
; #pragma unroll
;                 for (int bj = 0; bj < 2; ++bj)
; #pragma unroll
;                     for (int n = 0; n < 2; ++n) { const int tc = bj * 128 + wc * 32 + 8 * fq + 4 * n; f32x4 v = acc[ai][bj][m][n];
;     ...
;                         else { f32x4 s; s[0] = sigm(v[0]); s[1] = sigm(v[1]); s[2] = sigm(v[2]); s[3] = sigm(v[3]); st_bf4(GT + (size_t)row * 3072 + (pn - 7) * 256 + tc, s); }
	v_add_f32_e32 v96, 1.0, v96
	v_rcp_f32_e32 v104, v96
	v_mul_f32_e32 v96, 0xbfb8aa3b, v100
	v_exp_f32_e32 v96, v96
	v_exp_f32_e32 v103, v103
	v_add_f32_e32 v102, 1.0, v102
	v_rcp_f32_e32 v105, v102
	v_add_f32_e32 v96, 1.0, v96
	v_rcp_f32_e32 v106, v96
	v_add_f32_e32 v96, 1.0, v103
	v_lshl_add_u64 v[102:103], s[54:55], 0, v[124:125]
	v_rcp_f32_e32 v107, v96
	v_lshl_add_u64 v[102:103], s[56:57], 1, v[102:103]
	v_lshlrev_b32_e32 v96, 1, v142
	v_lshl_add_u64 v[102:103], v[102:103], 0, v[96:97]
	v_cvt_pk_bf16_f32 v192, v104, v105
	v_cvt_pk_bf16_f32 v193, v106, v107
	global_store_dwordx4 v[102:103], v[190:193], off offset:256
	s_mov_b64 s[70:71], 0
	s_andn2_b64 vcc, exec, s[70:71]
	v_or_b32_e32 v98, 32, v172
	v_mad_i64_i32 v[108:109], s[18:19], v98, s61, 0
	s_movk_i32 s18, 0x7ef
	s_nop 0
	v_bitop3_b32 v96, v172, s18, 32 bitop3:0xc8
	s_movk_i32 s18, 0x4000
	v_cmp_gt_i32_e32 vcc, s18, v98
	s_nop 1
	v_cndmask_b32_e32 v100, v151, v96, vcc
	v_add_u32_e32 v96, 0xfffff880, v96
	v_ashrrev_i32_e32 v99, 31, v98
	v_lshlrev_b32_e32 v119, 3, v100
	v_add_u32_e32 v100, 0xffffc020, v172
	v_lshlrev_b64 v[110:111], 7, v[96:97]
	s_mov_b64 s[70:71], 0x1080000
	v_lshlrev_b64 v[106:107], 11, v[98:99]
	v_lshlrev_b64 v[104:105], 8, v[98:99]
	v_lshrrev_b32_e32 v118, 2, v100
	v_lshl_add_u64 v[112:113], v[110:111], 0, s[70:71]
	v_mul_f32_e32 v96, 0xbfb8aa3b, v92
	v_exp_f32_e32 v96, v96
	v_mul_f32_e32 v98, 0xbfb8aa3b, v93
	v_exp_f32_e32 v98, v98
	v_mul_f32_e32 v99, 0xbfb8aa3b, v95
	v_add_f32_e32 v96, 1.0, v96
	v_rcp_f32_e32 v100, v96
	v_mul_f32_e32 v96, 0xbfb8aa3b, v94
	v_exp_f32_e32 v96, v96
	v_exp_f32_e32 v99, v99
	v_add_f32_e32 v98, 1.0, v98
	v_rcp_f32_e32 v101, v98
	v_add_f32_e32 v96, 1.0, v96
	v_rcp_f32_e32 v114, v96
	v_add_f32_e32 v96, 1.0, v99
	v_rcp_f32_e32 v115, v96
	v_cvt_pk_bf16_f32 v198, v100, v101
	v_cvt_pk_bf16_f32 v199, v114, v115
	v_mul_f32_e32 v92, 0xbfb8aa3b, v88
	v_exp_f32_e32 v92, v92
	v_mul_f32_e32 v93, 0xbfb8aa3b, v89
	v_mul_f32_e32 v95, 0xbfb8aa3b, v91
	v_exp_f32_e32 v93, v93
	v_add_f32_e32 v92, 1.0, v92
	v_rcp_f32_e32 v94, v92
	v_mul_f32_e32 v92, 0xbfb8aa3b, v90
	v_exp_f32_e32 v92, v92
	v_exp_f32_e32 v95, v95
	v_add_f32_e32 v93, 1.0, v93
	v_rcp_f32_e32 v100, v93
	v_add_f32_e32 v92, 1.0, v92
	v_rcp_f32_e32 v101, v92
	v_add_f32_e32 v92, 1.0, v95
	v_rcp_f32_e32 v95, v92
	v_lshl_add_u64 v[92:93], s[54:55], 0, v[108:109]
	v_lshl_add_u64 v[92:93], s[56:57], 1, v[92:93]
	v_lshlrev_b32_e32 v96, 1, v142
	v_lshl_add_u64 v[92:93], v[92:93], 0, v[96:97]
	v_cvt_pk_bf16_f32 v200, v94, v100
	v_cvt_pk_bf16_f32 v201, v101, v95
	global_store_dwordx4 v[92:93], v[198:201], off
	v_mul_f32_e32 v88, 0xbfb8aa3b, v84
	v_exp_f32_e32 v88, v88
	v_mul_f32_e32 v89, 0xbfb8aa3b, v85
	v_mul_f32_e32 v91, 0xbfb8aa3b, v87
	v_exp_f32_e32 v89, v89
	v_add_f32_e32 v88, 1.0, v88
	v_rcp_f32_e32 v90, v88
	v_mul_f32_e32 v88, 0xbfb8aa3b, v86
	v_exp_f32_e32 v88, v88
	v_exp_f32_e32 v91, v91
	v_add_f32_e32 v89, 1.0, v89
	v_rcp_f32_e32 v94, v89
	v_add_f32_e32 v88, 1.0, v88
	v_rcp_f32_e32 v95, v88
	v_add_f32_e32 v88, 1.0, v91
	v_rcp_f32_e32 v91, v88
	v_cvt_pk_bf16_f32 v250, v90, v94
	v_cvt_pk_bf16_f32 v251, v95, v91
	v_mul_f32_e32 v84, 0xbfb8aa3b, v80
	v_exp_f32_e32 v84, v84
	v_mul_f32_e32 v85, 0xbfb8aa3b, v81
	v_mul_f32_e32 v87, 0xbfb8aa3b, v83
	v_exp_f32_e32 v85, v85
	v_add_f32_e32 v84, 1.0, v84
	v_rcp_f32_e32 v86, v84
	v_mul_f32_e32 v84, 0xbfb8aa3b, v82
	v_exp_f32_e32 v84, v84
	v_exp_f32_e32 v87, v87
	v_add_f32_e32 v85, 1.0, v85
	v_rcp_f32_e32 v88, v85
	v_add_f32_e32 v84, 1.0, v84
	v_rcp_f32_e32 v89, v84
	v_add_f32_e32 v84, 1.0, v87
	v_rcp_f32_e32 v87, v84
	v_lshl_add_u64 v[84:85], s[54:55], 0, v[108:109]
	v_lshl_add_u64 v[84:85], s[56:57], 1, v[84:85]
	v_lshlrev_b32_e32 v96, 1, v142
	v_lshl_add_u64 v[84:85], v[84:85], 0, v[96:97]
	v_cvt_pk_bf16_f32 v252, v86, v88
	v_cvt_pk_bf16_f32 v253, v89, v87
	global_store_dwordx4 v[84:85], v[250:253], off offset:256
	s_mov_b64 s[70:71], 0
	s_andn2_b64 vcc, exec, s[70:71]
	v_or_b32_e32 v80, 48, v172
	v_mad_i64_i32 v[90:91], s[18:19], v80, s61, 0
	s_movk_i32 s18, 0x7ff
	s_nop 0
	v_bitop3_b32 v82, v172, s18, 48 bitop3:0xc8
	s_movk_i32 s18, 0x4000
	v_cmp_gt_i32_e32 vcc, s18, v80
	v_add_u32_e32 v96, 0xfffff880, v82
	v_ashrrev_i32_e32 v81, 31, v80
	v_cndmask_b32_e32 v83, v151, v82, vcc
	v_lshlrev_b32_e32 v103, 3, v83
	v_add_u32_e32 v83, 0xffffc030, v172
	v_lshlrev_b64 v[92:93], 7, v[96:97]
	s_mov_b64 s[70:71], 0x1080000
	v_lshlrev_b64 v[88:89], 11, v[80:81]
	v_lshrrev_b32_e32 v102, 2, v83
	v_lshlrev_b64 v[84:85], 10, v[80:81]
	v_lshl_add_u64 v[94:95], v[92:93], 0, s[70:71]
	v_mul_f32_e32 v80, 0xbfb8aa3b, v76
	v_exp_f32_e32 v80, v80
	v_mul_f32_e32 v81, 0xbfb8aa3b, v77
	v_mul_f32_e32 v83, 0xbfb8aa3b, v79
	v_exp_f32_e32 v81, v81
	v_add_f32_e32 v80, 1.0, v80
	v_rcp_f32_e32 v82, v80
	v_mul_f32_e32 v80, 0xbfb8aa3b, v78
	v_exp_f32_e32 v80, v80
	v_exp_f32_e32 v83, v83
	v_add_f32_e32 v81, 1.0, v81
	v_rcp_f32_e32 v98, v81
	v_add_f32_e32 v80, 1.0, v80
	v_rcp_f32_e32 v99, v80
	v_add_f32_e32 v80, 1.0, v83
	v_rcp_f32_e32 v83, v80
	v_cvt_pk_bf16_f32 v190, v82, v98
	v_cvt_pk_bf16_f32 v191, v99, v83
	v_mul_f32_e32 v76, 0xbfb8aa3b, v72
	v_exp_f32_e32 v76, v76
	v_mul_f32_e32 v77, 0xbfb8aa3b, v73
	v_mul_f32_e32 v79, 0xbfb8aa3b, v75
	v_exp_f32_e32 v77, v77
	v_add_f32_e32 v76, 1.0, v76
	v_rcp_f32_e32 v78, v76
	v_mul_f32_e32 v76, 0xbfb8aa3b, v74
	v_exp_f32_e32 v76, v76
	v_exp_f32_e32 v79, v79
	v_add_f32_e32 v77, 1.0, v77
	v_rcp_f32_e32 v82, v77
	v_add_f32_e32 v76, 1.0, v76
	v_rcp_f32_e32 v83, v76
	v_add_f32_e32 v76, 1.0, v79
	v_rcp_f32_e32 v79, v76
	v_lshl_add_u64 v[76:77], s[54:55], 0, v[90:91]
	v_lshl_add_u64 v[76:77], s[56:57], 1, v[76:77]
	v_lshlrev_b32_e32 v96, 1, v142
; __device__ __forceinline__ float sigm(float x) { return __builtin_amdgcn_rcpf(1.f + __expf(-x)); }
; __device__ __forceinline__ void st_bf4(bf16_t* p, const f32x4 v) { u32x2 w; w.x = cvt_pk_bf16(v[0], v[1]); w.y = cvt_pk_bf16(v[2], v[3]); *(u32x2*)p = w; }
;     __device__ __forceinline__ void operator()(const f32x4 (&acc)[2][2][4][2], const Unit& u, int wr, int wc, int fr, int fq) const {
;     ...
;         for (int ai = 0; ai < 2; ++ai)
; #pragma unroll
;             for (int m = 0; m < 4; ++m) { const int row = u.pm * 256 + ai * 128 + wr * 64 + m * 16 + fr;
; #pragma unroll
;                 for (int bj = 0; bj < 2; ++bj)
; #pragma unroll
;                     for (int n = 0; n < 2; ++n) { const int tc = bj * 128 + wc * 32 + 8 * fq + 4 * n; f32x4 v = acc[ai][bj][m][n];
;     ...
;                         else { f32x4 s; s[0] = sigm(v[0]); s[1] = sigm(v[1]); s[2] = sigm(v[2]); s[3] = sigm(v[3]); st_bf4(GT + (size_t)row * 3072 + (pn - 7) * 256 + tc, s); }
	v_lshl_add_u64 v[76:77], v[76:77], 0, v[96:97]
	v_cvt_pk_bf16_f32 v192, v78, v82
	v_cvt_pk_bf16_f32 v193, v83, v79
	global_store_dwordx4 v[76:77], v[190:193], off
	v_mul_f32_e32 v72, 0xbfb8aa3b, v68
	v_exp_f32_e32 v72, v72
	v_mul_f32_e32 v73, 0xbfb8aa3b, v69
	v_mul_f32_e32 v75, 0xbfb8aa3b, v71
	v_exp_f32_e32 v73, v73
	v_add_f32_e32 v72, 1.0, v72
	v_rcp_f32_e32 v74, v72
	v_mul_f32_e32 v72, 0xbfb8aa3b, v70
	v_exp_f32_e32 v72, v72
	v_exp_f32_e32 v75, v75
	v_add_f32_e32 v73, 1.0, v73
	v_rcp_f32_e32 v78, v73
	v_add_f32_e32 v72, 1.0, v72
	v_rcp_f32_e32 v79, v72
	v_add_f32_e32 v72, 1.0, v75
	v_rcp_f32_e32 v75, v72
	v_cvt_pk_bf16_f32 v198, v74, v78
	v_cvt_pk_bf16_f32 v199, v79, v75
	v_mul_f32_e32 v68, 0xbfb8aa3b, v64
	v_exp_f32_e32 v68, v68
	v_mul_f32_e32 v69, 0xbfb8aa3b, v65
	v_mul_f32_e32 v71, 0xbfb8aa3b, v67
	v_exp_f32_e32 v69, v69
	v_add_f32_e32 v68, 1.0, v68
	v_rcp_f32_e32 v70, v68
	v_mul_f32_e32 v68, 0xbfb8aa3b, v66
	v_exp_f32_e32 v68, v68
	v_exp_f32_e32 v71, v71
	v_add_f32_e32 v69, 1.0, v69
	v_rcp_f32_e32 v72, v69
	v_add_f32_e32 v68, 1.0, v68
	v_rcp_f32_e32 v73, v68
	v_add_f32_e32 v68, 1.0, v71
	v_rcp_f32_e32 v71, v68
	v_lshl_add_u64 v[68:69], s[54:55], 0, v[90:91]
	v_lshl_add_u64 v[68:69], s[56:57], 1, v[68:69]
	v_lshlrev_b32_e32 v96, 1, v142
	v_lshl_add_u64 v[68:69], v[68:69], 0, v[96:97]
	v_cvt_pk_bf16_f32 v200, v70, v72
	v_cvt_pk_bf16_f32 v201, v73, v71
	global_store_dwordx4 v[68:69], v[198:201], off offset:256
	s_mov_b64 s[70:71], 0
	s_andn2_b64 vcc, exec, s[70:71]
	s_add_i32 s46, s53, 0x80
	v_or_b32_e32 v68, s46, v143
	v_mad_i64_i32 v[76:77], s[18:19], v68, s61, 0
	v_mov_b32_e32 v64, 0x7cf
	s_movk_i32 s18, 0x4000
	v_bitop3_b32 v64, s46, v64, v143 bitop3:0xc8
	v_cmp_gt_i32_e32 vcc, s18, v68
	v_add_u32_e32 v96, 0xfffff880, v64
	v_ashrrev_i32_e32 v69, 31, v68
	v_cndmask_b32_e32 v65, v151, v64, vcc
	v_lshlrev_b32_e32 v87, 3, v65
	v_add_u32_e32 v65, 0xffffc000, v68
	v_lshlrev_b64 v[78:79], 7, v[96:97]
	s_mov_b64 s[70:71], 0x1080000
	v_lshlrev_b64 v[74:75], 11, v[68:69]
	v_lshlrev_b64 v[72:73], 8, v[68:69]
	v_lshrrev_b32_e32 v86, 2, v65
	v_lshlrev_b64 v[70:71], 10, v[68:69]
	v_lshl_add_u64 v[80:81], v[78:79], 0, s[70:71]
	s_mov_b32 s75, 0x400000
	v_mul_f32_e32 v64, 0xbfb8aa3b, v60
	v_exp_f32_e32 v64, v64
	v_mul_f32_e32 v65, 0xbfb8aa3b, v61
	v_mul_f32_e32 v67, 0xbfb8aa3b, v63
	v_exp_f32_e32 v65, v65
	v_add_f32_e32 v64, 1.0, v64
	v_rcp_f32_e32 v66, v64
	v_mul_f32_e32 v64, 0xbfb8aa3b, v62
	v_exp_f32_e32 v64, v64
	v_exp_f32_e32 v67, v67
	v_add_f32_e32 v65, 1.0, v65
	v_rcp_f32_e32 v69, v65
	v_add_f32_e32 v64, 1.0, v64
	v_rcp_f32_e32 v82, v64
	v_add_f32_e32 v64, 1.0, v67
	v_rcp_f32_e32 v67, v64
	v_cvt_pk_bf16_f32 v250, v66, v69
	v_cvt_pk_bf16_f32 v251, v82, v67
	v_mul_f32_e32 v60, 0xbfb8aa3b, v56
	v_exp_f32_e32 v60, v60
	v_mul_f32_e32 v61, 0xbfb8aa3b, v57
	v_mul_f32_e32 v63, 0xbfb8aa3b, v59
	v_exp_f32_e32 v61, v61
	v_add_f32_e32 v60, 1.0, v60
	v_rcp_f32_e32 v62, v60
	v_mul_f32_e32 v60, 0xbfb8aa3b, v58
	v_exp_f32_e32 v60, v60
	v_exp_f32_e32 v63, v63
	v_add_f32_e32 v61, 1.0, v61
	v_rcp_f32_e32 v66, v61
	v_add_f32_e32 v60, 1.0, v60
	v_rcp_f32_e32 v67, v60
	v_add_f32_e32 v60, 1.0, v63
	v_rcp_f32_e32 v63, v60
	v_lshl_add_u64 v[60:61], s[54:55], 0, v[76:77]
	v_lshl_add_u64 v[60:61], s[56:57], 1, v[60:61]
	v_lshlrev_b32_e32 v96, 1, v142
	v_lshl_add_u64 v[60:61], v[60:61], 0, v[96:97]
	v_cvt_pk_bf16_f32 v252, v62, v66
	v_cvt_pk_bf16_f32 v253, v67, v63
	global_store_dwordx4 v[60:61], v[250:253], off
	v_mul_f32_e32 v56, 0xbfb8aa3b, v52
	v_exp_f32_e32 v56, v56
	v_mul_f32_e32 v57, 0xbfb8aa3b, v53
	v_mul_f32_e32 v59, 0xbfb8aa3b, v55
	v_exp_f32_e32 v57, v57
	v_add_f32_e32 v56, 1.0, v56
	v_rcp_f32_e32 v58, v56
	v_mul_f32_e32 v56, 0xbfb8aa3b, v54
	v_exp_f32_e32 v56, v56
	v_exp_f32_e32 v59, v59
	v_add_f32_e32 v57, 1.0, v57
	v_rcp_f32_e32 v62, v57
	v_add_f32_e32 v56, 1.0, v56
	v_rcp_f32_e32 v63, v56
	v_add_f32_e32 v56, 1.0, v59
	v_rcp_f32_e32 v59, v56
	v_cvt_pk_bf16_f32 v190, v58, v62
	v_cvt_pk_bf16_f32 v191, v63, v59
	v_mul_f32_e32 v52, 0xbfb8aa3b, v48
	v_exp_f32_e32 v52, v52
	v_mul_f32_e32 v53, 0xbfb8aa3b, v49
	v_mul_f32_e32 v55, 0xbfb8aa3b, v51
	v_exp_f32_e32 v53, v53
	v_add_f32_e32 v52, 1.0, v52
	v_rcp_f32_e32 v54, v52
	v_mul_f32_e32 v52, 0xbfb8aa3b, v50
	v_exp_f32_e32 v52, v52
	v_exp_f32_e32 v55, v55
	v_add_f32_e32 v53, 1.0, v53
	v_rcp_f32_e32 v56, v53
	v_add_f32_e32 v52, 1.0, v52
	v_rcp_f32_e32 v57, v52
	v_add_f32_e32 v52, 1.0, v55
	v_rcp_f32_e32 v55, v52
	v_lshl_add_u64 v[52:53], s[54:55], 0, v[76:77]
	v_lshl_add_u64 v[52:53], s[56:57], 1, v[52:53]
	v_lshlrev_b32_e32 v96, 1, v142
	v_lshl_add_u64 v[52:53], v[52:53], 0, v[96:97]
	v_cvt_pk_bf16_f32 v192, v54, v56
	v_cvt_pk_bf16_f32 v193, v57, v55
	global_store_dwordx4 v[52:53], v[190:193], off offset:256
	s_mov_b64 s[70:71], 0
	s_andn2_b64 vcc, exec, s[70:71]
	v_or_b32_e32 v48, 16, v68
	v_mad_i64_i32 v[58:59], s[18:19], v48, s61, 0
	s_movk_i32 s18, 0x7df
	s_nop 0
	v_bitop3_b32 v50, v68, s18, 16 bitop3:0xc8
	s_movk_i32 s18, 0x4000
	v_cmp_gt_i32_e32 vcc, s18, v48
	v_add_u32_e32 v96, 0xfffff880, v50
	v_ashrrev_i32_e32 v49, 31, v48
	v_cndmask_b32_e32 v51, v151, v50, vcc
	v_lshlrev_b32_e32 v70, 3, v51
	v_add_u32_e32 v51, 0xffffc010, v68
	v_lshlrev_b64 v[60:61], 7, v[96:97]
	s_mov_b64 s[70:71], 0x1080000
	v_lshlrev_b64 v[56:57], 11, v[48:49]
	v_lshlrev_b64 v[54:55], 8, v[48:49]
	v_lshrrev_b32_e32 v69, 2, v51
	v_lshl_add_u64 v[62:63], v[60:61], 0, s[70:71]
	v_mul_f32_e32 v48, 0xbfb8aa3b, v44
	v_exp_f32_e32 v48, v48
	v_mul_f32_e32 v49, 0xbfb8aa3b, v45
	v_mul_f32_e32 v51, 0xbfb8aa3b, v47
	v_exp_f32_e32 v49, v49
	v_add_f32_e32 v48, 1.0, v48
	v_rcp_f32_e32 v50, v48
	v_mul_f32_e32 v48, 0xbfb8aa3b, v46
	v_exp_f32_e32 v48, v48
; __device__ __forceinline__ float sigm(float x) { return __builtin_amdgcn_rcpf(1.f + __expf(-x)); }
; __device__ __forceinline__ void st_bf4(bf16_t* p, const f32x4 v) { u32x2 w; w.x = cvt_pk_bf16(v[0], v[1]); w.y = cvt_pk_bf16(v[2], v[3]); *(u32x2*)p = w; }
;     __device__ __forceinline__ void operator()(const f32x4 (&acc)[2][2][4][2], const Unit& u, int wr, int wc, int fr, int fq) const {
;     ...
;         for (int ai = 0; ai < 2; ++ai)
; #pragma unroll
;             for (int m = 0; m < 4; ++m) { const int row = u.pm * 256 + ai * 128 + wr * 64 + m * 16 + fr;
; #pragma unroll
;                 for (int bj = 0; bj < 2; ++bj)
; #pragma unroll
;                     for (int n = 0; n < 2; ++n) { const int tc = bj * 128 + wc * 32 + 8 * fq + 4 * n; f32x4 v = acc[ai][bj][m][n];
;     ...
;                         else { f32x4 s; s[0] = sigm(v[0]); s[1] = sigm(v[1]); s[2] = sigm(v[2]); s[3] = sigm(v[3]); st_bf4(GT + (size_t)row * 3072 + (pn - 7) * 256 + tc, s); }
	v_exp_f32_e32 v51, v51
	v_add_f32_e32 v49, 1.0, v49
	v_rcp_f32_e32 v64, v49
	v_add_f32_e32 v48, 1.0, v48
	v_rcp_f32_e32 v65, v48
	v_add_f32_e32 v48, 1.0, v51
	v_rcp_f32_e32 v51, v48
	v_cvt_pk_bf16_f32 v198, v50, v64
	v_cvt_pk_bf16_f32 v199, v65, v51
	v_mul_f32_e32 v44, 0xbfb8aa3b, v40
	v_exp_f32_e32 v44, v44
	v_mul_f32_e32 v45, 0xbfb8aa3b, v41
	v_mul_f32_e32 v47, 0xbfb8aa3b, v43
	v_exp_f32_e32 v45, v45
	v_add_f32_e32 v44, 1.0, v44
	v_rcp_f32_e32 v46, v44
	v_mul_f32_e32 v44, 0xbfb8aa3b, v42
	v_exp_f32_e32 v44, v44
	v_exp_f32_e32 v47, v47
	v_add_f32_e32 v45, 1.0, v45
	v_rcp_f32_e32 v50, v45
	v_add_f32_e32 v44, 1.0, v44
	v_rcp_f32_e32 v51, v44
	v_add_f32_e32 v44, 1.0, v47
	v_rcp_f32_e32 v47, v44
	v_lshl_add_u64 v[44:45], s[54:55], 0, v[58:59]
	v_lshl_add_u64 v[44:45], s[56:57], 1, v[44:45]
	v_lshlrev_b32_e32 v96, 1, v142
	v_lshl_add_u64 v[44:45], v[44:45], 0, v[96:97]
	v_cvt_pk_bf16_f32 v200, v46, v50
	v_cvt_pk_bf16_f32 v201, v51, v47
	global_store_dwordx4 v[44:45], v[198:201], off
	v_mul_f32_e32 v40, 0xbfb8aa3b, v36
	v_exp_f32_e32 v40, v40
	v_mul_f32_e32 v41, 0xbfb8aa3b, v37
	v_mul_f32_e32 v43, 0xbfb8aa3b, v39
	v_exp_f32_e32 v41, v41
	v_add_f32_e32 v40, 1.0, v40
	v_rcp_f32_e32 v42, v40
	v_mul_f32_e32 v40, 0xbfb8aa3b, v38
	v_exp_f32_e32 v40, v40
	v_exp_f32_e32 v43, v43
	v_add_f32_e32 v41, 1.0, v41
	v_rcp_f32_e32 v46, v41
	v_add_f32_e32 v40, 1.0, v40
	v_rcp_f32_e32 v47, v40
	v_add_f32_e32 v40, 1.0, v43
	v_rcp_f32_e32 v43, v40
	v_cvt_pk_bf16_f32 v250, v42, v46
	v_cvt_pk_bf16_f32 v251, v47, v43
	v_mul_f32_e32 v36, 0xbfb8aa3b, v32
	v_exp_f32_e32 v36, v36
	v_mul_f32_e32 v37, 0xbfb8aa3b, v33
	v_mul_f32_e32 v39, 0xbfb8aa3b, v35
	v_exp_f32_e32 v37, v37
	v_add_f32_e32 v36, 1.0, v36
	v_rcp_f32_e32 v38, v36
	v_mul_f32_e32 v36, 0xbfb8aa3b, v34
	v_exp_f32_e32 v36, v36
	v_exp_f32_e32 v39, v39
	v_add_f32_e32 v37, 1.0, v37
	v_rcp_f32_e32 v40, v37
	v_add_f32_e32 v36, 1.0, v36
	v_rcp_f32_e32 v41, v36
	v_add_f32_e32 v36, 1.0, v39
	v_rcp_f32_e32 v39, v36
	v_lshl_add_u64 v[36:37], s[54:55], 0, v[58:59]
	v_lshl_add_u64 v[36:37], s[56:57], 1, v[36:37]
	v_lshlrev_b32_e32 v96, 1, v142
	v_lshl_add_u64 v[36:37], v[36:37], 0, v[96:97]
	v_cvt_pk_bf16_f32 v252, v38, v40
	v_cvt_pk_bf16_f32 v253, v41, v39
	global_store_dwordx4 v[36:37], v[250:253], off offset:256
	s_mov_b64 s[70:71], 0
	s_andn2_b64 vcc, exec, s[70:71]
	v_or_b32_e32 v32, 32, v68
	v_mad_i64_i32 v[42:43], s[18:19], v32, s61, 0
	s_movk_i32 s18, 0x7ef
	s_nop 0
	v_bitop3_b32 v34, v68, s18, 32 bitop3:0xc8
	s_movk_i32 s18, 0x4000
	v_cmp_gt_i32_e32 vcc, s18, v32
	v_add_u32_e32 v96, 0xfffff880, v34
	v_ashrrev_i32_e32 v33, 31, v32
	v_cndmask_b32_e32 v35, v151, v34, vcc
	v_lshlrev_b32_e32 v53, 3, v35
	v_add_u32_e32 v35, 0xffffc020, v68
	v_lshlrev_b64 v[44:45], 7, v[96:97]
	s_mov_b64 s[70:71], 0x1080000
	v_lshlrev_b64 v[40:41], 11, v[32:33]
	v_lshlrev_b64 v[38:39], 8, v[32:33]
	v_lshrrev_b32_e32 v52, 2, v35
	v_lshl_add_u64 v[46:47], v[44:45], 0, s[70:71]
	v_mul_f32_e32 v32, 0xbfb8aa3b, v28
	v_exp_f32_e32 v32, v32
	v_mul_f32_e32 v33, 0xbfb8aa3b, v29
	v_mul_f32_e32 v35, 0xbfb8aa3b, v31
	v_exp_f32_e32 v33, v33
	v_add_f32_e32 v32, 1.0, v32
	v_rcp_f32_e32 v34, v32
	v_mul_f32_e32 v32, 0xbfb8aa3b, v30
	v_exp_f32_e32 v32, v32
	v_exp_f32_e32 v35, v35
	v_add_f32_e32 v33, 1.0, v33
	v_rcp_f32_e32 v48, v33
	v_add_f32_e32 v32, 1.0, v32
	v_rcp_f32_e32 v49, v32
	v_add_f32_e32 v32, 1.0, v35
	v_rcp_f32_e32 v35, v32
	v_cvt_pk_bf16_f32 v190, v34, v48
	v_cvt_pk_bf16_f32 v191, v49, v35
	v_mul_f32_e32 v28, 0xbfb8aa3b, v24
	v_exp_f32_e32 v28, v28
	v_mul_f32_e32 v29, 0xbfb8aa3b, v25
	v_mul_f32_e32 v31, 0xbfb8aa3b, v27
	v_exp_f32_e32 v29, v29
	v_add_f32_e32 v28, 1.0, v28
	v_rcp_f32_e32 v30, v28
	v_mul_f32_e32 v28, 0xbfb8aa3b, v26
	v_exp_f32_e32 v28, v28
	v_exp_f32_e32 v31, v31
	v_add_f32_e32 v29, 1.0, v29
	v_rcp_f32_e32 v34, v29
	v_add_f32_e32 v28, 1.0, v28
	v_rcp_f32_e32 v35, v28
	v_add_f32_e32 v28, 1.0, v31
	v_rcp_f32_e32 v31, v28
	v_lshl_add_u64 v[28:29], s[54:55], 0, v[42:43]
	v_lshl_add_u64 v[28:29], s[56:57], 1, v[28:29]
	v_lshlrev_b32_e32 v96, 1, v142
	v_lshl_add_u64 v[28:29], v[28:29], 0, v[96:97]
	v_cvt_pk_bf16_f32 v192, v30, v34
	v_cvt_pk_bf16_f32 v193, v35, v31
	global_store_dwordx4 v[28:29], v[190:193], off
	v_mul_f32_e32 v24, 0xbfb8aa3b, v20
	v_exp_f32_e32 v24, v24
	v_mul_f32_e32 v25, 0xbfb8aa3b, v21
	v_mul_f32_e32 v27, 0xbfb8aa3b, v23
	v_exp_f32_e32 v25, v25
	v_add_f32_e32 v24, 1.0, v24
	v_rcp_f32_e32 v26, v24
	v_mul_f32_e32 v24, 0xbfb8aa3b, v22
	v_exp_f32_e32 v24, v24
	v_exp_f32_e32 v27, v27
	v_add_f32_e32 v25, 1.0, v25
	v_rcp_f32_e32 v30, v25
	v_add_f32_e32 v24, 1.0, v24
	v_rcp_f32_e32 v31, v24
	v_add_f32_e32 v24, 1.0, v27
	v_rcp_f32_e32 v27, v24
	v_cvt_pk_bf16_f32 v198, v26, v30
	v_cvt_pk_bf16_f32 v199, v31, v27
	v_mul_f32_e32 v20, 0xbfb8aa3b, v16
	v_exp_f32_e32 v20, v20
	v_mul_f32_e32 v21, 0xbfb8aa3b, v17
	v_mul_f32_e32 v23, 0xbfb8aa3b, v19
	v_exp_f32_e32 v21, v21
	v_add_f32_e32 v20, 1.0, v20
	v_rcp_f32_e32 v22, v20
	v_mul_f32_e32 v20, 0xbfb8aa3b, v18
	v_exp_f32_e32 v20, v20
	v_exp_f32_e32 v23, v23
	v_add_f32_e32 v21, 1.0, v21
	v_rcp_f32_e32 v24, v21
	v_add_f32_e32 v20, 1.0, v20
	v_rcp_f32_e32 v25, v20
	v_add_f32_e32 v20, 1.0, v23
	v_rcp_f32_e32 v23, v20
	v_lshl_add_u64 v[20:21], s[54:55], 0, v[42:43]
	v_lshl_add_u64 v[20:21], s[56:57], 1, v[20:21]
	v_lshlrev_b32_e32 v96, 1, v142
	v_lshl_add_u64 v[20:21], v[20:21], 0, v[96:97]
	v_cvt_pk_bf16_f32 v200, v22, v24
	v_cvt_pk_bf16_f32 v201, v25, v23
	global_store_dwordx4 v[20:21], v[198:201], off offset:256
	s_mov_b64 s[70:71], 0
	s_andn2_b64 vcc, exec, s[70:71]
	v_or_b32_e32 v16, 48, v68
	v_mad_i64_i32 v[26:27], s[18:19], v16, s61, 0
	s_movk_i32 s18, 0x3fff
	s_nop 0
; __device__ __forceinline__ float sigm(float x) { return __builtin_amdgcn_rcpf(1.f + __expf(-x)); }
; __device__ __forceinline__ void st_bf4(bf16_t* p, const f32x4 v) { u32x2 w; w.x = cvt_pk_bf16(v[0], v[1]); w.y = cvt_pk_bf16(v[2], v[3]); *(u32x2*)p = w; }
;     __device__ __forceinline__ void operator()(const f32x4 (&acc)[2][2][4][2], const Unit& u, int wr, int wc, int fr, int fq) const {
;     ...
;         for (int ai = 0; ai < 2; ++ai)
; #pragma unroll
;             for (int m = 0; m < 4; ++m) { const int row = u.pm * 256 + ai * 128 + wr * 64 + m * 16 + fr;
; #pragma unroll
;                 for (int bj = 0; bj < 2; ++bj)
; #pragma unroll
;                     for (int n = 0; n < 2; ++n) { const int tc = bj * 128 + wc * 32 + 8 * fq + 4 * n; f32x4 v = acc[ai][bj][m][n];
;     ...
;                         else if (pn < 7) { *(f32x4*)(U + (size_t)row * 512 + (pn - 5) * 256 + tc) = v; }
;                         else { f32x4 s; s[0] = sigm(v[0]); s[1] = sigm(v[1]); s[2] = sigm(v[2]); s[3] = sigm(v[3]); st_bf4(GT + (size_t)row * 3072 + (pn - 7) * 256 + tc, s); }
	v_cmp_lt_i32_e64 s[20:21], s18, v16
	s_movk_i32 s18, 0x7ff
	v_bitop3_b32 v18, v68, s18, 48 bitop3:0xc8
	s_movk_i32 s18, 0x4000
	v_cmp_gt_i32_e32 vcc, s18, v16
	v_add_u32_e32 v96, 0xfffff880, v18
	v_ashrrev_i32_e32 v17, 31, v16
	v_cndmask_b32_e32 v19, v151, v18, vcc
	v_lshlrev_b32_e32 v37, 3, v19
	v_add_u32_e32 v19, 0xffffc030, v68
	v_lshlrev_b64 v[28:29], 7, v[96:97]
	s_mov_b64 s[70:71], 0x1080000
	v_lshlrev_b64 v[24:25], 11, v[16:17]
	v_lshlrev_b64 v[22:23], 8, v[16:17]
	v_lshrrev_b32_e32 v36, 2, v19
	v_lshlrev_b64 v[20:21], 10, v[16:17]
	v_lshl_add_u64 v[30:31], v[28:29], 0, s[70:71]
	v_mul_f32_e32 v16, 0xbfb8aa3b, v12
	v_exp_f32_e32 v16, v16
	v_mul_f32_e32 v17, 0xbfb8aa3b, v13
	v_mul_f32_e32 v19, 0xbfb8aa3b, v15
	v_exp_f32_e32 v17, v17
	v_add_f32_e32 v16, 1.0, v16
	v_rcp_f32_e32 v18, v16
	v_mul_f32_e32 v16, 0xbfb8aa3b, v14
	v_exp_f32_e32 v16, v16
	v_exp_f32_e32 v19, v19
	v_add_f32_e32 v17, 1.0, v17
	v_rcp_f32_e32 v32, v17
	v_add_f32_e32 v16, 1.0, v16
	v_rcp_f32_e32 v33, v16
	v_add_f32_e32 v16, 1.0, v19
	v_rcp_f32_e32 v19, v16
	v_cvt_pk_bf16_f32 v250, v18, v32
	v_cvt_pk_bf16_f32 v251, v33, v19
	v_lshl_add_u64 v[16:17], s[30:31], 0, v[24:25]
	v_lshl_add_u64 v[16:17], s[92:93], 2, v[16:17]
	v_mul_f32_e32 v12, 0xbfb8aa3b, v8
	v_exp_f32_e32 v12, v12
	v_mul_f32_e32 v13, 0xbfb8aa3b, v9
	v_mul_f32_e32 v15, 0xbfb8aa3b, v11
	v_exp_f32_e32 v13, v13
	v_add_f32_e32 v12, 1.0, v12
	v_rcp_f32_e32 v14, v12
	v_mul_f32_e32 v12, 0xbfb8aa3b, v10
	v_exp_f32_e32 v12, v12
	v_exp_f32_e32 v15, v15
	v_add_f32_e32 v13, 1.0, v13
	v_rcp_f32_e32 v18, v13
	v_add_f32_e32 v12, 1.0, v12
	v_rcp_f32_e32 v19, v12
	v_add_f32_e32 v12, 1.0, v15
	v_rcp_f32_e32 v15, v12
	v_lshl_add_u64 v[12:13], s[54:55], 0, v[26:27]
	v_lshl_add_u64 v[12:13], s[56:57], 1, v[12:13]
	v_lshlrev_b32_e32 v96, 1, v142
	v_lshl_add_u64 v[12:13], v[12:13], 0, v[96:97]
	v_cvt_pk_bf16_f32 v252, v14, v18
	v_cvt_pk_bf16_f32 v253, v19, v15
	global_store_dwordx4 v[12:13], v[250:253], off
	s_mov_b64 s[70:71], 0x1100000
	s_nop 0
	v_lshl_add_u64 v[12:13], v[28:29], 0, s[70:71]
	v_mul_f32_e32 v8, 0xbfb8aa3b, v4
	v_exp_f32_e32 v8, v8
	v_mul_f32_e32 v9, 0xbfb8aa3b, v5
	v_mul_f32_e32 v11, 0xbfb8aa3b, v7
	v_exp_f32_e32 v9, v9
	v_add_f32_e32 v8, 1.0, v8
	v_rcp_f32_e32 v10, v8
	v_mul_f32_e32 v8, 0xbfb8aa3b, v6
	v_exp_f32_e32 v8, v8
	v_exp_f32_e32 v11, v11
	v_add_f32_e32 v9, 1.0, v9
	v_rcp_f32_e32 v14, v9
	v_add_f32_e32 v8, 1.0, v8
	v_rcp_f32_e32 v15, v8
	v_add_f32_e32 v8, 1.0, v11
	v_rcp_f32_e32 v11, v8
	v_cvt_pk_bf16_f32 v190, v10, v14
	v_cvt_pk_bf16_f32 v191, v15, v11
	s_mov_b32 s70, 0x1200000
	s_mov_b32 s71, 0x1400000
	v_mul_f32_e32 v4, 0xbfb8aa3b, v0
	v_exp_f32_e32 v4, v4
	v_mul_f32_e32 v5, 0xbfb8aa3b, v1
	v_mul_f32_e32 v7, 0xbfb8aa3b, v3
	v_exp_f32_e32 v5, v5
	v_add_f32_e32 v4, 1.0, v4
	v_rcp_f32_e32 v6, v4
	v_mul_f32_e32 v4, 0xbfb8aa3b, v2
	v_exp_f32_e32 v4, v4
	v_exp_f32_e32 v7, v7
	v_add_f32_e32 v5, 1.0, v5
	v_rcp_f32_e32 v8, v5
	v_add_f32_e32 v4, 1.0, v4
	v_rcp_f32_e32 v9, v4
	v_add_f32_e32 v4, 1.0, v7
	v_rcp_f32_e32 v7, v4
	v_lshl_add_u64 v[4:5], s[54:55], 0, v[26:27]
	v_lshl_add_u64 v[4:5], s[56:57], 1, v[4:5]
	v_lshlrev_b32_e32 v96, 1, v142
	v_lshl_add_u64 v[4:5], v[4:5], 0, v[96:97]
	v_cvt_pk_bf16_f32 v192, v6, v8
	v_cvt_pk_bf16_f32 v193, v9, v7
	global_store_dwordx4 v[4:5], v[190:193], off offset:256
	s_mov_b64 s[14:15], 0
	s_branch .LBB0_1574
.Lsp_u:
	s_nop 7
	v_lshl_add_u64 v[130:131], s[72:73], 0, v[178:179]
	v_lshl_add_u64 v[130:131], s[0:1], 2, v[130:131]
	v_lshlrev_b32_e32 v96, 2, v142
	v_lshl_add_u64 v[130:131], v[130:131], 0, v[96:97]
	v_add_co_u32_e32 v130, vcc, 0xfffff000, v130
	s_nop 1
	v_addc_co_u32_e32 v131, vcc, -1, v131, vcc
	global_store_dwordx4 v[130:131], v[126:129], off offset:-1024
	s_ashr_i32 s93, s0, 31
	s_mov_b32 s92, s0
	v_lshl_add_u64 v[130:131], s[30:31], 0, v[178:179]
	v_lshl_add_u64 v[132:133], s[92:93], 2, v[130:131]
	v_lshlrev_b32_e32 v130, 2, v142
	v_lshl_add_u64 v[126:127], s[72:73], 0, v[178:179]
	v_lshl_add_u64 v[126:127], s[0:1], 2, v[126:127]
	v_lshlrev_b32_e32 v96, 2, v144
	v_lshl_add_u64 v[126:127], v[126:127], 0, v[96:97]
	v_add_co_u32_e32 v126, vcc, 0xfffff000, v126
	s_nop 1
	v_addc_co_u32_e32 v127, vcc, -1, v127, vcc
	global_store_dwordx4 v[126:127], v[122:125], off offset:-1024
	v_readlane_b32 s70, v254, 59
	v_readlane_b32 s71, v254, 60
	v_lshl_add_u64 v[122:123], s[72:73], 0, v[178:179]
	v_lshl_add_u64 v[122:123], s[0:1], 2, v[122:123]
	v_lshlrev_b32_e32 v96, 2, v150
	v_lshl_add_u64 v[122:123], v[122:123], 0, v[96:97]
	v_add_co_u32_e32 v122, vcc, 0xfffff000, v122
	s_nop 1
	v_addc_co_u32_e32 v123, vcc, -1, v123, vcc
	global_store_dwordx4 v[122:123], v[118:121], off offset:-1024
	s_nop 1
	v_lshl_add_u64 v[118:119], s[72:73], 0, v[178:179]
	v_lshl_add_u64 v[118:119], s[0:1], 2, v[118:119]
	v_lshlrev_b32_e32 v96, 2, v152
	v_lshl_add_u64 v[118:119], v[118:119], 0, v[96:97]
	v_add_co_u32_e32 v118, vcc, 0xfffff000, v118
	s_nop 1
	v_addc_co_u32_e32 v119, vcc, -1, v119, vcc
	global_store_dwordx4 v[118:119], v[114:117], off offset:-1024
	s_mov_b64 s[70:71], 0
	s_andn2_b64 vcc, exec, s[70:71]
	v_or_b32_e32 v114, 16, v172
	v_mad_i64_i32 v[124:125], s[18:19], v114, s61, 0
	s_movk_i32 s18, 0x7df
	s_nop 0
	v_bitop3_b32 v96, v172, s18, 16 bitop3:0xc8
	s_movk_i32 s18, 0x4000
	v_cmp_gt_i32_e32 vcc, s18, v114
	s_nop 1
	v_cndmask_b32_e32 v116, v151, v96, vcc
	v_add_u32_e32 v96, 0xfffff880, v96
	v_ashrrev_i32_e32 v115, 31, v114
	v_lshlrev_b32_e32 v176, 3, v116
	v_add_u32_e32 v116, 0xffffc010, v172
	v_lshlrev_b64 v[126:127], 7, v[96:97]
	s_mov_b64 s[70:71], 0x1080000
	v_lshlrev_b64 v[122:123], 11, v[114:115]
	v_lshlrev_b64 v[120:121], 8, v[114:115]
	v_lshrrev_b32_e32 v173, 2, v116
;     __device__ __forceinline__ void operator()(const f32x4 (&acc)[2][2][4][2], const Unit& u, int wr, int wc, int fr, int fq) const {
;     ...
;         for (int ai = 0; ai < 2; ++ai)
; #pragma unroll
;             for (int m = 0; m < 4; ++m) { const int row = u.pm * 256 + ai * 128 + wr * 64 + m * 16 + fr;
; #pragma unroll
;                 for (int bj = 0; bj < 2; ++bj)
; #pragma unroll
;                     for (int n = 0; n < 2; ++n) { const int tc = bj * 128 + wc * 32 + 8 * fq + 4 * n; f32x4 v = acc[ai][bj][m][n];
;     ...
;                         else if (pn < 7) { *(f32x4*)(U + (size_t)row * 512 + (pn - 5) * 256 + tc) = v; }
	v_lshl_add_u64 v[128:129], v[126:127], 0, s[70:71]
	v_lshl_add_u64 v[114:115], s[72:73], 0, v[122:123]
	v_lshl_add_u64 v[114:115], s[0:1], 2, v[114:115]
	v_mov_b32_e32 v131, v97
	v_lshl_add_u64 v[114:115], v[114:115], 0, v[130:131]
	v_add_co_u32_e32 v114, vcc, 0xfffff000, v114
	s_nop 1
	v_addc_co_u32_e32 v115, vcc, -1, v115, vcc
	global_store_dwordx4 v[114:115], v[110:113], off offset:-1024
	s_nop 1
	v_lshl_add_u64 v[114:115], s[30:31], 0, v[122:123]
	v_lshl_add_u64 v[114:115], s[92:93], 2, v[114:115]
	v_lshl_add_u64 v[110:111], s[72:73], 0, v[122:123]
	v_lshl_add_u64 v[110:111], s[0:1], 2, v[110:111]
	v_lshlrev_b32_e32 v96, 2, v144
	v_lshl_add_u64 v[110:111], v[110:111], 0, v[96:97]
	v_add_co_u32_e32 v110, vcc, 0xfffff000, v110
	s_nop 1
	v_addc_co_u32_e32 v111, vcc, -1, v111, vcc
	global_store_dwordx4 v[110:111], v[106:109], off offset:-1024
	s_nop 1
	v_lshl_add_u64 v[106:107], s[72:73], 0, v[122:123]
	v_lshl_add_u64 v[106:107], s[0:1], 2, v[106:107]
	v_lshlrev_b32_e32 v96, 2, v150
	v_lshl_add_u64 v[106:107], v[106:107], 0, v[96:97]
	v_add_co_u32_e32 v106, vcc, 0xfffff000, v106
	s_nop 1
	v_addc_co_u32_e32 v107, vcc, -1, v107, vcc
	global_store_dwordx4 v[106:107], v[102:105], off offset:-1024
	s_nop 1
	v_lshl_add_u64 v[102:103], s[72:73], 0, v[122:123]
	v_lshl_add_u64 v[102:103], s[0:1], 2, v[102:103]
	v_lshlrev_b32_e32 v96, 2, v152
	v_lshl_add_u64 v[102:103], v[102:103], 0, v[96:97]
	v_add_co_u32_e32 v102, vcc, 0xfffff000, v102
	s_nop 1
	v_addc_co_u32_e32 v103, vcc, -1, v103, vcc
	global_store_dwordx4 v[102:103], v[98:101], off offset:-1024
	s_mov_b64 s[70:71], 0
	s_andn2_b64 vcc, exec, s[70:71]
	v_or_b32_e32 v98, 32, v172
	v_mad_i64_i32 v[108:109], s[18:19], v98, s61, 0
	s_movk_i32 s18, 0x7ef
	s_nop 0
	v_bitop3_b32 v96, v172, s18, 32 bitop3:0xc8
	s_movk_i32 s18, 0x4000
	v_cmp_gt_i32_e32 vcc, s18, v98
	s_nop 1
	v_cndmask_b32_e32 v100, v151, v96, vcc
	v_add_u32_e32 v96, 0xfffff880, v96
	v_ashrrev_i32_e32 v99, 31, v98
	v_lshlrev_b32_e32 v119, 3, v100
	v_add_u32_e32 v100, 0xffffc020, v172
	v_lshlrev_b64 v[110:111], 7, v[96:97]
	s_mov_b64 s[70:71], 0x1080000
	v_lshlrev_b64 v[106:107], 11, v[98:99]
	v_lshlrev_b64 v[104:105], 8, v[98:99]
	v_lshrrev_b32_e32 v118, 2, v100
	v_lshl_add_u64 v[112:113], v[110:111], 0, s[70:71]
	v_lshl_add_u64 v[98:99], s[72:73], 0, v[106:107]
	v_lshl_add_u64 v[98:99], s[0:1], 2, v[98:99]
	v_mov_b32_e32 v131, v97
	v_lshl_add_u64 v[98:99], v[98:99], 0, v[130:131]
	v_add_co_u32_e32 v98, vcc, 0xfffff000, v98
	s_nop 1
	v_addc_co_u32_e32 v99, vcc, -1, v99, vcc
	global_store_dwordx4 v[98:99], v[92:95], off offset:-1024
	s_nop 1
	v_lshl_add_u64 v[98:99], s[30:31], 0, v[106:107]
	v_lshl_add_u64 v[98:99], s[92:93], 2, v[98:99]
	v_lshl_add_u64 v[92:93], s[72:73], 0, v[106:107]
	v_lshl_add_u64 v[92:93], s[0:1], 2, v[92:93]
	v_lshlrev_b32_e32 v96, 2, v144
	v_lshl_add_u64 v[92:93], v[92:93], 0, v[96:97]
	v_add_co_u32_e32 v92, vcc, 0xfffff000, v92
	s_nop 1
	v_addc_co_u32_e32 v93, vcc, -1, v93, vcc
	global_store_dwordx4 v[92:93], v[88:91], off offset:-1024
	s_nop 1
	v_lshl_add_u64 v[88:89], s[72:73], 0, v[106:107]
	v_lshl_add_u64 v[88:89], s[0:1], 2, v[88:89]
	v_lshlrev_b32_e32 v96, 2, v150
	v_lshl_add_u64 v[88:89], v[88:89], 0, v[96:97]
	v_add_co_u32_e32 v88, vcc, 0xfffff000, v88
	s_nop 1
	v_addc_co_u32_e32 v89, vcc, -1, v89, vcc
	global_store_dwordx4 v[88:89], v[84:87], off offset:-1024
	s_nop 1
	v_lshl_add_u64 v[84:85], s[72:73], 0, v[106:107]
	v_lshl_add_u64 v[84:85], s[0:1], 2, v[84:85]
	v_lshlrev_b32_e32 v96, 2, v152
	v_lshl_add_u64 v[84:85], v[84:85], 0, v[96:97]
	v_add_co_u32_e32 v84, vcc, 0xfffff000, v84
	s_nop 1
	v_addc_co_u32_e32 v85, vcc, -1, v85, vcc
	global_store_dwordx4 v[84:85], v[80:83], off offset:-1024
	s_mov_b64 s[70:71], 0
	s_andn2_b64 vcc, exec, s[70:71]
	v_or_b32_e32 v80, 48, v172
	v_mad_i64_i32 v[90:91], s[18:19], v80, s61, 0
	s_movk_i32 s18, 0x7ff
	s_nop 0
	v_bitop3_b32 v82, v172, s18, 48 bitop3:0xc8
	s_movk_i32 s18, 0x4000
	v_cmp_gt_i32_e32 vcc, s18, v80
	v_add_u32_e32 v96, 0xfffff880, v82
	v_ashrrev_i32_e32 v81, 31, v80
	v_cndmask_b32_e32 v83, v151, v82, vcc
	v_lshlrev_b32_e32 v103, 3, v83
	v_add_u32_e32 v83, 0xffffc030, v172
	v_lshlrev_b64 v[92:93], 7, v[96:97]
	s_mov_b64 s[70:71], 0x1080000
	v_lshlrev_b64 v[88:89], 11, v[80:81]
	v_lshrrev_b32_e32 v102, 2, v83
	v_lshlrev_b64 v[84:85], 10, v[80:81]
	v_lshl_add_u64 v[94:95], v[92:93], 0, s[70:71]
	v_lshl_add_u64 v[80:81], s[72:73], 0, v[88:89]
	v_lshl_add_u64 v[80:81], s[0:1], 2, v[80:81]
	v_mov_b32_e32 v131, v97
	v_lshl_add_u64 v[80:81], v[80:81], 0, v[130:131]
	v_add_co_u32_e32 v80, vcc, 0xfffff000, v80
	s_nop 1
	v_addc_co_u32_e32 v81, vcc, -1, v81, vcc
	global_store_dwordx4 v[80:81], v[76:79], off offset:-1024
	s_nop 1
	v_lshl_add_u64 v[76:77], s[72:73], 0, v[88:89]
	v_lshl_add_u64 v[76:77], s[0:1], 2, v[76:77]
	v_lshlrev_b32_e32 v96, 2, v144
	v_lshl_add_u64 v[76:77], v[76:77], 0, v[96:97]
	v_add_co_u32_e32 v76, vcc, 0xfffff000, v76
	s_nop 1
	v_addc_co_u32_e32 v77, vcc, -1, v77, vcc
	global_store_dwordx4 v[76:77], v[72:75], off offset:-1024
	s_nop 1
	v_lshl_add_u64 v[72:73], s[72:73], 0, v[88:89]
	v_lshl_add_u64 v[72:73], s[0:1], 2, v[72:73]
	v_lshlrev_b32_e32 v96, 2, v150
	v_lshl_add_u64 v[72:73], v[72:73], 0, v[96:97]
	v_add_co_u32_e32 v72, vcc, 0xfffff000, v72
	s_nop 1
	v_addc_co_u32_e32 v73, vcc, -1, v73, vcc
	global_store_dwordx4 v[72:73], v[68:71], off offset:-1024
	s_nop 1
	v_lshl_add_u64 v[68:69], s[72:73], 0, v[88:89]
	v_lshl_add_u64 v[68:69], s[0:1], 2, v[68:69]
	v_lshlrev_b32_e32 v96, 2, v152
	v_lshl_add_u64 v[68:69], v[68:69], 0, v[96:97]
	v_add_co_u32_e32 v68, vcc, 0xfffff000, v68
	s_nop 1
	v_addc_co_u32_e32 v69, vcc, -1, v69, vcc
;     __device__ __forceinline__ void operator()(const f32x4 (&acc)[2][2][4][2], const Unit& u, int wr, int wc, int fr, int fq) const {
;     ...
;         for (int ai = 0; ai < 2; ++ai)
; #pragma unroll
;             for (int m = 0; m < 4; ++m) { const int row = u.pm * 256 + ai * 128 + wr * 64 + m * 16 + fr;
; #pragma unroll
;                 for (int bj = 0; bj < 2; ++bj)
; #pragma unroll
;                     for (int n = 0; n < 2; ++n) { const int tc = bj * 128 + wc * 32 + 8 * fq + 4 * n; f32x4 v = acc[ai][bj][m][n];
;     ...
;                         else if (pn < 7) { *(f32x4*)(U + (size_t)row * 512 + (pn - 5) * 256 + tc) = v; }
	global_store_dwordx4 v[68:69], v[64:67], off offset:-1024
	s_mov_b64 s[70:71], 0
	s_andn2_b64 vcc, exec, s[70:71]
	s_add_i32 s46, s53, 0x80
	v_or_b32_e32 v68, s46, v143
	v_mad_i64_i32 v[76:77], s[18:19], v68, s61, 0
	v_mov_b32_e32 v64, 0x7cf
	s_movk_i32 s18, 0x4000
	v_bitop3_b32 v64, s46, v64, v143 bitop3:0xc8
	v_cmp_gt_i32_e32 vcc, s18, v68
	v_add_u32_e32 v96, 0xfffff880, v64
	v_ashrrev_i32_e32 v69, 31, v68
	v_cndmask_b32_e32 v65, v151, v64, vcc
	v_lshlrev_b32_e32 v87, 3, v65
	v_add_u32_e32 v65, 0xffffc000, v68
	v_lshlrev_b64 v[78:79], 7, v[96:97]
	s_mov_b64 s[70:71], 0x1080000
	v_lshlrev_b64 v[74:75], 11, v[68:69]
	v_lshlrev_b64 v[72:73], 8, v[68:69]
	v_lshrrev_b32_e32 v86, 2, v65
	v_lshlrev_b64 v[70:71], 10, v[68:69]
	v_lshl_add_u64 v[80:81], v[78:79], 0, s[70:71]
	s_mov_b32 s75, 0x400000
	v_lshl_add_u64 v[64:65], s[72:73], 0, v[74:75]
	v_lshl_add_u64 v[64:65], s[0:1], 2, v[64:65]
	v_mov_b32_e32 v131, v97
	v_lshl_add_u64 v[64:65], v[64:65], 0, v[130:131]
	v_add_co_u32_e32 v64, vcc, 0xfffff000, v64
	s_nop 1
	v_addc_co_u32_e32 v65, vcc, -1, v65, vcc
	global_store_dwordx4 v[64:65], v[60:63], off offset:-1024
	s_nop 1
	v_lshl_add_u64 v[64:65], s[30:31], 0, v[74:75]
	v_lshl_add_u64 v[64:65], s[92:93], 2, v[64:65]
	v_lshl_add_u64 v[60:61], s[72:73], 0, v[74:75]
	v_lshl_add_u64 v[60:61], s[0:1], 2, v[60:61]
	v_lshlrev_b32_e32 v96, 2, v144
	v_lshl_add_u64 v[60:61], v[60:61], 0, v[96:97]
	v_add_co_u32_e32 v60, vcc, 0xfffff000, v60
	s_nop 1
	v_addc_co_u32_e32 v61, vcc, -1, v61, vcc
	global_store_dwordx4 v[60:61], v[56:59], off offset:-1024
	s_nop 1
	v_lshl_add_u64 v[56:57], s[72:73], 0, v[74:75]
	v_lshl_add_u64 v[56:57], s[0:1], 2, v[56:57]
	v_lshlrev_b32_e32 v96, 2, v150
	v_lshl_add_u64 v[56:57], v[56:57], 0, v[96:97]
	v_add_co_u32_e32 v56, vcc, 0xfffff000, v56
	s_nop 1
	v_addc_co_u32_e32 v57, vcc, -1, v57, vcc
	global_store_dwordx4 v[56:57], v[52:55], off offset:-1024
	s_nop 1
	v_lshl_add_u64 v[52:53], s[72:73], 0, v[74:75]
	v_lshl_add_u64 v[52:53], s[0:1], 2, v[52:53]
	v_lshlrev_b32_e32 v96, 2, v152
	v_lshl_add_u64 v[52:53], v[52:53], 0, v[96:97]
	v_add_co_u32_e32 v52, vcc, 0xfffff000, v52
	s_nop 1
	v_addc_co_u32_e32 v53, vcc, -1, v53, vcc
	global_store_dwordx4 v[52:53], v[48:51], off offset:-1024
	s_mov_b64 s[70:71], 0
	s_andn2_b64 vcc, exec, s[70:71]
	v_or_b32_e32 v48, 16, v68
	v_mad_i64_i32 v[58:59], s[18:19], v48, s61, 0
	s_movk_i32 s18, 0x7df
	s_nop 0
	v_bitop3_b32 v50, v68, s18, 16 bitop3:0xc8
	s_movk_i32 s18, 0x4000
	v_cmp_gt_i32_e32 vcc, s18, v48
	v_add_u32_e32 v96, 0xfffff880, v50
	v_ashrrev_i32_e32 v49, 31, v48
	v_cndmask_b32_e32 v51, v151, v50, vcc
	v_lshlrev_b32_e32 v70, 3, v51
	v_add_u32_e32 v51, 0xffffc010, v68
	v_lshlrev_b64 v[60:61], 7, v[96:97]
	s_mov_b64 s[70:71], 0x1080000
	v_lshlrev_b64 v[56:57], 11, v[48:49]
	v_lshlrev_b64 v[54:55], 8, v[48:49]
	v_lshrrev_b32_e32 v69, 2, v51
	v_lshl_add_u64 v[62:63], v[60:61], 0, s[70:71]
	v_lshl_add_u64 v[48:49], s[72:73], 0, v[56:57]
	v_lshl_add_u64 v[48:49], s[0:1], 2, v[48:49]
	v_mov_b32_e32 v131, v97
	v_lshl_add_u64 v[48:49], v[48:49], 0, v[130:131]
	v_add_co_u32_e32 v48, vcc, 0xfffff000, v48
	s_nop 1
	v_addc_co_u32_e32 v49, vcc, -1, v49, vcc
	global_store_dwordx4 v[48:49], v[44:47], off offset:-1024
	s_nop 1
	v_lshl_add_u64 v[48:49], s[30:31], 0, v[56:57]
	v_lshl_add_u64 v[48:49], s[92:93], 2, v[48:49]
	v_lshl_add_u64 v[44:45], s[72:73], 0, v[56:57]
	v_lshl_add_u64 v[44:45], s[0:1], 2, v[44:45]
	v_lshlrev_b32_e32 v96, 2, v144
	v_lshl_add_u64 v[44:45], v[44:45], 0, v[96:97]
	v_add_co_u32_e32 v44, vcc, 0xfffff000, v44
	s_nop 1
	v_addc_co_u32_e32 v45, vcc, -1, v45, vcc
	global_store_dwordx4 v[44:45], v[40:43], off offset:-1024
	s_nop 1
	v_lshl_add_u64 v[40:41], s[72:73], 0, v[56:57]
	v_lshl_add_u64 v[40:41], s[0:1], 2, v[40:41]
	v_lshlrev_b32_e32 v96, 2, v150
	v_lshl_add_u64 v[40:41], v[40:41], 0, v[96:97]
	v_add_co_u32_e32 v40, vcc, 0xfffff000, v40
	s_nop 1
	v_addc_co_u32_e32 v41, vcc, -1, v41, vcc
	global_store_dwordx4 v[40:41], v[36:39], off offset:-1024
	s_nop 1
	v_lshl_add_u64 v[36:37], s[72:73], 0, v[56:57]
	v_lshl_add_u64 v[36:37], s[0:1], 2, v[36:37]
	v_lshlrev_b32_e32 v96, 2, v152
	v_lshl_add_u64 v[36:37], v[36:37], 0, v[96:97]
	v_add_co_u32_e32 v36, vcc, 0xfffff000, v36
	s_nop 1
	v_addc_co_u32_e32 v37, vcc, -1, v37, vcc
	global_store_dwordx4 v[36:37], v[32:35], off offset:-1024
	s_mov_b64 s[70:71], 0
	s_andn2_b64 vcc, exec, s[70:71]
	v_or_b32_e32 v32, 32, v68
	v_mad_i64_i32 v[42:43], s[18:19], v32, s61, 0
	s_movk_i32 s18, 0x7ef
	s_nop 0
	v_bitop3_b32 v34, v68, s18, 32 bitop3:0xc8
	s_movk_i32 s18, 0x4000
	v_cmp_gt_i32_e32 vcc, s18, v32
	v_add_u32_e32 v96, 0xfffff880, v34
	v_ashrrev_i32_e32 v33, 31, v32
	v_cndmask_b32_e32 v35, v151, v34, vcc
	v_lshlrev_b32_e32 v53, 3, v35
	v_add_u32_e32 v35, 0xffffc020, v68
	v_lshlrev_b64 v[44:45], 7, v[96:97]
	s_mov_b64 s[70:71], 0x1080000
	v_lshlrev_b64 v[40:41], 11, v[32:33]
	v_lshlrev_b64 v[38:39], 8, v[32:33]
	v_lshrrev_b32_e32 v52, 2, v35
	v_lshl_add_u64 v[46:47], v[44:45], 0, s[70:71]
	v_lshl_add_u64 v[32:33], s[72:73], 0, v[40:41]
	v_lshl_add_u64 v[32:33], s[0:1], 2, v[32:33]
	v_mov_b32_e32 v131, v97
	v_lshl_add_u64 v[32:33], v[32:33], 0, v[130:131]
	v_add_co_u32_e32 v32, vcc, 0xfffff000, v32
	s_nop 1
	v_addc_co_u32_e32 v33, vcc, -1, v33, vcc
	global_store_dwordx4 v[32:33], v[28:31], off offset:-1024
	s_nop 1
	v_lshl_add_u64 v[32:33], s[30:31], 0, v[40:41]
	v_lshl_add_u64 v[32:33], s[92:93], 2, v[32:33]
	v_lshl_add_u64 v[28:29], s[72:73], 0, v[40:41]
	v_lshl_add_u64 v[28:29], s[0:1], 2, v[28:29]
	v_lshlrev_b32_e32 v96, 2, v144
	v_lshl_add_u64 v[28:29], v[28:29], 0, v[96:97]
	v_add_co_u32_e32 v28, vcc, 0xfffff000, v28
	s_nop 1
;     __device__ __forceinline__ void operator()(const f32x4 (&acc)[2][2][4][2], const Unit& u, int wr, int wc, int fr, int fq) const {
;     ...
;         for (int ai = 0; ai < 2; ++ai)
; #pragma unroll
;             for (int m = 0; m < 4; ++m) { const int row = u.pm * 256 + ai * 128 + wr * 64 + m * 16 + fr;
; #pragma unroll
;                 for (int bj = 0; bj < 2; ++bj)
; #pragma unroll
;                     for (int n = 0; n < 2; ++n) { const int tc = bj * 128 + wc * 32 + 8 * fq + 4 * n; f32x4 v = acc[ai][bj][m][n];
;                         if (pn < 2) { *(f32x4*)(XA + (size_t)row * 512 + pn * 256 + tc) = v; }
;     ...
;                         else if (pn < 7) { *(f32x4*)(U + (size_t)row * 512 + (pn - 5) * 256 + tc) = v; }
	v_addc_co_u32_e32 v29, vcc, -1, v29, vcc
	global_store_dwordx4 v[28:29], v[24:27], off offset:-1024
	s_nop 1
	v_lshl_add_u64 v[24:25], s[72:73], 0, v[40:41]
	v_lshl_add_u64 v[24:25], s[0:1], 2, v[24:25]
	v_lshlrev_b32_e32 v96, 2, v150
	v_lshl_add_u64 v[24:25], v[24:25], 0, v[96:97]
	v_add_co_u32_e32 v24, vcc, 0xfffff000, v24
	s_nop 1
	v_addc_co_u32_e32 v25, vcc, -1, v25, vcc
	global_store_dwordx4 v[24:25], v[20:23], off offset:-1024
	s_nop 1
	v_lshl_add_u64 v[20:21], s[72:73], 0, v[40:41]
	v_lshl_add_u64 v[20:21], s[0:1], 2, v[20:21]
	v_lshlrev_b32_e32 v96, 2, v152
	v_lshl_add_u64 v[20:21], v[20:21], 0, v[96:97]
	v_add_co_u32_e32 v20, vcc, 0xfffff000, v20
	s_nop 1
	v_addc_co_u32_e32 v21, vcc, -1, v21, vcc
	global_store_dwordx4 v[20:21], v[16:19], off offset:-1024
	s_mov_b64 s[70:71], 0
	s_andn2_b64 vcc, exec, s[70:71]
	v_or_b32_e32 v16, 48, v68
	v_mad_i64_i32 v[26:27], s[18:19], v16, s61, 0
	s_movk_i32 s18, 0x3fff
	s_nop 0
	v_cmp_lt_i32_e64 s[20:21], s18, v16
	s_movk_i32 s18, 0x7ff
	v_bitop3_b32 v18, v68, s18, 48 bitop3:0xc8
	s_movk_i32 s18, 0x4000
	v_cmp_gt_i32_e32 vcc, s18, v16
	v_add_u32_e32 v96, 0xfffff880, v18
	v_ashrrev_i32_e32 v17, 31, v16
	v_cndmask_b32_e32 v19, v151, v18, vcc
	v_lshlrev_b32_e32 v37, 3, v19
	v_add_u32_e32 v19, 0xffffc030, v68
	v_lshlrev_b64 v[28:29], 7, v[96:97]
	s_mov_b64 s[70:71], 0x1080000
	v_lshlrev_b64 v[24:25], 11, v[16:17]
	v_lshlrev_b64 v[22:23], 8, v[16:17]
	v_lshrrev_b32_e32 v36, 2, v19
	v_lshlrev_b64 v[20:21], 10, v[16:17]
	v_lshl_add_u64 v[30:31], v[28:29], 0, s[70:71]
	v_lshl_add_u64 v[16:17], s[72:73], 0, v[24:25]
	v_lshl_add_u64 v[16:17], s[0:1], 2, v[16:17]
	v_mov_b32_e32 v131, v97
	v_lshl_add_u64 v[16:17], v[16:17], 0, v[130:131]
	v_add_co_u32_e32 v16, vcc, 0xfffff000, v16
	s_nop 1
	v_addc_co_u32_e32 v17, vcc, -1, v17, vcc
	global_store_dwordx4 v[16:17], v[12:15], off offset:-1024
	s_nop 1
	v_lshl_add_u64 v[16:17], s[30:31], 0, v[24:25]
	v_lshl_add_u64 v[16:17], s[92:93], 2, v[16:17]
	v_lshl_add_u64 v[12:13], s[72:73], 0, v[24:25]
	v_lshl_add_u64 v[12:13], s[0:1], 2, v[12:13]
	v_lshlrev_b32_e32 v96, 2, v144
	v_lshl_add_u64 v[12:13], v[12:13], 0, v[96:97]
	v_add_co_u32_e32 v12, vcc, 0xfffff000, v12
	s_nop 1
	v_addc_co_u32_e32 v13, vcc, -1, v13, vcc
	global_store_dwordx4 v[12:13], v[8:11], off offset:-1024
	s_mov_b64 s[70:71], 0x1100000
	s_nop 0
	v_lshl_add_u64 v[12:13], v[28:29], 0, s[70:71]
	v_lshl_add_u64 v[8:9], s[72:73], 0, v[24:25]
	v_lshl_add_u64 v[8:9], s[0:1], 2, v[8:9]
	v_lshlrev_b32_e32 v96, 2, v150
	v_lshl_add_u64 v[8:9], v[8:9], 0, v[96:97]
	v_add_co_u32_e32 v8, vcc, 0xfffff000, v8
	s_nop 1
	v_addc_co_u32_e32 v9, vcc, -1, v9, vcc
	global_store_dwordx4 v[8:9], v[4:7], off offset:-1024
	s_mov_b32 s70, 0x1200000
	s_mov_b32 s71, 0x1400000
	v_lshl_add_u64 v[4:5], s[72:73], 0, v[24:25]
	v_lshl_add_u64 v[4:5], s[0:1], 2, v[4:5]
	v_lshlrev_b32_e32 v96, 2, v152
	v_lshl_add_u64 v[4:5], v[4:5], 0, v[96:97]
	v_add_co_u32_e32 v4, vcc, 0xfffff000, v4
	s_nop 1
	v_addc_co_u32_e32 v5, vcc, -1, v5, vcc
	global_store_dwordx4 v[4:5], v[0:3], off offset:-1024
	s_mov_b64 s[14:15], 0
	s_branch .LBB0_1574
.Lsp_xa:
	s_nop 7
	s_ashr_i32 s93, s0, 31
	s_mov_b32 s92, s0
	v_lshl_add_u64 v[130:131], s[30:31], 0, v[178:179]
	v_lshl_add_u64 v[132:133], s[92:93], 2, v[130:131]
	v_lshlrev_b32_e32 v130, 2, v142
	v_mov_b32_e32 v131, v97
	v_lshl_add_u64 v[146:147], v[132:133], 0, v[130:131]
	global_store_dwordx4 v[146:147], v[126:129], off
	v_cndmask_b32_e64 v96, 0, 1, s[78:79]
	v_cmp_ne_u32_e64 s[14:15], 1, v96
	v_mov_b32_e32 v131, v97
	v_lshl_add_u64 v[126:127], v[132:133], 0, v[130:131]
	global_store_dwordx4 v[126:127], v[122:125], off offset:16
	v_readlane_b32 s70, v254, 59
	v_readlane_b32 s71, v254, 60
	v_mov_b32_e32 v131, v97
	v_lshl_add_u64 v[122:123], v[132:133], 0, v[130:131]
	global_store_dwordx4 v[122:123], v[118:121], off offset:512
	s_mov_b64 s[70:71], -1
	s_andn2_b64 vcc, exec, s[70:71]
	v_mov_b32_e32 v131, v97
	v_lshl_add_u64 v[118:119], v[132:133], 0, v[130:131]
	global_store_dwordx4 v[118:119], v[114:117], off offset:528
	s_nop 1
	v_or_b32_e32 v114, 16, v172
	v_mad_i64_i32 v[124:125], s[18:19], v114, s61, 0
	s_movk_i32 s18, 0x7df
	s_nop 0
	v_bitop3_b32 v96, v172, s18, 16 bitop3:0xc8
	s_movk_i32 s18, 0x4000
	v_cmp_gt_i32_e32 vcc, s18, v114
	s_nop 1
	v_cndmask_b32_e32 v116, v151, v96, vcc
	v_add_u32_e32 v96, 0xfffff880, v96
	v_ashrrev_i32_e32 v115, 31, v114
	v_lshlrev_b32_e32 v176, 3, v116
	v_add_u32_e32 v116, 0xffffc010, v172
	v_lshlrev_b64 v[126:127], 7, v[96:97]
	s_mov_b64 s[70:71], 0x1080000
	v_lshlrev_b64 v[122:123], 11, v[114:115]
	v_lshlrev_b64 v[120:121], 8, v[114:115]
	v_lshrrev_b32_e32 v173, 2, v116
	v_lshl_add_u64 v[128:129], v[126:127], 0, s[70:71]
	v_lshl_add_u64 v[114:115], s[30:31], 0, v[122:123]
	v_lshl_add_u64 v[114:115], s[92:93], 2, v[114:115]
	v_mov_b32_e32 v131, v97
	v_lshl_add_u64 v[116:117], v[114:115], 0, v[130:131]
	global_store_dwordx4 v[116:117], v[110:113], off
	v_mov_b32_e32 v131, v97
	s_nop 0
	v_lshl_add_u64 v[110:111], v[114:115], 0, v[130:131]
	global_store_dwordx4 v[110:111], v[106:109], off offset:16
	v_mov_b32_e32 v131, v97
	s_nop 0
	v_lshl_add_u64 v[106:107], v[114:115], 0, v[130:131]
	global_store_dwordx4 v[106:107], v[102:105], off offset:512
	s_mov_b64 s[70:71], -1
	s_andn2_b64 vcc, exec, s[70:71]
	v_mov_b32_e32 v131, v97
	v_lshl_add_u64 v[102:103], v[114:115], 0, v[130:131]
	global_store_dwordx4 v[102:103], v[98:101], off offset:528
	s_nop 1
	v_or_b32_e32 v98, 32, v172
	v_mad_i64_i32 v[108:109], s[18:19], v98, s61, 0
	s_movk_i32 s18, 0x7ef
	s_nop 0
	v_bitop3_b32 v96, v172, s18, 32 bitop3:0xc8
	s_movk_i32 s18, 0x4000
	v_cmp_gt_i32_e32 vcc, s18, v98
	s_nop 1
;     __device__ __forceinline__ void operator()(const f32x4 (&acc)[2][2][4][2], const Unit& u, int wr, int wc, int fr, int fq) const {
;     ...
;         for (int ai = 0; ai < 2; ++ai)
; #pragma unroll
;             for (int m = 0; m < 4; ++m) { const int row = u.pm * 256 + ai * 128 + wr * 64 + m * 16 + fr;
; #pragma unroll
;                 for (int bj = 0; bj < 2; ++bj)
; #pragma unroll
;                     for (int n = 0; n < 2; ++n) { const int tc = bj * 128 + wc * 32 + 8 * fq + 4 * n; f32x4 v = acc[ai][bj][m][n];
;                         if (pn < 2) { *(f32x4*)(XA + (size_t)row * 512 + pn * 256 + tc) = v; }
	v_cndmask_b32_e32 v100, v151, v96, vcc
	v_add_u32_e32 v96, 0xfffff880, v96
	v_ashrrev_i32_e32 v99, 31, v98
	v_lshlrev_b32_e32 v119, 3, v100
	v_add_u32_e32 v100, 0xffffc020, v172
	v_lshlrev_b64 v[110:111], 7, v[96:97]
	s_mov_b64 s[70:71], 0x1080000
	v_lshlrev_b64 v[106:107], 11, v[98:99]
	v_lshlrev_b64 v[104:105], 8, v[98:99]
	v_lshrrev_b32_e32 v118, 2, v100
	v_lshl_add_u64 v[112:113], v[110:111], 0, s[70:71]
	v_lshl_add_u64 v[98:99], s[30:31], 0, v[106:107]
	v_lshl_add_u64 v[98:99], s[92:93], 2, v[98:99]
	v_mov_b32_e32 v131, v97
	v_lshl_add_u64 v[100:101], v[98:99], 0, v[130:131]
	global_store_dwordx4 v[100:101], v[92:95], off
	v_mov_b32_e32 v131, v97
	s_nop 0
	v_lshl_add_u64 v[92:93], v[98:99], 0, v[130:131]
	global_store_dwordx4 v[92:93], v[88:91], off offset:16
	v_mov_b32_e32 v131, v97
	s_nop 0
	v_lshl_add_u64 v[88:89], v[98:99], 0, v[130:131]
	global_store_dwordx4 v[88:89], v[84:87], off offset:512
	s_mov_b64 s[70:71], -1
	s_andn2_b64 vcc, exec, s[70:71]
	v_mov_b32_e32 v131, v97
	v_lshl_add_u64 v[84:85], v[98:99], 0, v[130:131]
	global_store_dwordx4 v[84:85], v[80:83], off offset:528
	s_nop 1
	v_or_b32_e32 v80, 48, v172
	v_mad_i64_i32 v[90:91], s[18:19], v80, s61, 0
	s_movk_i32 s18, 0x7ff
	s_nop 0
	v_bitop3_b32 v82, v172, s18, 48 bitop3:0xc8
	s_movk_i32 s18, 0x4000
	v_cmp_gt_i32_e32 vcc, s18, v80
	v_add_u32_e32 v96, 0xfffff880, v82
	v_ashrrev_i32_e32 v81, 31, v80
	v_cndmask_b32_e32 v83, v151, v82, vcc
	v_lshlrev_b32_e32 v103, 3, v83
	v_add_u32_e32 v83, 0xffffc030, v172
	v_lshlrev_b64 v[92:93], 7, v[96:97]
	s_mov_b64 s[70:71], 0x1080000
	v_lshlrev_b64 v[88:89], 11, v[80:81]
	v_lshrrev_b32_e32 v102, 2, v83
	v_lshlrev_b64 v[84:85], 10, v[80:81]
	v_lshl_add_u64 v[94:95], v[92:93], 0, s[70:71]
	v_lshl_add_u64 v[80:81], s[30:31], 0, v[88:89]
	v_lshl_add_u64 v[80:81], s[92:93], 2, v[80:81]
	v_mov_b32_e32 v131, v97
	v_lshl_add_u64 v[82:83], v[80:81], 0, v[130:131]
	global_store_dwordx4 v[82:83], v[76:79], off
	v_mov_b32_e32 v131, v97
	s_nop 0
	v_lshl_add_u64 v[76:77], v[80:81], 0, v[130:131]
	global_store_dwordx4 v[76:77], v[72:75], off offset:16
	v_mov_b32_e32 v131, v97
	s_nop 0
	v_lshl_add_u64 v[72:73], v[80:81], 0, v[130:131]
	global_store_dwordx4 v[72:73], v[68:71], off offset:512
	s_mov_b64 s[70:71], -1
	s_andn2_b64 vcc, exec, s[70:71]
	v_mov_b32_e32 v131, v97
	v_lshl_add_u64 v[68:69], v[80:81], 0, v[130:131]
	global_store_dwordx4 v[68:69], v[64:67], off offset:528
	s_add_i32 s46, s53, 0x80
	s_nop 0
	v_or_b32_e32 v68, s46, v143
	v_mad_i64_i32 v[76:77], s[18:19], v68, s61, 0
	v_mov_b32_e32 v64, 0x7cf
	s_movk_i32 s18, 0x4000
	v_bitop3_b32 v64, s46, v64, v143 bitop3:0xc8
	v_cmp_gt_i32_e32 vcc, s18, v68
	v_add_u32_e32 v96, 0xfffff880, v64
	v_ashrrev_i32_e32 v69, 31, v68
	v_cndmask_b32_e32 v65, v151, v64, vcc
	v_lshlrev_b32_e32 v87, 3, v65
	v_add_u32_e32 v65, 0xffffc000, v68
	v_lshlrev_b64 v[78:79], 7, v[96:97]
	s_mov_b64 s[70:71], 0x1080000
	v_lshlrev_b64 v[74:75], 11, v[68:69]
	v_lshlrev_b64 v[72:73], 8, v[68:69]
	v_lshrrev_b32_e32 v86, 2, v65
	v_lshlrev_b64 v[70:71], 10, v[68:69]
	v_lshl_add_u64 v[80:81], v[78:79], 0, s[70:71]
	s_mov_b32 s75, 0x400000
	v_lshl_add_u64 v[64:65], s[30:31], 0, v[74:75]
	v_lshl_add_u64 v[64:65], s[92:93], 2, v[64:65]
	v_mov_b32_e32 v131, v97
	v_lshl_add_u64 v[66:67], v[64:65], 0, v[130:131]
	global_store_dwordx4 v[66:67], v[60:63], off
	v_mov_b32_e32 v131, v97
	s_nop 0
	v_lshl_add_u64 v[60:61], v[64:65], 0, v[130:131]
	global_store_dwordx4 v[60:61], v[56:59], off offset:16
	v_mov_b32_e32 v131, v97
	s_nop 0
	v_lshl_add_u64 v[56:57], v[64:65], 0, v[130:131]
	global_store_dwordx4 v[56:57], v[52:55], off offset:512
	s_mov_b64 s[70:71], -1
	s_andn2_b64 vcc, exec, s[70:71]
	v_mov_b32_e32 v131, v97
	v_lshl_add_u64 v[52:53], v[64:65], 0, v[130:131]
	global_store_dwordx4 v[52:53], v[48:51], off offset:528
	s_nop 1
	v_or_b32_e32 v48, 16, v68
	v_mad_i64_i32 v[58:59], s[18:19], v48, s61, 0
	s_movk_i32 s18, 0x7df
	s_nop 0
	v_bitop3_b32 v50, v68, s18, 16 bitop3:0xc8
;     __device__ __forceinline__ void operator()(const f32x4 (&acc)[2][2][4][2], const Unit& u, int wr, int wc, int fr, int fq) const {
;     ...
;         for (int ai = 0; ai < 2; ++ai)
; #pragma unroll
;             for (int m = 0; m < 4; ++m) { const int row = u.pm * 256 + ai * 128 + wr * 64 + m * 16 + fr;
; #pragma unroll
;                 for (int bj = 0; bj < 2; ++bj)
; #pragma unroll
;                     for (int n = 0; n < 2; ++n) { const int tc = bj * 128 + wc * 32 + 8 * fq + 4 * n; f32x4 v = acc[ai][bj][m][n];
;                         if (pn < 2) { *(f32x4*)(XA + (size_t)row * 512 + pn * 256 + tc) = v; }
	s_movk_i32 s18, 0x4000
	v_cmp_gt_i32_e32 vcc, s18, v48
	v_add_u32_e32 v96, 0xfffff880, v50
	v_ashrrev_i32_e32 v49, 31, v48
	v_cndmask_b32_e32 v51, v151, v50, vcc
	v_lshlrev_b32_e32 v70, 3, v51
	v_add_u32_e32 v51, 0xffffc010, v68
	v_lshlrev_b64 v[60:61], 7, v[96:97]
	s_mov_b64 s[70:71], 0x1080000
	v_lshlrev_b64 v[56:57], 11, v[48:49]
	v_lshlrev_b64 v[54:55], 8, v[48:49]
	v_lshrrev_b32_e32 v69, 2, v51
	v_lshl_add_u64 v[62:63], v[60:61], 0, s[70:71]
	v_lshl_add_u64 v[48:49], s[30:31], 0, v[56:57]
	v_lshl_add_u64 v[48:49], s[92:93], 2, v[48:49]
	v_mov_b32_e32 v131, v97
	v_lshl_add_u64 v[50:51], v[48:49], 0, v[130:131]
	global_store_dwordx4 v[50:51], v[44:47], off
	v_mov_b32_e32 v131, v97
	s_nop 0
	v_lshl_add_u64 v[44:45], v[48:49], 0, v[130:131]
	global_store_dwordx4 v[44:45], v[40:43], off offset:16
	v_mov_b32_e32 v131, v97
	s_nop 0
	v_lshl_add_u64 v[40:41], v[48:49], 0, v[130:131]
	global_store_dwordx4 v[40:41], v[36:39], off offset:512
	s_mov_b64 s[70:71], -1
	s_andn2_b64 vcc, exec, s[70:71]
	v_mov_b32_e32 v131, v97
	v_lshl_add_u64 v[36:37], v[48:49], 0, v[130:131]
	global_store_dwordx4 v[36:37], v[32:35], off offset:528
	s_nop 1
	v_or_b32_e32 v32, 32, v68
	v_mad_i64_i32 v[42:43], s[18:19], v32, s61, 0
	s_movk_i32 s18, 0x7ef
	s_nop 0
	v_bitop3_b32 v34, v68, s18, 32 bitop3:0xc8
	s_movk_i32 s18, 0x4000
	v_cmp_gt_i32_e32 vcc, s18, v32
	v_add_u32_e32 v96, 0xfffff880, v34
	v_ashrrev_i32_e32 v33, 31, v32
	v_cndmask_b32_e32 v35, v151, v34, vcc
	v_lshlrev_b32_e32 v53, 3, v35
	v_add_u32_e32 v35, 0xffffc020, v68
	v_lshlrev_b64 v[44:45], 7, v[96:97]
	s_mov_b64 s[70:71], 0x1080000
	v_lshlrev_b64 v[40:41], 11, v[32:33]
	v_lshlrev_b64 v[38:39], 8, v[32:33]
	v_lshrrev_b32_e32 v52, 2, v35
	v_lshl_add_u64 v[46:47], v[44:45], 0, s[70:71]
	v_lshl_add_u64 v[32:33], s[30:31], 0, v[40:41]
	v_lshl_add_u64 v[32:33], s[92:93], 2, v[32:33]
	v_mov_b32_e32 v131, v97
	v_lshl_add_u64 v[34:35], v[32:33], 0, v[130:131]
	global_store_dwordx4 v[34:35], v[28:31], off
	v_mov_b32_e32 v131, v97
	s_nop 0
	v_lshl_add_u64 v[28:29], v[32:33], 0, v[130:131]
	global_store_dwordx4 v[28:29], v[24:27], off offset:16
	v_mov_b32_e32 v131, v97
	s_nop 0
	v_lshl_add_u64 v[24:25], v[32:33], 0, v[130:131]
	global_store_dwordx4 v[24:25], v[20:23], off offset:512
	s_mov_b64 s[70:71], -1
	s_andn2_b64 vcc, exec, s[70:71]
	v_mov_b32_e32 v131, v97
	v_lshl_add_u64 v[20:21], v[32:33], 0, v[130:131]
	global_store_dwordx4 v[20:21], v[16:19], off offset:528
	s_nop 1
	v_or_b32_e32 v16, 48, v68
	v_mad_i64_i32 v[26:27], s[18:19], v16, s61, 0
	s_movk_i32 s18, 0x3fff
	s_nop 0
	v_cmp_lt_i32_e64 s[20:21], s18, v16
	s_movk_i32 s18, 0x7ff
	v_bitop3_b32 v18, v68, s18, 48 bitop3:0xc8
	s_movk_i32 s18, 0x4000
	v_cmp_gt_i32_e32 vcc, s18, v16
	v_add_u32_e32 v96, 0xfffff880, v18
	v_ashrrev_i32_e32 v17, 31, v16
	v_cndmask_b32_e32 v19, v151, v18, vcc
	v_lshlrev_b32_e32 v37, 3, v19
	v_add_u32_e32 v19, 0xffffc030, v68
	v_lshlrev_b64 v[28:29], 7, v[96:97]
	s_mov_b64 s[70:71], 0x1080000
	v_lshlrev_b64 v[24:25], 11, v[16:17]
	v_lshlrev_b64 v[22:23], 8, v[16:17]
	v_lshrrev_b32_e32 v36, 2, v19
	v_lshlrev_b64 v[20:21], 10, v[16:17]
	v_lshl_add_u64 v[30:31], v[28:29], 0, s[70:71]
	v_lshl_add_u64 v[16:17], s[30:31], 0, v[24:25]
	v_lshl_add_u64 v[16:17], s[92:93], 2, v[16:17]
	v_mov_b32_e32 v131, v97
	v_lshl_add_u64 v[18:19], v[16:17], 0, v[130:131]
	global_store_dwordx4 v[18:19], v[12:15], off
	v_mov_b32_e32 v131, v97
	s_nop 0
	v_lshl_add_u64 v[12:13], v[16:17], 0, v[130:131]
	global_store_dwordx4 v[12:13], v[8:11], off offset:16
	s_mov_b64 s[70:71], 0x1100000
	s_nop 0
	v_lshl_add_u64 v[12:13], v[28:29], 0, s[70:71]
	v_mov_b32_e32 v131, v97
	v_lshl_add_u64 v[8:9], v[16:17], 0, v[130:131]
	global_store_dwordx4 v[8:9], v[4:7], off offset:512
	s_mov_b32 s70, 0x1200000
	s_mov_b32 s71, 0x1400000
	v_mov_b32_e32 v131, v97
	v_lshl_add_u64 v[4:5], v[16:17], 0, v[130:131]
	global_store_dwordx4 v[4:5], v[0:3], off offset:528
	s_branch .LBB0_1574
